# EpiResid stores (down, W_out epilogues) with nt streaming hint
# baseline (speedup 1.0000x reference)
; #define PG8_STAGE(bufoff, gbase, voff) do { _Pragma("unroll") for (int _i = 0; _i < 2; ++_i) \
;         __builtin_amdgcn_global_load_lds((const unsigned*)((const char*)(gbase) + (voff)[_i]), (PG8_LAS unsigned*)(lds + (bufoff) + ldsw + _i * 8192), 16, 0, 0); } while (0)
; #define PG8_LDA(dst, b, h) do { _Pragma("unroll") for (int m = 0; m < 4; ++m) _Pragma("unroll") for (int k = 0; k < 2; ++k) dst[m][k] = *(const PG8_LAS bf16x8*)(lds + PG8_SA(b, h) + aoff + m * 2048 + k * 1024); } while (0)
; #define PG8_LDB(dst, b, h) do { _Pragma("unroll") for (int n = 0; n < 2; ++n) _Pragma("unroll") for (int k = 0; k < 2; ++k) dst[n][k] = *(const PG8_LAS bf16x8*)(lds + PG8_SB(b, h) + boff + n * 2048 + k * 1024); } while (0)
; #define PG8_MMA(ai, bj, At, Bt) do { __builtin_amdgcn_s_setprio(1); _Pragma("unroll") for (int m = 0; m < 4; ++m) _Pragma("unroll") for (int n = 0; n < 2; ++n) _Pragma("unroll") for (int k = 0; k < 2; ++k) \
;         acc[ai][bj][m][n] = __builtin_amdgcn_mfma_f32_16x16x32_bf16(Bt[n][k], At[m][k], acc[ai][bj][m][n], 0, 0, 0); __builtin_amdgcn_s_setprio(0); } while (0)
; #define PG8_WAIT_V(n) asm volatile("s_waitcnt vmcnt(" #n ")" ::: "memory")
; #define PG8_WAIT_L(n) asm volatile("s_waitcnt lgkmcnt(" #n ")" ::: "memory")
; #define PG8_BAR __builtin_amdgcn_s_barrier()
; #define PG8_SCHED __builtin_amdgcn_sched_barrier(0)
; template <class Epi, class Sched, bool ALIGN_EPI = false, bool SP2 = false>
; __device__ __forceinline__ void gemm_phase(PG8_LAS unsigned char* lds, const Gemm g, const Sched& S, const Epi& E, const int tid) {
;     ...
;             PG8_LDB(B0, 0, 0); PG8_LDB(B1, 0, 1); PG8_SCHED; PG8_LDA(At, 0, 0); PG8_STAGE(PG8_SA(1, 1), a1 + hstep, voffA);
;             PG8_WAIT_V(8); PG8_WAIT_L(0); PG8_BAR; PG8_MMA(0, 0, At, B0); PG8_MMA(0, 1, At, B1); PG8_BAR; PG8_SCHED;
;             PG8_LDA(At, 0, 1); PG8_STAGE(PG8_SB(0, 0), b2, voffB); PG8_STAGE(PG8_SB(0, 1), b2 + hstep, voffB); PG8_STAGE(PG8_SA(0, 0), a2, voffA);
;             PG8_WAIT_V(8); PG8_WAIT_L(0); PG8_BAR; PG8_MMA(1, 0, At, B0); PG8_MMA(1, 1, At, B1); PG8_BAR; PG8_SCHED;
.LBB0_403:
	s_add_u32 s52, s50, 0x100
	s_addc_u32 s53, s51, 0
	s_add_i32 s76, 0, 0x10000
	s_cmpk_eq_i32 s75, 0x54
	s_cselect_b32 s57, s45, s53
	s_cselect_b32 s56, s44, s52
	s_cselect_b32 s55, s47, s73
	s_cselect_b32 s54, s46, s72
	s_add_i32 s77, 0, 0x14000
	v_add_u32_e32 v146, s76, v233
	v_add_u32_e32 v162, s77, v233
	ds_read_b128 v[126:129], v146
	ds_read_b128 v[130:133], v146 offset:1024
	ds_read_b128 v[142:145], v146 offset:2048
	ds_read_b128 v[146:149], v146 offset:3072
	ds_read_b128 v[150:153], v162
	ds_read_b128 v[154:157], v162 offset:1024
	ds_read_b128 v[158:161], v162 offset:2048
	ds_read_b128 v[162:165], v162 offset:3072
	v_lshl_add_u64 v[210:211], s[50:51], 0, v[192:193]
	s_add_i32 m0, s60, 0xc000
	ds_read_b128 v[166:169], v236
	ds_read_b128 v[170:173], v236 offset:1024
	ds_read_b128 v[174:177], v236 offset:2048
	ds_read_b128 v[178:181], v236 offset:3072
	ds_read_b128 v[194:197], v236 offset:4096
	ds_read_b128 v[198:201], v236 offset:5120
	ds_read_b128 v[202:205], v236 offset:6144
	ds_read_b128 v[206:209], v236 offset:7168
	global_load_lds_dwordx4 v[210:211], off
	v_lshl_add_u64 v[210:211], s[50:51], 0, v[190:191]
	s_add_i32 m0, s60, 0xe000
	s_nop 0
	global_load_lds_dwordx4 v[210:211], off
	s_waitcnt vmcnt(8)
	s_waitcnt lgkmcnt(0)
	s_barrier
	s_setprio 1
	s_waitcnt lgkmcnt(0)
	v_mfma_f32_16x16x32_bf16 v[138:141], v[126:129], v[166:169], v[138:141]
	v_mfma_f32_16x16x32_bf16 v[134:137], v[142:145], v[166:169], v[134:137]
	v_mfma_f32_16x16x32_bf16 v[114:117], v[126:129], v[174:177], v[114:117]
	v_mfma_f32_16x16x32_bf16 v[110:113], v[142:145], v[174:177], v[110:113]
	v_mfma_f32_16x16x32_bf16 v[92:95], v[126:129], v[194:197], v[92:95]
	v_mfma_f32_16x16x32_bf16 v[88:91], v[142:145], v[194:197], v[88:91]
	v_mfma_f32_16x16x32_bf16 v[76:79], v[126:129], v[202:205], v[76:79]
	v_mfma_f32_16x16x32_bf16 v[72:75], v[142:145], v[202:205], v[72:75]
	v_mfma_f32_16x16x32_bf16 v[138:141], v[130:133], v[170:173], v[138:141]
	v_mfma_f32_16x16x32_bf16 v[134:137], v[146:149], v[170:173], v[134:137]
	v_mfma_f32_16x16x32_bf16 v[114:117], v[130:133], v[178:181], v[114:117]
	v_mfma_f32_16x16x32_bf16 v[110:113], v[146:149], v[178:181], v[110:113]
	v_mfma_f32_16x16x32_bf16 v[92:95], v[130:133], v[198:201], v[92:95]
	v_mfma_f32_16x16x32_bf16 v[88:91], v[146:149], v[198:201], v[88:91]
	v_mfma_f32_16x16x32_bf16 v[76:79], v[130:133], v[206:209], v[76:79]
	v_mfma_f32_16x16x32_bf16 v[72:75], v[146:149], v[206:209], v[72:75]
	s_setprio 0
	s_setprio 1
	v_mfma_f32_16x16x32_bf16 v[122:125], v[150:153], v[166:169], v[122:125]
	v_mfma_f32_16x16x32_bf16 v[118:121], v[158:161], v[166:169], v[118:121]
	v_mfma_f32_16x16x32_bf16 v[106:109], v[150:153], v[174:177], v[106:109]
	v_mfma_f32_16x16x32_bf16 v[102:105], v[158:161], v[174:177], v[102:105]
	v_mfma_f32_16x16x32_bf16 v[84:87], v[150:153], v[194:197], v[84:87]
	v_mfma_f32_16x16x32_bf16 v[80:83], v[158:161], v[194:197], v[80:83]
	v_mfma_f32_16x16x32_bf16 v[68:71], v[150:153], v[202:205], v[68:71]
	v_mfma_f32_16x16x32_bf16 v[64:67], v[158:161], v[202:205], v[64:67]
	v_mfma_f32_16x16x32_bf16 v[122:125], v[154:157], v[170:173], v[122:125]
	v_mfma_f32_16x16x32_bf16 v[118:121], v[162:165], v[170:173], v[118:121]
	v_mfma_f32_16x16x32_bf16 v[106:109], v[154:157], v[178:181], v[106:109]
	v_mfma_f32_16x16x32_bf16 v[102:105], v[162:165], v[178:181], v[102:105]
	v_mfma_f32_16x16x32_bf16 v[84:87], v[154:157], v[198:201], v[84:87]
	v_mfma_f32_16x16x32_bf16 v[80:83], v[162:165], v[198:201], v[80:83]
	v_mfma_f32_16x16x32_bf16 v[68:71], v[154:157], v[206:209], v[68:71]
	v_mfma_f32_16x16x32_bf16 v[64:67], v[162:165], v[206:209], v[64:67]
	s_setprio 0
	s_barrier
	s_add_i32 s50, s76, s59
	v_lshl_add_u64 v[210:211], s[54:55], 0, v[96:97]
	s_mov_b32 m0, s50
	ds_read_b128 v[166:169], v236 offset:16384
	ds_read_b128 v[170:173], v236 offset:17408
	ds_read_b128 v[174:177], v236 offset:18432
	ds_read_b128 v[178:181], v236 offset:19456
	ds_read_b128 v[194:197], v236 offset:20480
	ds_read_b128 v[198:201], v236 offset:21504
	ds_read_b128 v[202:205], v236 offset:22528
	ds_read_b128 v[206:209], v236 offset:23552
	global_load_lds_dwordx4 v[210:211], off
	s_add_i32 m0, s50, 0x2000
	s_add_u32 s50, s54, 0x160000
	v_lshl_add_u64 v[212:213], s[54:55], 0, v[98:99]
	s_addc_u32 s51, s55, 0
	s_add_i32 s76, s77, s59
	global_load_lds_dwordx4 v[212:213], off
	v_lshl_add_u64 v[214:215], s[50:51], 0, v[96:97]
	s_mov_b32 m0, s76
	v_lshl_add_u64 v[216:217], s[56:57], 0, v[186:187]
	global_load_lds_dwordx4 v[214:215], off
	v_lshl_add_u64 v[214:215], s[50:51], 0, v[98:99]
	s_add_i32 m0, s76, 0x2000
	s_nop 0
	global_load_lds_dwordx4 v[214:215], off
	v_lshl_add_u64 v[214:215], s[56:57], 0, v[188:189]
	s_mov_b32 m0, s60
	s_nop 0
	global_load_lds_dwordx4 v[214:215], off
	s_mov_b32 m0, s61
	s_nop 0
	global_load_lds_dwordx4 v[216:217], off
	s_waitcnt vmcnt(8)
	s_waitcnt lgkmcnt(0)
	s_barrier
; #define PG8_STAGE(bufoff, gbase, voff) do { _Pragma("unroll") for (int _i = 0; _i < 2; ++_i) \
;         __builtin_amdgcn_global_load_lds((const unsigned*)((const char*)(gbase) + (voff)[_i]), (PG8_LAS unsigned*)(lds + (bufoff) + ldsw + _i * 8192), 16, 0, 0); } while (0)
; #define PG8_LDA(dst, b, h) do { _Pragma("unroll") for (int m = 0; m < 4; ++m) _Pragma("unroll") for (int k = 0; k < 2; ++k) dst[m][k] = *(const PG8_LAS bf16x8*)(lds + PG8_SA(b, h) + aoff + m * 2048 + k * 1024); } while (0)
; #define PG8_LDB(dst, b, h) do { _Pragma("unroll") for (int n = 0; n < 2; ++n) _Pragma("unroll") for (int k = 0; k < 2; ++k) dst[n][k] = *(const PG8_LAS bf16x8*)(lds + PG8_SB(b, h) + boff + n * 2048 + k * 1024); } while (0)
; #define PG8_MMA(ai, bj, At, Bt) do { __builtin_amdgcn_s_setprio(1); _Pragma("unroll") for (int m = 0; m < 4; ++m) _Pragma("unroll") for (int n = 0; n < 2; ++n) _Pragma("unroll") for (int k = 0; k < 2; ++k) \
;         acc[ai][bj][m][n] = __builtin_amdgcn_mfma_f32_16x16x32_bf16(Bt[n][k], At[m][k], acc[ai][bj][m][n], 0, 0, 0); __builtin_amdgcn_s_setprio(0); } while (0)
; #define PG8_WAIT_V(n) asm volatile("s_waitcnt vmcnt(" #n ")" ::: "memory")
; #define PG8_WAIT_L(n) asm volatile("s_waitcnt lgkmcnt(" #n ")" ::: "memory")
; #define PG8_BAR __builtin_amdgcn_s_barrier()
; #define PG8_SCHED __builtin_amdgcn_sched_barrier(0)
; template <class Epi, class Sched, bool ALIGN_EPI = false, bool SP2 = false>
; __device__ __forceinline__ void gemm_phase(PG8_LAS unsigned char* lds, const Gemm g, const Sched& S, const Epi& E, const int tid) {
;     ...
;             PG8_WAIT_V(8); PG8_WAIT_L(0); PG8_BAR; PG8_MMA(1, 0, At, B0); PG8_MMA(1, 1, At, B1); PG8_BAR; PG8_SCHED;
;             PG8_LDB(B0, 1, 0); PG8_LDB(B1, 1, 1); PG8_SCHED; PG8_LDA(At, 1, 0); PG8_STAGE(PG8_SA(0, 1), a2 + hstep, voffA);
;             PG8_WAIT_V(8); PG8_WAIT_L(0); PG8_BAR; PG8_MMA(0, 0, At, B0); PG8_MMA(0, 1, At, B1); PG8_BAR; PG8_SCHED;
	s_setprio 1
	s_waitcnt lgkmcnt(0)
	v_mfma_f32_16x16x32_bf16 v[60:63], v[126:129], v[166:169], v[60:63]
	v_mfma_f32_16x16x32_bf16 v[56:59], v[142:145], v[166:169], v[56:59]
	v_mfma_f32_16x16x32_bf16 v[44:47], v[126:129], v[174:177], v[44:47]
	v_mfma_f32_16x16x32_bf16 v[40:43], v[142:145], v[174:177], v[40:43]
	v_mfma_f32_16x16x32_bf16 v[28:31], v[126:129], v[194:197], v[28:31]
	v_mfma_f32_16x16x32_bf16 v[24:27], v[142:145], v[194:197], v[24:27]
	v_mfma_f32_16x16x32_bf16 v[12:15], v[126:129], v[202:205], v[12:15]
	v_mfma_f32_16x16x32_bf16 v[8:11], v[142:145], v[202:205], v[8:11]
	v_mfma_f32_16x16x32_bf16 v[60:63], v[130:133], v[170:173], v[60:63]
	v_mfma_f32_16x16x32_bf16 v[56:59], v[146:149], v[170:173], v[56:59]
	v_mfma_f32_16x16x32_bf16 v[44:47], v[130:133], v[178:181], v[44:47]
	v_mfma_f32_16x16x32_bf16 v[40:43], v[146:149], v[178:181], v[40:43]
	v_mfma_f32_16x16x32_bf16 v[28:31], v[130:133], v[198:201], v[28:31]
	v_mfma_f32_16x16x32_bf16 v[24:27], v[146:149], v[198:201], v[24:27]
	v_mfma_f32_16x16x32_bf16 v[12:15], v[130:133], v[206:209], v[12:15]
	v_mfma_f32_16x16x32_bf16 v[8:11], v[146:149], v[206:209], v[8:11]
	s_setprio 0
	s_setprio 1
	v_mfma_f32_16x16x32_bf16 v[52:55], v[150:153], v[166:169], v[52:55]
	v_mfma_f32_16x16x32_bf16 v[48:51], v[158:161], v[166:169], v[48:51]
	v_mfma_f32_16x16x32_bf16 v[36:39], v[150:153], v[174:177], v[36:39]
	v_mfma_f32_16x16x32_bf16 v[32:35], v[158:161], v[174:177], v[32:35]
	v_mfma_f32_16x16x32_bf16 v[20:23], v[150:153], v[194:197], v[20:23]
	v_mfma_f32_16x16x32_bf16 v[16:19], v[158:161], v[194:197], v[16:19]
	v_mfma_f32_16x16x32_bf16 v[4:7], v[150:153], v[202:205], v[4:7]
	v_mfma_f32_16x16x32_bf16 v[0:3], v[158:161], v[202:205], v[0:3]
	v_mfma_f32_16x16x32_bf16 v[52:55], v[154:157], v[170:173], v[52:55]
	v_mfma_f32_16x16x32_bf16 v[48:51], v[162:165], v[170:173], v[48:51]
	v_mfma_f32_16x16x32_bf16 v[36:39], v[154:157], v[178:181], v[36:39]
	v_mfma_f32_16x16x32_bf16 v[32:35], v[162:165], v[178:181], v[32:35]
	v_mfma_f32_16x16x32_bf16 v[20:23], v[154:157], v[198:201], v[20:23]
	v_mfma_f32_16x16x32_bf16 v[16:19], v[162:165], v[198:201], v[16:19]
	v_mfma_f32_16x16x32_bf16 v[4:7], v[154:157], v[206:209], v[4:7]
	v_mfma_f32_16x16x32_bf16 v[0:3], v[162:165], v[206:209], v[0:3]
	s_setprio 0
	s_barrier
	s_add_i32 s76, 0, 0x18000
	s_add_i32 s77, 0, 0x1c000
	v_add_u32_e32 v146, s76, v233
	v_add_u32_e32 v162, s77, v233
	ds_read_b128 v[126:129], v146
	ds_read_b128 v[130:133], v146 offset:1024
	ds_read_b128 v[142:145], v146 offset:2048
	ds_read_b128 v[146:149], v146 offset:3072
	ds_read_b128 v[150:153], v162
	ds_read_b128 v[154:157], v162 offset:1024
	ds_read_b128 v[158:161], v162 offset:2048
	ds_read_b128 v[162:165], v162 offset:3072
	s_add_u32 s50, s56, 0x160000
	s_addc_u32 s51, s57, 0
	s_mov_b32 m0, s64
	v_lshl_add_u64 v[218:219], s[50:51], 0, v[188:189]
	ds_read_b128 v[166:169], v236 offset:32768
	ds_read_b128 v[170:173], v236 offset:33792
	ds_read_b128 v[174:177], v236 offset:34816
	ds_read_b128 v[178:181], v236 offset:35840
	ds_read_b128 v[194:197], v236 offset:36864
	ds_read_b128 v[198:201], v236 offset:37888
	ds_read_b128 v[202:205], v236 offset:38912
	ds_read_b128 v[206:209], v236 offset:39936
	global_load_lds_dwordx4 v[218:219], off
	v_lshl_add_u64 v[218:219], s[50:51], 0, v[186:187]
	s_mov_b32 m0, s65
	s_nop 0
	global_load_lds_dwordx4 v[218:219], off
	s_waitcnt vmcnt(8)
	s_waitcnt lgkmcnt(0)
	s_barrier
	s_setprio 1
	s_waitcnt lgkmcnt(0)
	v_mfma_f32_16x16x32_bf16 v[138:141], v[126:129], v[166:169], v[138:141]
	v_mfma_f32_16x16x32_bf16 v[134:137], v[142:145], v[166:169], v[134:137]
	v_mfma_f32_16x16x32_bf16 v[114:117], v[126:129], v[174:177], v[114:117]
	v_mfma_f32_16x16x32_bf16 v[110:113], v[142:145], v[174:177], v[110:113]
	v_mfma_f32_16x16x32_bf16 v[92:95], v[126:129], v[194:197], v[92:95]
	v_mfma_f32_16x16x32_bf16 v[88:91], v[142:145], v[194:197], v[88:91]
	v_mfma_f32_16x16x32_bf16 v[76:79], v[126:129], v[202:205], v[76:79]
	v_mfma_f32_16x16x32_bf16 v[72:75], v[142:145], v[202:205], v[72:75]
	v_mfma_f32_16x16x32_bf16 v[138:141], v[130:133], v[170:173], v[138:141]
	v_mfma_f32_16x16x32_bf16 v[134:137], v[146:149], v[170:173], v[134:137]
	v_mfma_f32_16x16x32_bf16 v[114:117], v[130:133], v[178:181], v[114:117]
	v_mfma_f32_16x16x32_bf16 v[110:113], v[146:149], v[178:181], v[110:113]
	v_mfma_f32_16x16x32_bf16 v[92:95], v[130:133], v[198:201], v[92:95]
	v_mfma_f32_16x16x32_bf16 v[88:91], v[146:149], v[198:201], v[88:91]
	v_mfma_f32_16x16x32_bf16 v[76:79], v[130:133], v[206:209], v[76:79]
	v_mfma_f32_16x16x32_bf16 v[72:75], v[146:149], v[206:209], v[72:75]
	s_setprio 0
	s_setprio 1
	v_mfma_f32_16x16x32_bf16 v[122:125], v[150:153], v[166:169], v[122:125]
	v_mfma_f32_16x16x32_bf16 v[118:121], v[158:161], v[166:169], v[118:121]
	v_mfma_f32_16x16x32_bf16 v[106:109], v[150:153], v[174:177], v[106:109]
	v_mfma_f32_16x16x32_bf16 v[102:105], v[158:161], v[174:177], v[102:105]
	v_mfma_f32_16x16x32_bf16 v[84:87], v[150:153], v[194:197], v[84:87]
	v_mfma_f32_16x16x32_bf16 v[80:83], v[158:161], v[194:197], v[80:83]
	v_mfma_f32_16x16x32_bf16 v[68:71], v[150:153], v[202:205], v[68:71]
	v_mfma_f32_16x16x32_bf16 v[64:67], v[158:161], v[202:205], v[64:67]
	v_mfma_f32_16x16x32_bf16 v[122:125], v[154:157], v[170:173], v[122:125]
	v_mfma_f32_16x16x32_bf16 v[118:121], v[162:165], v[170:173], v[118:121]
	v_mfma_f32_16x16x32_bf16 v[106:109], v[154:157], v[178:181], v[106:109]
	v_mfma_f32_16x16x32_bf16 v[102:105], v[162:165], v[178:181], v[102:105]
	v_mfma_f32_16x16x32_bf16 v[84:87], v[154:157], v[198:201], v[84:87]
	v_mfma_f32_16x16x32_bf16 v[80:83], v[162:165], v[198:201], v[80:83]
	v_mfma_f32_16x16x32_bf16 v[68:71], v[154:157], v[206:209], v[68:71]
	v_mfma_f32_16x16x32_bf16 v[64:67], v[162:165], v[206:209], v[64:67]
	s_setprio 0
	s_barrier
; #define PG8_GAS __attribute__((address_space(1)))
; #define PG8_STAGE(bufoff, gbase, voff) do { _Pragma("unroll") for (int _i = 0; _i < 2; ++_i) \
;         __builtin_amdgcn_global_load_lds((const unsigned*)((const char*)(gbase) + (voff)[_i]), (PG8_LAS unsigned*)(lds + (bufoff) + ldsw + _i * 8192), 16, 0, 0); } while (0)
; #define PG8_LDA(dst, b, h) do { _Pragma("unroll") for (int m = 0; m < 4; ++m) _Pragma("unroll") for (int k = 0; k < 2; ++k) dst[m][k] = *(const PG8_LAS bf16x8*)(lds + PG8_SA(b, h) + aoff + m * 2048 + k * 1024); } while (0)
; #define PG8_MMA(ai, bj, At, Bt) do { __builtin_amdgcn_s_setprio(1); _Pragma("unroll") for (int m = 0; m < 4; ++m) _Pragma("unroll") for (int n = 0; n < 2; ++n) _Pragma("unroll") for (int k = 0; k < 2; ++k) \
;         acc[ai][bj][m][n] = __builtin_amdgcn_mfma_f32_16x16x32_bf16(Bt[n][k], At[m][k], acc[ai][bj][m][n], 0, 0, 0); __builtin_amdgcn_s_setprio(0); } while (0)
; #define PG8_WAIT_V(n) asm volatile("s_waitcnt vmcnt(" #n ")" ::: "memory")
; #define PG8_WAIT_L(n) asm volatile("s_waitcnt lgkmcnt(" #n ")" ::: "memory")
; #define PG8_BAR __builtin_amdgcn_s_barrier()
;     __device__ __forceinline__ void operator()(const f32x4 (&acc)[2][2][4][2], const Unit& u, int wr, int wc, int fr, int fq) const {
;         const int row0 = u.pm * BM + wr * 64 + fr, col0 = u.pn * BM + wc * 32 + 8 * fq, lcol = u.pn * BM + (wc * 4 + fq) * 16;
; #pragma unroll
;         for (int ai = 0; ai < 2; ++ai) {
;             u32x4 L4[4], H4[4][2];
; #pragma unroll
;             for (int m = 0; m < 4; ++m) {
;                 const int row = row0 + ai * HALF + m * 16; const size_t off = (size_t)row * 2048 + col0, loff = (size_t)row * 2048 + lcol;
;                 L4[m] = *(const PG8_GAS u32x4*)(lin + loff); H4[m][0] = *(const PG8_GAS u32x4*)(hin + off); H4[m][1] = *(const PG8_GAS u32x4*)(hin + off + HALF);
;             }
; template <class Epi, class Sched, bool ALIGN_EPI = false, bool SP2 = false>
; __device__ __forceinline__ void gemm_phase(PG8_LAS unsigned char* lds, const Gemm g, const Sched& S, const Epi& E, const int tid) {
;     ...
;             PG8_LDA(At, 1, 1); PG8_STAGE(PG8_SB(1, 0), b3, voffB); PG8_STAGE(PG8_SB(1, 1), b3 + hstep, voffB); PG8_STAGE(PG8_SA(1, 0), a3, voffA);
;             PG8_WAIT_V(8); PG8_WAIT_L(0); PG8_BAR; PG8_MMA(1, 0, At, B0); PG8_MMA(1, 1, At, B1); PG8_BAR; PG8_SCHED;
	s_add_i32 s50, s76, s59
	v_lshl_add_u64 v[210:211], v[210:211], 0, s[28:29]
	s_mov_b32 m0, s50
	ds_read_b128 v[166:169], v236 offset:49152
	ds_read_b128 v[170:173], v236 offset:50176
	ds_read_b128 v[174:177], v236 offset:51200
	ds_read_b128 v[178:181], v236 offset:52224
	ds_read_b128 v[194:197], v236 offset:53248
	ds_read_b128 v[198:201], v236 offset:54272
	ds_read_b128 v[202:205], v236 offset:55296
	ds_read_b128 v[206:209], v236 offset:56320
	global_load_lds_dwordx4 v[210:211], off
	s_add_i32 m0, s50, 0x2000
	s_add_u32 s50, s54, 0x160080
	v_lshl_add_u64 v[210:211], v[212:213], 0, s[28:29]
	s_addc_u32 s51, s55, 0
	s_add_i32 s54, s77, s59
	global_load_lds_dwordx4 v[210:211], off
	v_lshl_add_u64 v[210:211], s[50:51], 0, v[96:97]
	s_mov_b32 m0, s54
	s_nop 0
	global_load_lds_dwordx4 v[210:211], off
	v_lshl_add_u64 v[210:211], s[50:51], 0, v[98:99]
	s_add_i32 m0, s54, 0x2000
	s_nop 0
	global_load_lds_dwordx4 v[210:211], off
	v_lshl_add_u64 v[210:211], v[214:215], 0, s[28:29]
	s_mov_b32 m0, s63
	s_nop 0
	global_load_lds_dwordx4 v[210:211], off
	v_lshl_add_u64 v[210:211], v[216:217], 0, s[28:29]
	s_mov_b32 m0, s66
	s_nop 0
	global_load_lds_dwordx4 v[210:211], off
	s_waitcnt vmcnt(8)
	s_waitcnt lgkmcnt(0)
	s_barrier
	s_setprio 1
	s_waitcnt lgkmcnt(0)
	v_mfma_f32_16x16x32_bf16 v[60:63], v[126:129], v[166:169], v[60:63]
	v_mfma_f32_16x16x32_bf16 v[56:59], v[142:145], v[166:169], v[56:59]
	v_mfma_f32_16x16x32_bf16 v[44:47], v[126:129], v[174:177], v[44:47]
	v_mfma_f32_16x16x32_bf16 v[40:43], v[142:145], v[174:177], v[40:43]
	v_mfma_f32_16x16x32_bf16 v[28:31], v[126:129], v[194:197], v[28:31]
	v_mfma_f32_16x16x32_bf16 v[24:27], v[142:145], v[194:197], v[24:27]
	v_mfma_f32_16x16x32_bf16 v[12:15], v[126:129], v[202:205], v[12:15]
	v_mfma_f32_16x16x32_bf16 v[8:11], v[142:145], v[202:205], v[8:11]
	v_mfma_f32_16x16x32_bf16 v[60:63], v[130:133], v[170:173], v[60:63]
	v_mfma_f32_16x16x32_bf16 v[56:59], v[146:149], v[170:173], v[56:59]
	v_mfma_f32_16x16x32_bf16 v[44:47], v[130:133], v[178:181], v[44:47]
	v_mfma_f32_16x16x32_bf16 v[40:43], v[146:149], v[178:181], v[40:43]
	v_mfma_f32_16x16x32_bf16 v[28:31], v[130:133], v[198:201], v[28:31]
	v_mfma_f32_16x16x32_bf16 v[24:27], v[146:149], v[198:201], v[24:27]
	v_mfma_f32_16x16x32_bf16 v[12:15], v[130:133], v[206:209], v[12:15]
	v_mfma_f32_16x16x32_bf16 v[8:11], v[146:149], v[206:209], v[8:11]
	s_setprio 0
	s_setprio 1
	v_mfma_f32_16x16x32_bf16 v[52:55], v[150:153], v[166:169], v[52:55]
	v_mfma_f32_16x16x32_bf16 v[48:51], v[158:161], v[166:169], v[48:51]
	v_mfma_f32_16x16x32_bf16 v[36:39], v[150:153], v[174:177], v[36:39]
	v_mfma_f32_16x16x32_bf16 v[32:35], v[158:161], v[174:177], v[32:35]
	v_mfma_f32_16x16x32_bf16 v[20:23], v[150:153], v[194:197], v[20:23]
	v_mfma_f32_16x16x32_bf16 v[16:19], v[158:161], v[194:197], v[16:19]
	v_mfma_f32_16x16x32_bf16 v[4:7], v[150:153], v[202:205], v[4:7]
	v_mfma_f32_16x16x32_bf16 v[0:3], v[158:161], v[202:205], v[0:3]
	v_mfma_f32_16x16x32_bf16 v[52:55], v[154:157], v[170:173], v[52:55]
	v_mfma_f32_16x16x32_bf16 v[48:51], v[162:165], v[170:173], v[48:51]
	v_mfma_f32_16x16x32_bf16 v[36:39], v[154:157], v[178:181], v[36:39]
	v_mfma_f32_16x16x32_bf16 v[32:35], v[162:165], v[178:181], v[32:35]
	v_mfma_f32_16x16x32_bf16 v[20:23], v[154:157], v[198:201], v[20:23]
	v_mfma_f32_16x16x32_bf16 v[16:19], v[162:165], v[198:201], v[16:19]
	v_mfma_f32_16x16x32_bf16 v[4:7], v[154:157], v[206:209], v[4:7]
	v_mfma_f32_16x16x32_bf16 v[0:3], v[162:165], v[206:209], v[0:3]
	s_setprio 0
	s_barrier
	s_add_i32 s75, s75, 2
	s_add_u32 s72, s72, 0x100
	s_addc_u32 s73, s73, 0
	s_cmpk_gt_u32 s75, 0x55
	s_mov_b64 s[50:51], s[52:53]
	s_cbranch_scc0 .LBB0_403
	v_and_b32_e32 v127, 64, v228
	v_xor_b32_e32 v126, 16, v228
	v_add_u32_e32 v127, 64, v127
	v_cmp_lt_i32_e32 vcc, v126, v127
	s_lshl_b32 s50, s70, 8
	v_lshl_add_u32 v198, s71, 8, v101
	v_cndmask_b32_e32 v126, v228, v126, vcc
	v_or_b32_e32 v194, s50, v235
	v_lshlrev_b32_e32 v238, 2, v126
	v_xor_b32_e32 v126, 32, v228
	v_or_b32_e32 v196, s50, v234
	v_ashrrev_i32_e32 v195, 31, v194
	v_cmp_lt_i32_e32 vcc, v126, v127
	v_ashrrev_i32_e32 v199, 31, v198
	v_ashrrev_i32_e32 v197, 31, v196
	v_cndmask_b32_e32 v126, v228, v126, vcc
	v_lshl_add_u64 v[202:203], s[34:35], 0, v[194:195]
	v_lshlrev_b64 v[216:217], 11, v[198:199]
	v_lshlrev_b32_e32 v237, 2, v126
	v_lshlrev_b64 v[218:219], 1, v[196:197]
	v_lshl_add_u64 v[126:127], v[202:203], 0, v[216:217]
	v_lshl_add_u64 v[200:201], s[30:31], 0, v[218:219]
	global_load_dwordx4 v[170:173], v[126:127], off
	v_lshlrev_b64 v[220:221], 12, v[198:199]
	v_lshl_add_u64 v[126:127], v[200:201], 0, v[220:221]
	global_load_dwordx4 v[178:181], v[126:127], off
	global_load_dwordx4 v[174:177], v[126:127], off offset:256
	v_or_b32_e32 v212, 16, v198
	v_ashrrev_i32_e32 v213, 31, v212
	v_lshlrev_b64 v[214:215], 11, v[212:213]
	v_lshl_add_u64 v[126:127], v[202:203], 0, v[214:215]
	v_or_b32_e32 v208, 32, v198
	global_load_dwordx4 v[158:161], v[126:127], off
	v_lshlrev_b64 v[126:127], 12, v[212:213]
	v_ashrrev_i32_e32 v209, 31, v208
	v_lshl_add_u64 v[126:127], v[200:201], 0, v[126:127]
	v_lshlrev_b64 v[210:211], 11, v[208:209]
	global_load_dwordx4 v[166:169], v[126:127], off
	global_load_dwordx4 v[162:165], v[126:127], off offset:256
	v_lshl_add_u64 v[126:127], v[202:203], 0, v[210:211]
	v_or_b32_e32 v204, 48, v198
	global_load_dwordx4 v[146:149], v[126:127], off
	v_lshlrev_b64 v[126:127], 12, v[208:209]
	v_ashrrev_i32_e32 v205, 31, v204
	v_lshl_add_u64 v[126:127], v[200:201], 0, v[126:127]
	v_lshlrev_b64 v[206:207], 11, v[204:205]
	v_lshlrev_b64 v[130:131], 12, v[204:205]
	global_load_dwordx4 v[154:157], v[126:127], off
	global_load_dwordx4 v[150:153], v[126:127], off offset:256
	v_lshl_add_u64 v[126:127], v[202:203], 0, v[206:207]
	v_lshl_add_u64 v[130:131], v[200:201], 0, v[130:131]
	global_load_dwordx4 v[126:129], v[126:127], off
	s_nop 0
	global_load_dwordx4 v[142:145], v[130:131], off
	s_nop 0
	global_load_dwordx4 v[130:133], v[130:131], off offset:256
	v_mov_b32_e32 v243, v136
	v_mov_b32_e32 v242, v140
	s_waitcnt vmcnt(0)
; #define PG8_GAS __attribute__((address_space(1)))
; __device__ __forceinline__ float e_x24(unsigned h16, unsigned l8) { return __uint_as_float(((h16 - (l8 >> 7)) << 16) | (l8 << 8)); }
;     __device__ __forceinline__ void operator()(const f32x4 (&acc)[2][2][4][2], const Unit& u, int wr, int wc, int fr, int fq) const {
;     ...
;             for (int m = 0; m < 4; ++m) {
;                 const int row = row0 + ai * HALF + m * 16; const size_t off = (size_t)row * 2048 + col0, loff = (size_t)row * 2048 + lcol; float ss = 0.f;
;                 const u32x4 l4 = L4[m];
;                 u32x4 lo4;
; #pragma unroll
;                 for (int bj = 0; bj < 2; ++bj) {
;                     const u32x4 h4 = H4[m][bj];
;                     u32x4 ho;
; #pragma unroll
;                     for (int j = 0; j < 4; ++j) {
;                         const unsigned lw = l4[2 * bj + (j >> 1)], lb0 = (lw >> (16 * (j & 1))) & 0xffu, lb1 = (lw >> (16 * (j & 1) + 8)) & 0xffu;
;                         const float x0 = e_x24(h4[j] & 0xffffu, lb0) + acc[ai][bj][m][j >> 1][2 * (j & 1)] * scale, x1 = e_x24(h4[j] >> 16, lb1) + acc[ai][bj][m][j >> 1][2 * (j & 1) + 1] * scale;
;                         const unsigned b0 = __float_as_uint(x0), b1 = __float_as_uint(x1);
;                         ho[j] = ((b0 + 0x8000u) >> 16) | ((b1 + 0x8000u) & 0xffff0000u);
;                         const unsigned nb = ((b0 >> 8) & 0xffu) | (b1 & 0xff00u);
;                         if ((j & 1) == 0) lo4[2 * bj + (j >> 1)] = nb; else lo4[2 * bj + (j >> 1)] |= nb << 16;
;                         ss += x0 * x0 + x1 * x1;
;                     }
;                     *(PG8_GAS u32x4*)(hout + off + bj * HALF) = ho;
;                 }
;                 *(PG8_GAS u32x4*)(lout + loff) = lo4;
	v_lshrrev_b32_sdwa v222, v229, v171 dst_sel:DWORD dst_unused:UNUSED_PAD src0_sel:DWORD src1_sel:BYTE_0
	v_lshrrev_b32_sdwa v223, v229, v170 dst_sel:DWORD dst_unused:UNUSED_PAD src0_sel:DWORD src1_sel:BYTE_0
	v_sub_u32_sdwa v224, v178, v223 dst_sel:WORD_1 dst_unused:UNUSED_PAD src0_sel:DWORD src1_sel:DWORD
	v_sub_u32_sdwa v222, v180, v222 dst_sel:WORD_1 dst_unused:UNUSED_PAD src0_sel:DWORD src1_sel:DWORD
	v_lshlrev_b32_sdwa v223, v230, v171 dst_sel:DWORD dst_unused:UNUSED_PAD src0_sel:DWORD src1_sel:BYTE_0
	v_lshlrev_b32_sdwa v225, v230, v170 dst_sel:DWORD dst_unused:UNUSED_PAD src0_sel:DWORD src1_sel:BYTE_0
	v_or_b32_e32 v223, v222, v223
	v_or_b32_e32 v222, v224, v225
	v_mov_b32_e32 v224, v138
	v_mov_b32_e32 v225, v134
	v_pk_fma_f32 v[222:223], v[224:225], 0.5, v[222:223] op_sel_hi:[1,0,1]
	v_lshlrev_b32_e32 v224, 1, v170
	v_add_u32_e32 v134, 0x8000, v222
	v_lshrrev_b32_e32 v138, 16, v134
	v_lshlrev_b32_e32 v134, 1, v171
	v_and_b32_e32 v134, 0x10000, v134
	v_and_b32_e32 v224, 0x10000, v224
	v_sub_u32_e32 v134, v180, v134
	v_sub_u32_e32 v178, v178, v224
	v_and_b32_e32 v134, 0xffff0000, v134
	v_and_b32_e32 v178, 0xffff0000, v178
	v_and_b32_e32 v180, 0xff00, v171
	v_and_b32_e32 v224, 0xff00, v170
	v_or_b32_e32 v225, v134, v180
	v_or_b32_e32 v224, v178, v224
	v_mov_b32_e32 v134, v139
	v_pk_fma_f32 v[224:225], v[134:135], 0.5, v[224:225] op_sel_hi:[1,0,1]
	v_and_b32_sdwa v135, v171, s93 dst_sel:DWORD dst_unused:UNUSED_PAD src0_sel:WORD_1 src1_sel:DWORD
	v_and_b32_sdwa v178, v170, s93 dst_sel:DWORD dst_unused:UNUSED_PAD src0_sel:WORD_1 src1_sel:DWORD
	v_lshlrev_b32_sdwa v239, v231, v170 dst_sel:DWORD dst_unused:UNUSED_PAD src0_sel:DWORD src1_sel:BYTE_3
	v_lshlrev_b32_sdwa v136, v231, v171 dst_sel:DWORD dst_unused:UNUSED_PAD src0_sel:DWORD src1_sel:BYTE_3
	v_lshrrev_b32_e32 v180, 7, v178
	v_lshrrev_b32_e32 v240, 7, v135
	v_and_b32_e32 v136, 0x10000, v136
	v_and_b32_e32 v140, 0x10000, v239
	v_sub_u32_sdwa v180, v179, v180 dst_sel:WORD_1 dst_unused:UNUSED_PAD src0_sel:DWORD src1_sel:DWORD
	v_sub_u32_sdwa v240, v181, v240 dst_sel:WORD_1 dst_unused:UNUSED_PAD src0_sel:DWORD src1_sel:DWORD
	v_lshlrev_b32_e32 v135, 8, v135
	v_lshlrev_b32_e32 v178, 8, v178
	v_sub_u32_e32 v136, v181, v136
	v_sub_u32_e32 v140, v179, v140
	v_or_b32_e32 v241, v240, v135
	v_or_b32_e32 v240, v180, v178
	v_and_b32_e32 v136, 0xffff0000, v136
	v_and_b32_e32 v140, 0xffff0000, v140
	v_lshlrev_b32_sdwa v171, v230, v171 dst_sel:DWORD dst_unused:UNUSED_PAD src0_sel:DWORD src1_sel:BYTE_3
	v_lshlrev_b32_sdwa v170, v230, v170 dst_sel:DWORD dst_unused:UNUSED_PAD src0_sel:DWORD src1_sel:BYTE_3
	v_pk_fma_f32 v[240:241], v[242:243], 0.5, v[240:241] op_sel_hi:[1,0,1]
	v_or_b32_e32 v171, v136, v171
	v_or_b32_e32 v170, v140, v170
	v_mov_b32_e32 v136, v141
	v_add_u32_e32 v135, 0x8000, v240
	v_pk_fma_f32 v[140:141], v[136:137], 0.5, v[170:171] op_sel_hi:[1,0,1]
	v_lshrrev_b32_e32 v135, 16, v135
	v_add_u32_e32 v136, 0x8000, v140
	v_and_or_b32 v135, v136, s90, v135
	v_pk_mul_f32 v[136:137], v[140:141], v[140:141]
	v_add_u32_e32 v178, 0x8000, v141
	v_pk_fma_f32 v[170:171], v[240:241], v[240:241], v[136:137]
	v_add_u32_e32 v136, 0x8000, v223
	v_lshrrev_b32_e32 v136, 16, v136
	v_add_u32_e32 v137, 0x8000, v225
	v_and_or_b32 v136, v137, s90, v136
	v_add_u32_e32 v137, 0x8000, v241
	v_lshrrev_b32_e32 v137, 16, v137
	v_add_u32_e32 v134, 0x8000, v224
	v_and_or_b32 v137, v178, s90, v137
	v_lshl_add_u64 v[178:179], s[30:31], 0, v[220:221]
	v_and_or_b32 v134, v134, s90, v138
	v_lshl_add_u64 v[178:179], v[178:179], 0, v[218:219]
	global_store_dwordx4 v[178:179], v[134:137], off nt
	v_lshlrev_b32_sdwa v220, v231, v172 dst_sel:DWORD dst_unused:UNUSED_PAD src0_sel:DWORD src1_sel:BYTE_3
	v_mov_b32_e32 v219, v120
	v_lshrrev_b32_sdwa v134, v229, v173 dst_sel:DWORD dst_unused:UNUSED_PAD src0_sel:DWORD src1_sel:BYTE_0
	v_lshrrev_b32_sdwa v135, v229, v172 dst_sel:DWORD dst_unused:UNUSED_PAD src0_sel:DWORD src1_sel:BYTE_0
	v_sub_u32_sdwa v136, v174, v135 dst_sel:WORD_1 dst_unused:UNUSED_PAD src0_sel:DWORD src1_sel:DWORD
	v_sub_u32_sdwa v134, v176, v134 dst_sel:WORD_1 dst_unused:UNUSED_PAD src0_sel:DWORD src1_sel:DWORD
	v_lshlrev_b32_sdwa v135, v230, v173 dst_sel:DWORD dst_unused:UNUSED_PAD src0_sel:DWORD src1_sel:BYTE_0
	v_lshlrev_b32_sdwa v137, v230, v172 dst_sel:DWORD dst_unused:UNUSED_PAD src0_sel:DWORD src1_sel:BYTE_0
	v_or_b32_e32 v135, v134, v135
	v_or_b32_e32 v134, v136, v137
	v_mov_b32_e32 v136, v122
	v_mov_b32_e32 v137, v118
	v_pk_fma_f32 v[134:135], v[136:137], 0.5, v[134:135] op_sel_hi:[1,0,1]
	v_lshlrev_b32_e32 v122, 1, v172
	v_add_u32_e32 v118, 0x8000, v134
	v_lshrrev_b32_e32 v180, 16, v118
	v_lshlrev_b32_e32 v118, 1, v173
	v_and_b32_e32 v118, 0x10000, v118
	v_and_b32_e32 v122, 0x10000, v122
	v_sub_u32_e32 v118, v176, v118
	v_sub_u32_e32 v122, v174, v122
	v_and_b32_e32 v118, 0xffff0000, v118
	v_and_b32_e32 v122, 0xffff0000, v122
	v_and_b32_e32 v136, 0xff00, v173
	v_and_b32_e32 v174, 0xff00, v172
	v_or_b32_e32 v137, v118, v136
	v_or_b32_e32 v136, v122, v174
	v_mov_b32_e32 v118, v123
	v_pk_fma_f32 v[122:123], v[118:119], 0.5, v[136:137] op_sel_hi:[1,0,1]
	v_and_b32_sdwa v119, v173, s93 dst_sel:DWORD dst_unused:UNUSED_PAD src0_sel:WORD_1 src1_sel:DWORD
	v_add_u32_e32 v118, 0x8000, v122
	v_and_b32_sdwa v174, v172, s93 dst_sel:DWORD dst_unused:UNUSED_PAD src0_sel:WORD_1 src1_sel:DWORD
	v_lshlrev_b32_sdwa v120, v231, v173 dst_sel:DWORD dst_unused:UNUSED_PAD src0_sel:DWORD src1_sel:BYTE_3
	v_and_or_b32 v118, v118, s90, v180
	v_lshrrev_b32_e32 v176, 7, v174
	v_lshrrev_b32_e32 v180, 7, v119
	v_mov_b32_e32 v218, v124
	v_and_b32_e32 v120, 0x10000, v120
	v_and_b32_e32 v124, 0x10000, v220
; #define PG8_GAS __attribute__((address_space(1)))
; __device__ __forceinline__ float e_x24(unsigned h16, unsigned l8) { return __uint_as_float(((h16 - (l8 >> 7)) << 16) | (l8 << 8)); }
;     __device__ __forceinline__ void operator()(const f32x4 (&acc)[2][2][4][2], const Unit& u, int wr, int wc, int fr, int fq) const {
;     ...
;             for (int m = 0; m < 4; ++m) {
;                 const int row = row0 + ai * HALF + m * 16; const size_t off = (size_t)row * 2048 + col0, loff = (size_t)row * 2048 + lcol; float ss = 0.f;
;                 const u32x4 l4 = L4[m];
;                 u32x4 lo4;
; #pragma unroll
;                 for (int bj = 0; bj < 2; ++bj) {
;                     const u32x4 h4 = H4[m][bj];
;                     u32x4 ho;
; #pragma unroll
;                     for (int j = 0; j < 4; ++j) {
;                         const unsigned lw = l4[2 * bj + (j >> 1)], lb0 = (lw >> (16 * (j & 1))) & 0xffu, lb1 = (lw >> (16 * (j & 1) + 8)) & 0xffu;
;                         const float x0 = e_x24(h4[j] & 0xffffu, lb0) + acc[ai][bj][m][j >> 1][2 * (j & 1)] * scale, x1 = e_x24(h4[j] >> 16, lb1) + acc[ai][bj][m][j >> 1][2 * (j & 1) + 1] * scale;
;                         const unsigned b0 = __float_as_uint(x0), b1 = __float_as_uint(x1);
;                         ho[j] = ((b0 + 0x8000u) >> 16) | ((b1 + 0x8000u) & 0xffff0000u);
;                         const unsigned nb = ((b0 >> 8) & 0xffu) | (b1 & 0xff00u);
;                         if ((j & 1) == 0) lo4[2 * bj + (j >> 1)] = nb; else lo4[2 * bj + (j >> 1)] |= nb << 16;
;                         ss += x0 * x0 + x1 * x1;
;                     }
;                     *(PG8_GAS u32x4*)(hout + off + bj * HALF) = ho;
;                 }
;                 *(PG8_GAS u32x4*)(lout + loff) = lo4;
;                 ss += __shfl_xor(ss, 16); ss += __shfl_xor(ss, 32);
;                 if (fq == 0) __hip_atomic_fetch_add((PG8_GAS unsigned long long*)(rowsq_out + row), (unsigned long long)(ss * 16777216.0f + 0.5f), __ATOMIC_RELAXED, __HIP_MEMORY_SCOPE_AGENT);
	v_sub_u32_sdwa v176, v175, v176 dst_sel:WORD_1 dst_unused:UNUSED_PAD src0_sel:DWORD src1_sel:DWORD
	v_sub_u32_sdwa v180, v177, v180 dst_sel:WORD_1 dst_unused:UNUSED_PAD src0_sel:DWORD src1_sel:DWORD
	v_lshlrev_b32_e32 v119, 8, v119
	v_lshlrev_b32_e32 v174, 8, v174
	v_sub_u32_e32 v120, v177, v120
	v_sub_u32_e32 v124, v175, v124
	v_or_b32_e32 v181, v180, v119
	v_or_b32_e32 v180, v176, v174
	v_and_b32_e32 v120, 0xffff0000, v120
	v_and_b32_e32 v124, 0xffff0000, v124
	v_lshlrev_b32_sdwa v173, v230, v173 dst_sel:DWORD dst_unused:UNUSED_PAD src0_sel:DWORD src1_sel:BYTE_3
	v_lshlrev_b32_sdwa v172, v230, v172 dst_sel:DWORD dst_unused:UNUSED_PAD src0_sel:DWORD src1_sel:BYTE_3
	v_pk_fma_f32 v[180:181], v[218:219], 0.5, v[180:181] op_sel_hi:[1,0,1]
	v_or_b32_e32 v173, v120, v173
	v_or_b32_e32 v172, v124, v172
	v_mov_b32_e32 v120, v125
	v_add_u32_e32 v119, 0x8000, v180
	v_pk_fma_f32 v[124:125], v[120:121], 0.5, v[172:173] op_sel_hi:[1,0,1]
	v_lshrrev_b32_e32 v119, 16, v119
	v_add_u32_e32 v120, 0x8000, v124
	v_pk_mul_f32 v[138:139], v[224:225], v[224:225]
	v_pk_mul_f32 v[136:137], v[122:123], v[122:123]
	v_and_or_b32 v119, v120, s90, v119
	v_pk_mul_f32 v[120:121], v[124:125], v[124:125]
	v_pk_fma_f32 v[138:139], v[222:223], v[222:223], v[138:139]
	v_pk_fma_f32 v[136:137], v[134:135], v[134:135], v[136:137]
	v_pk_fma_f32 v[172:173], v[180:181], v[180:181], v[120:121]
	v_add_u32_e32 v120, 0x8000, v135
	v_lshrrev_b32_e32 v134, 8, v134
	v_lshrrev_b32_e32 v120, 16, v120
	v_add_u32_e32 v121, 0x8000, v123
	v_perm_b32 v122, v122, v134, s94
	v_add_f32_e32 v134, v138, v170
	v_and_or_b32 v120, v121, s90, v120
	v_add_u32_e32 v121, 0x8000, v181
	v_add_f32_e32 v134, v139, v134
	v_lshrrev_b32_e32 v121, 16, v121
	v_add_u32_e32 v174, 0x8000, v125
	v_add_f32_e32 v134, v171, v134
	v_and_or_b32 v121, v174, s90, v121
	v_lshrrev_b32_e32 v174, 8, v181
	v_lshrrev_b32_e32 v175, 8, v180
	v_add_f32_e32 v134, v136, v134
	v_lshrrev_b32_e32 v176, 8, v241
	v_lshrrev_b32_e32 v177, 8, v240
	v_perm_b32 v124, v124, v175, s94
	v_perm_b32 v125, v125, v174, s94
	v_lshrrev_b32_e32 v135, 8, v135
	v_lshrrev_b32_e32 v174, 8, v223
	v_lshrrev_b32_e32 v175, 8, v222
	v_add_f32_e32 v134, v172, v134
	v_perm_b32 v140, v140, v177, s94
	v_perm_b32 v141, v141, v176, s94
	v_perm_b32 v175, v224, v175, s94
	v_perm_b32 v174, v225, v174, s94
	v_perm_b32 v123, v123, v135, s94
	v_add_f32_e32 v134, v137, v134
	global_store_dwordx4 v[178:179], v[118:121], off offset:256 nt
	v_lshl_or_b32 v125, v125, 16, v123
	v_lshl_or_b32 v124, v124, 16, v122
	v_lshl_add_u64 v[118:119], s[34:35], 0, v[216:217]
	v_lshl_or_b32 v123, v141, 16, v174
	v_lshl_or_b32 v122, v140, 16, v175
	v_add_f32_e32 v134, v173, v134
	v_lshl_add_u64 v[118:119], v[118:119], 0, v[194:195]
	global_store_dwordx4 v[118:119], v[122:125], off nt
	ds_bpermute_b32 v118, v238, v134
	s_waitcnt lgkmcnt(0)
	v_add_f32_e32 v118, v134, v118
	ds_bpermute_b32 v119, v237, v118
	s_and_saveexec_b64 s[50:51], s[40:41]
	s_cbranch_execz .LBB0_406
	s_waitcnt lgkmcnt(0)
	v_add_f32_e32 v118, v118, v119
	v_fma_f32 v118, v118, s80, 0.5
	v_trunc_f32_e32 v118, v118
	v_mul_f32_e32 v119, 0x2f800000, v118
	v_floor_f32_e32 v119, v119
	v_fmac_f32_e32 v118, 0xcf800000, v119
	v_cvt_u32_f32_e32 v118, v118
	v_cvt_u32_f32_e32 v119, v119
	v_lshl_add_u64 v[120:121], v[198:199], 3, s[48:49]
	global_atomic_add_x2 v[120:121], v[118:119], off
.LBB0_406:
	s_or_b64 exec, exec, s[50:51]
	v_lshrrev_b32_sdwa v118, v229, v159 dst_sel:DWORD dst_unused:UNUSED_PAD src0_sel:DWORD src1_sel:BYTE_0
	s_waitcnt lgkmcnt(0)
	v_lshrrev_b32_sdwa v119, v229, v158 dst_sel:DWORD dst_unused:UNUSED_PAD src0_sel:DWORD src1_sel:BYTE_0
	v_sub_u32_sdwa v120, v166, v119 dst_sel:WORD_1 dst_unused:UNUSED_PAD src0_sel:DWORD src1_sel:DWORD
	v_sub_u32_sdwa v118, v168, v118 dst_sel:WORD_1 dst_unused:UNUSED_PAD src0_sel:DWORD src1_sel:DWORD
	v_lshlrev_b32_sdwa v119, v230, v159 dst_sel:DWORD dst_unused:UNUSED_PAD src0_sel:DWORD src1_sel:BYTE_0
	v_lshlrev_b32_sdwa v121, v230, v158 dst_sel:DWORD dst_unused:UNUSED_PAD src0_sel:DWORD src1_sel:BYTE_0
	v_or_b32_e32 v119, v118, v119
	v_or_b32_e32 v118, v120, v121
	v_mov_b32_e32 v120, v114
	v_mov_b32_e32 v121, v110
	v_pk_fma_f32 v[118:119], v[120:121], 0.5, v[118:119] op_sel_hi:[1,0,1]
	v_lshlrev_b32_e32 v122, 1, v159
	v_lshlrev_b32_e32 v123, 1, v158
	v_add_u32_e32 v110, 0x8000, v118
	v_lshrrev_b32_e32 v136, 16, v110
	v_and_b32_e32 v110, 0x10000, v122
	v_and_b32_e32 v114, 0x10000, v123
	v_sub_u32_e32 v110, v168, v110
	v_sub_u32_e32 v114, v166, v114
	v_and_b32_e32 v124, 0xff00, v159
	v_and_b32_e32 v125, 0xff00, v158
	v_and_b32_e32 v110, 0xffff0000, v110
	v_and_b32_e32 v114, 0xffff0000, v114
	v_or_b32_e32 v121, v110, v124
	v_or_b32_e32 v120, v114, v125
	v_mov_b32_e32 v110, v115
	v_and_b32_sdwa v122, v158, s93 dst_sel:DWORD dst_unused:UNUSED_PAD src0_sel:WORD_1 src1_sel:DWORD
	v_pk_fma_f32 v[114:115], v[110:111], 0.5, v[120:121] op_sel_hi:[1,0,1]
	v_and_b32_sdwa v111, v159, s93 dst_sel:DWORD dst_unused:UNUSED_PAD src0_sel:WORD_1 src1_sel:DWORD
	v_lshrrev_b32_e32 v123, 7, v122
	v_lshlrev_b32_sdwa v134, v231, v158 dst_sel:DWORD dst_unused:UNUSED_PAD src0_sel:DWORD src1_sel:BYTE_3
	v_lshlrev_b32_sdwa v135, v231, v159 dst_sel:DWORD dst_unused:UNUSED_PAD src0_sel:DWORD src1_sel:BYTE_3
	v_lshrrev_b32_e32 v124, 7, v111
	v_sub_u32_sdwa v125, v167, v123 dst_sel:WORD_1 dst_unused:UNUSED_PAD src0_sel:DWORD src1_sel:DWORD
	v_lshlrev_b32_e32 v122, 8, v122
	v_sub_u32_sdwa v123, v169, v124 dst_sel:WORD_1 dst_unused:UNUSED_PAD src0_sel:DWORD src1_sel:DWORD
	v_lshlrev_b32_e32 v111, 8, v111
	v_or_b32_e32 v122, v125, v122
	v_mov_b32_e32 v124, v116
	v_mov_b32_e32 v125, v112
	v_and_b32_e32 v112, 0x10000, v135
; #define PG8_GAS __attribute__((address_space(1)))
; __device__ __forceinline__ float e_x24(unsigned h16, unsigned l8) { return __uint_as_float(((h16 - (l8 >> 7)) << 16) | (l8 << 8)); }
;     __device__ __forceinline__ void operator()(const f32x4 (&acc)[2][2][4][2], const Unit& u, int wr, int wc, int fr, int fq) const {
;     ...
;             for (int m = 0; m < 4; ++m) {
;                 const int row = row0 + ai * HALF + m * 16; const size_t off = (size_t)row * 2048 + col0, loff = (size_t)row * 2048 + lcol; float ss = 0.f;
;                 const u32x4 l4 = L4[m];
;                 u32x4 lo4;
; #pragma unroll
;                 for (int bj = 0; bj < 2; ++bj) {
;                     const u32x4 h4 = H4[m][bj];
;                     u32x4 ho;
; #pragma unroll
;                     for (int j = 0; j < 4; ++j) {
;                         const unsigned lw = l4[2 * bj + (j >> 1)], lb0 = (lw >> (16 * (j & 1))) & 0xffu, lb1 = (lw >> (16 * (j & 1) + 8)) & 0xffu;
;                         const float x0 = e_x24(h4[j] & 0xffffu, lb0) + acc[ai][bj][m][j >> 1][2 * (j & 1)] * scale, x1 = e_x24(h4[j] >> 16, lb1) + acc[ai][bj][m][j >> 1][2 * (j & 1) + 1] * scale;
;                         const unsigned b0 = __float_as_uint(x0), b1 = __float_as_uint(x1);
;                         ho[j] = ((b0 + 0x8000u) >> 16) | ((b1 + 0x8000u) & 0xffff0000u);
;                         const unsigned nb = ((b0 >> 8) & 0xffu) | (b1 & 0xff00u);
;                         if ((j & 1) == 0) lo4[2 * bj + (j >> 1)] = nb; else lo4[2 * bj + (j >> 1)] |= nb << 16;
;                         ss += x0 * x0 + x1 * x1;
;                     }
;                     *(PG8_GAS u32x4*)(hout + off + bj * HALF) = ho;
;                 }
;                 *(PG8_GAS u32x4*)(lout + loff) = lo4;
;                 ss += __shfl_xor(ss, 16); ss += __shfl_xor(ss, 32);
;                 if (fq == 0) __hip_atomic_fetch_add((PG8_GAS unsigned long long*)(rowsq_out + row), (unsigned long long)(ss * 16777216.0f + 0.5f), __ATOMIC_RELAXED, __HIP_MEMORY_SCOPE_AGENT);
	v_and_b32_e32 v116, 0x10000, v134
	v_or_b32_e32 v123, v123, v111
	v_sub_u32_e32 v112, v169, v112
	v_sub_u32_e32 v116, v167, v116
	v_pk_fma_f32 v[122:123], v[124:125], 0.5, v[122:123] op_sel_hi:[1,0,1]
	v_and_b32_e32 v112, 0xffff0000, v112
	v_and_b32_e32 v116, 0xffff0000, v116
	v_lshlrev_b32_sdwa v124, v230, v159 dst_sel:DWORD dst_unused:UNUSED_PAD src0_sel:DWORD src1_sel:BYTE_3
	v_lshlrev_b32_sdwa v134, v230, v158 dst_sel:DWORD dst_unused:UNUSED_PAD src0_sel:DWORD src1_sel:BYTE_3
	v_or_b32_e32 v125, v112, v124
	v_or_b32_e32 v124, v116, v134
	v_mov_b32_e32 v112, v117
	v_add_u32_e32 v111, 0x8000, v122
	v_pk_fma_f32 v[116:117], v[112:113], 0.5, v[124:125] op_sel_hi:[1,0,1]
	v_lshrrev_b32_e32 v111, 16, v111
	v_add_u32_e32 v112, 0x8000, v116
	v_and_or_b32 v111, v112, s90, v111
	v_pk_mul_f32 v[112:113], v[116:117], v[116:117]
	v_add_u32_e32 v134, 0x8000, v117
	v_pk_fma_f32 v[124:125], v[122:123], v[122:123], v[112:113]
	v_add_u32_e32 v112, 0x8000, v119
	v_lshrrev_b32_e32 v112, 16, v112
	v_add_u32_e32 v113, 0x8000, v115
	v_and_or_b32 v112, v113, s90, v112
	v_add_u32_e32 v113, 0x8000, v123
	v_lshrrev_b32_e32 v113, 16, v113
	v_add_u32_e32 v110, 0x8000, v114
	v_and_or_b32 v113, v134, s90, v113
	v_lshl_add_u64 v[134:135], v[214:215], 1, s[30:31]
	v_and_or_b32 v110, v110, s90, v136
	v_lshl_add_u64 v[134:135], v[196:197], 1, v[134:135]
	global_store_dwordx4 v[134:135], v[110:113], off nt
	v_lshlrev_b32_e32 v136, 1, v161
	v_lshlrev_b32_e32 v137, 1, v160
	v_lshrrev_b32_sdwa v110, v229, v161 dst_sel:DWORD dst_unused:UNUSED_PAD src0_sel:DWORD src1_sel:BYTE_0
	v_lshrrev_b32_sdwa v111, v229, v160 dst_sel:DWORD dst_unused:UNUSED_PAD src0_sel:DWORD src1_sel:BYTE_0
	v_sub_u32_sdwa v112, v162, v111 dst_sel:WORD_1 dst_unused:UNUSED_PAD src0_sel:DWORD src1_sel:DWORD
	v_sub_u32_sdwa v110, v164, v110 dst_sel:WORD_1 dst_unused:UNUSED_PAD src0_sel:DWORD src1_sel:DWORD
	v_lshlrev_b32_sdwa v111, v230, v161 dst_sel:DWORD dst_unused:UNUSED_PAD src0_sel:DWORD src1_sel:BYTE_0
	v_lshlrev_b32_sdwa v113, v230, v160 dst_sel:DWORD dst_unused:UNUSED_PAD src0_sel:DWORD src1_sel:BYTE_0
	v_or_b32_e32 v111, v110, v111
	v_or_b32_e32 v110, v112, v113
	v_mov_b32_e32 v112, v106
	v_mov_b32_e32 v113, v102
	v_pk_fma_f32 v[110:111], v[112:113], 0.5, v[110:111] op_sel_hi:[1,0,1]
	v_and_b32_e32 v112, 0x10000, v137
	v_add_u32_e32 v102, 0x8000, v110
	v_lshrrev_b32_e32 v106, 16, v102
	v_and_b32_e32 v102, 0x10000, v136
	v_sub_u32_e32 v102, v164, v102
	v_sub_u32_e32 v112, v162, v112
	v_and_b32_e32 v138, 0xff00, v161
	v_and_b32_e32 v139, 0xff00, v160
	v_and_b32_e32 v102, 0xffff0000, v102
	v_and_b32_e32 v112, 0xffff0000, v112
	v_or_b32_e32 v113, v102, v138
	v_or_b32_e32 v112, v112, v139
	v_mov_b32_e32 v102, v107
	v_pk_fma_f32 v[102:103], v[102:103], 0.5, v[112:113] op_sel_hi:[1,0,1]
	v_and_b32_sdwa v136, v160, s93 dst_sel:DWORD dst_unused:UNUSED_PAD src0_sel:WORD_1 src1_sel:DWORD
	v_add_u32_e32 v107, 0x8000, v102
	v_and_or_b32 v106, v107, s90, v106
	v_and_b32_sdwa v107, v161, s93 dst_sel:DWORD dst_unused:UNUSED_PAD src0_sel:WORD_1 src1_sel:DWORD
	v_lshrrev_b32_e32 v137, 7, v136
	v_lshrrev_b32_e32 v138, 7, v107
	v_sub_u32_sdwa v139, v163, v137 dst_sel:WORD_1 dst_unused:UNUSED_PAD src0_sel:DWORD src1_sel:DWORD
	v_sub_u32_sdwa v137, v165, v138 dst_sel:WORD_1 dst_unused:UNUSED_PAD src0_sel:DWORD src1_sel:DWORD
	v_lshlrev_b32_e32 v107, 8, v107
	v_lshlrev_b32_e32 v136, 8, v136
	v_or_b32_e32 v137, v137, v107
	v_or_b32_e32 v136, v139, v136
	v_mov_b32_e32 v138, v108
	v_mov_b32_e32 v139, v104
	v_pk_fma_f32 v[136:137], v[138:139], 0.5, v[136:137] op_sel_hi:[1,0,1]
	v_lshlrev_b32_sdwa v140, v231, v160 dst_sel:DWORD dst_unused:UNUSED_PAD src0_sel:DWORD src1_sel:BYTE_3
	v_lshlrev_b32_sdwa v141, v231, v161 dst_sel:DWORD dst_unused:UNUSED_PAD src0_sel:DWORD src1_sel:BYTE_3
	v_add_u32_e32 v104, 0x8000, v136
	v_lshrrev_b32_e32 v107, 16, v104
	v_and_b32_e32 v104, 0x10000, v141
	v_and_b32_e32 v108, 0x10000, v140
	v_sub_u32_e32 v104, v165, v104
	v_sub_u32_e32 v108, v163, v108
	v_pk_mul_f32 v[120:121], v[114:115], v[114:115]
	v_pk_mul_f32 v[112:113], v[102:103], v[102:103]
	v_and_b32_e32 v104, 0xffff0000, v104
	v_and_b32_e32 v108, 0xffff0000, v108
	v_lshlrev_b32_sdwa v138, v230, v161 dst_sel:DWORD dst_unused:UNUSED_PAD src0_sel:DWORD src1_sel:BYTE_3
	v_lshlrev_b32_sdwa v140, v230, v160 dst_sel:DWORD dst_unused:UNUSED_PAD src0_sel:DWORD src1_sel:BYTE_3
	v_pk_fma_f32 v[120:121], v[118:119], v[118:119], v[120:121]
	v_pk_fma_f32 v[112:113], v[110:111], v[110:111], v[112:113]
	v_or_b32_e32 v139, v104, v138
	v_or_b32_e32 v138, v108, v140
	v_mov_b32_e32 v104, v109
	v_lshrrev_b32_e32 v110, 8, v110
	v_pk_fma_f32 v[104:105], v[104:105], 0.5, v[138:139] op_sel_hi:[1,0,1]
	v_perm_b32 v102, v102, v110, s94
	v_add_f32_e32 v110, v120, v124
	v_add_u32_e32 v108, 0x8000, v104
	v_add_f32_e32 v110, v121, v110
	v_and_or_b32 v107, v108, s90, v107
	v_pk_mul_f32 v[108:109], v[104:105], v[104:105]
	v_add_f32_e32 v110, v125, v110
	v_pk_fma_f32 v[138:139], v[136:137], v[136:137], v[108:109]
	v_add_f32_e32 v110, v112, v110
	v_add_f32_e32 v110, v138, v110
	v_lshrrev_b32_e32 v118, 8, v118
	v_add_f32_e32 v110, v113, v110
	v_lshrrev_b32_e32 v119, 8, v119
	v_perm_b32 v114, v114, v118, s94
	v_add_f32_e32 v118, v139, v110
	v_perm_b32 v115, v115, v119, s94
	ds_bpermute_b32 v119, v238, v118
	v_add_u32_e32 v108, 0x8000, v111
	v_lshrrev_b32_e32 v108, 16, v108
	v_add_u32_e32 v109, 0x8000, v103
	v_lshrrev_b32_e32 v136, 8, v136
	v_and_or_b32 v108, v109, s90, v108
	v_add_u32_e32 v109, 0x8000, v137
	v_lshrrev_b32_e32 v137, 8, v137
	v_perm_b32 v104, v104, v136, s94
	v_lshrrev_b32_e32 v111, 8, v111
	v_add_u32_e32 v140, 0x8000, v105
	v_perm_b32 v105, v105, v137, s94
	v_perm_b32 v103, v103, v111, s94
	v_lshl_or_b32 v112, v104, 16, v102
	s_waitcnt lgkmcnt(0)
	v_add_f32_e32 v102, v118, v119
	v_lshl_or_b32 v113, v105, 16, v103
	ds_bpermute_b32 v103, v237, v102
	v_lshrrev_b32_e32 v123, 8, v123
	v_lshrrev_b32_e32 v122, 8, v122
	v_lshrrev_b32_e32 v109, 16, v109
	v_perm_b32 v116, v116, v122, s94
	v_perm_b32 v117, v117, v123, s94
	v_lshl_add_u64 v[104:105], s[34:35], 0, v[214:215]
	v_and_or_b32 v109, v140, s90, v109
	v_lshl_or_b32 v111, v117, 16, v115
	v_lshl_or_b32 v110, v116, 16, v114
	v_lshl_add_u64 v[104:105], v[104:105], 0, v[194:195]
	global_store_dwordx4 v[134:135], v[106:109], off offset:256 nt
	global_store_dwordx4 v[104:105], v[110:113], off nt
	s_and_saveexec_b64 s[50:51], s[40:41]
	s_cbranch_execz .LBB0_408
	s_waitcnt lgkmcnt(0)
	v_add_f32_e32 v102, v102, v103
	v_fma_f32 v102, v102, s80, 0.5
	v_trunc_f32_e32 v102, v102
	v_mul_f32_e32 v103, 0x2f800000, v102
	v_floor_f32_e32 v103, v103
	v_fmac_f32_e32 v102, 0xcf800000, v103
	v_cvt_u32_f32_e32 v102, v102
	v_cvt_u32_f32_e32 v103, v103
	v_lshl_add_u64 v[104:105], v[212:213], 3, s[48:49]
	global_atomic_add_x2 v[104:105], v[102:103], off
; #define PG8_GAS __attribute__((address_space(1)))
; __device__ __forceinline__ float e_x24(unsigned h16, unsigned l8) { return __uint_as_float(((h16 - (l8 >> 7)) << 16) | (l8 << 8)); }
;     __device__ __forceinline__ void operator()(const f32x4 (&acc)[2][2][4][2], const Unit& u, int wr, int wc, int fr, int fq) const {
;     ...
;             for (int m = 0; m < 4; ++m) {
;                 const int row = row0 + ai * HALF + m * 16; const size_t off = (size_t)row * 2048 + col0, loff = (size_t)row * 2048 + lcol; float ss = 0.f;
;                 const u32x4 l4 = L4[m];
;                 u32x4 lo4;
; #pragma unroll
;                 for (int bj = 0; bj < 2; ++bj) {
;                     const u32x4 h4 = H4[m][bj];
;                     u32x4 ho;
; #pragma unroll
;                     for (int j = 0; j < 4; ++j) {
;                         const unsigned lw = l4[2 * bj + (j >> 1)], lb0 = (lw >> (16 * (j & 1))) & 0xffu, lb1 = (lw >> (16 * (j & 1) + 8)) & 0xffu;
;                         const float x0 = e_x24(h4[j] & 0xffffu, lb0) + acc[ai][bj][m][j >> 1][2 * (j & 1)] * scale, x1 = e_x24(h4[j] >> 16, lb1) + acc[ai][bj][m][j >> 1][2 * (j & 1) + 1] * scale;
;                         const unsigned b0 = __float_as_uint(x0), b1 = __float_as_uint(x1);
;                         ho[j] = ((b0 + 0x8000u) >> 16) | ((b1 + 0x8000u) & 0xffff0000u);
;                         const unsigned nb = ((b0 >> 8) & 0xffu) | (b1 & 0xff00u);
;                         if ((j & 1) == 0) lo4[2 * bj + (j >> 1)] = nb; else lo4[2 * bj + (j >> 1)] |= nb << 16;
;                         ss += x0 * x0 + x1 * x1;
;                     }
;                     *(PG8_GAS u32x4*)(hout + off + bj * HALF) = ho;
.LBB0_408:
	s_or_b64 exec, exec, s[50:51]
	v_lshrrev_b32_sdwa v102, v229, v147 dst_sel:DWORD dst_unused:UNUSED_PAD src0_sel:DWORD src1_sel:BYTE_0
	s_waitcnt lgkmcnt(0)
	v_lshrrev_b32_sdwa v103, v229, v146 dst_sel:DWORD dst_unused:UNUSED_PAD src0_sel:DWORD src1_sel:BYTE_0
	v_sub_u32_sdwa v104, v154, v103 dst_sel:WORD_1 dst_unused:UNUSED_PAD src0_sel:DWORD src1_sel:DWORD
	v_sub_u32_sdwa v102, v156, v102 dst_sel:WORD_1 dst_unused:UNUSED_PAD src0_sel:DWORD src1_sel:DWORD
	v_lshlrev_b32_sdwa v103, v230, v147 dst_sel:DWORD dst_unused:UNUSED_PAD src0_sel:DWORD src1_sel:BYTE_0
	v_lshlrev_b32_sdwa v105, v230, v146 dst_sel:DWORD dst_unused:UNUSED_PAD src0_sel:DWORD src1_sel:BYTE_0
	v_or_b32_e32 v103, v102, v103
	v_or_b32_e32 v102, v104, v105
	v_mov_b32_e32 v104, v92
	v_mov_b32_e32 v105, v88
	v_pk_fma_f32 v[102:103], v[104:105], 0.5, v[102:103] op_sel_hi:[1,0,1]
	v_lshlrev_b32_e32 v106, 1, v147
	v_lshlrev_b32_e32 v107, 1, v146
	v_add_u32_e32 v88, 0x8000, v102
	v_lshrrev_b32_e32 v112, 16, v88
	v_and_b32_e32 v88, 0x10000, v106
	v_and_b32_e32 v92, 0x10000, v107
	v_sub_u32_e32 v88, v156, v88
	v_sub_u32_e32 v92, v154, v92
	v_and_b32_e32 v108, 0xff00, v147
	v_and_b32_e32 v109, 0xff00, v146
	v_and_b32_e32 v88, 0xffff0000, v88
	v_and_b32_e32 v92, 0xffff0000, v92
	v_or_b32_e32 v105, v88, v108
	v_or_b32_e32 v104, v92, v109
	v_mov_b32_e32 v88, v93
	v_and_b32_sdwa v106, v146, s93 dst_sel:DWORD dst_unused:UNUSED_PAD src0_sel:WORD_1 src1_sel:DWORD
	v_pk_fma_f32 v[92:93], v[88:89], 0.5, v[104:105] op_sel_hi:[1,0,1]
	v_and_b32_sdwa v89, v147, s93 dst_sel:DWORD dst_unused:UNUSED_PAD src0_sel:WORD_1 src1_sel:DWORD
	v_lshrrev_b32_e32 v107, 7, v106
	v_lshlrev_b32_sdwa v110, v231, v146 dst_sel:DWORD dst_unused:UNUSED_PAD src0_sel:DWORD src1_sel:BYTE_3
	v_lshlrev_b32_sdwa v111, v231, v147 dst_sel:DWORD dst_unused:UNUSED_PAD src0_sel:DWORD src1_sel:BYTE_3
	v_lshrrev_b32_e32 v108, 7, v89
	v_sub_u32_sdwa v109, v155, v107 dst_sel:WORD_1 dst_unused:UNUSED_PAD src0_sel:DWORD src1_sel:DWORD
	v_lshlrev_b32_e32 v106, 8, v106
	v_sub_u32_sdwa v107, v157, v108 dst_sel:WORD_1 dst_unused:UNUSED_PAD src0_sel:DWORD src1_sel:DWORD
	v_lshlrev_b32_e32 v89, 8, v89
	v_or_b32_e32 v106, v109, v106
	v_mov_b32_e32 v108, v94
	v_mov_b32_e32 v109, v90
	v_and_b32_e32 v90, 0x10000, v111
	v_and_b32_e32 v94, 0x10000, v110
	v_or_b32_e32 v107, v107, v89
	v_sub_u32_e32 v90, v157, v90
	v_sub_u32_e32 v94, v155, v94
	v_pk_fma_f32 v[106:107], v[108:109], 0.5, v[106:107] op_sel_hi:[1,0,1]
	v_and_b32_e32 v90, 0xffff0000, v90
	v_and_b32_e32 v94, 0xffff0000, v94
	v_lshlrev_b32_sdwa v108, v230, v147 dst_sel:DWORD dst_unused:UNUSED_PAD src0_sel:DWORD src1_sel:BYTE_3
	v_lshlrev_b32_sdwa v110, v230, v146 dst_sel:DWORD dst_unused:UNUSED_PAD src0_sel:DWORD src1_sel:BYTE_3
	v_or_b32_e32 v109, v90, v108
	v_or_b32_e32 v108, v94, v110
	v_mov_b32_e32 v90, v95
	v_add_u32_e32 v89, 0x8000, v106
	v_pk_fma_f32 v[94:95], v[90:91], 0.5, v[108:109] op_sel_hi:[1,0,1]
	v_lshrrev_b32_e32 v89, 16, v89
	v_add_u32_e32 v90, 0x8000, v94
	v_and_or_b32 v89, v90, s90, v89
	v_pk_mul_f32 v[90:91], v[94:95], v[94:95]
	v_add_u32_e32 v110, 0x8000, v95
	v_pk_fma_f32 v[108:109], v[106:107], v[106:107], v[90:91]
	v_add_u32_e32 v90, 0x8000, v103
	v_lshrrev_b32_e32 v90, 16, v90
	v_add_u32_e32 v91, 0x8000, v93
	v_and_or_b32 v90, v91, s90, v90
	v_add_u32_e32 v91, 0x8000, v107
	v_lshrrev_b32_e32 v91, 16, v91
	v_add_u32_e32 v88, 0x8000, v92
	v_and_or_b32 v91, v110, s90, v91
	v_lshl_add_u64 v[110:111], v[210:211], 1, s[30:31]
	v_and_or_b32 v88, v88, s90, v112
	v_lshl_add_u64 v[110:111], v[196:197], 1, v[110:111]
	global_store_dwordx4 v[110:111], v[88:91], off nt
	v_lshlrev_b32_e32 v112, 1, v149
	v_lshlrev_b32_e32 v113, 1, v148
	v_lshrrev_b32_sdwa v88, v229, v149 dst_sel:DWORD dst_unused:UNUSED_PAD src0_sel:DWORD src1_sel:BYTE_0
	v_lshrrev_b32_sdwa v89, v229, v148 dst_sel:DWORD dst_unused:UNUSED_PAD src0_sel:DWORD src1_sel:BYTE_0
	v_sub_u32_sdwa v90, v150, v89 dst_sel:WORD_1 dst_unused:UNUSED_PAD src0_sel:DWORD src1_sel:DWORD
	v_sub_u32_sdwa v88, v152, v88 dst_sel:WORD_1 dst_unused:UNUSED_PAD src0_sel:DWORD src1_sel:DWORD
	v_lshlrev_b32_sdwa v89, v230, v149 dst_sel:DWORD dst_unused:UNUSED_PAD src0_sel:DWORD src1_sel:BYTE_0
	v_lshlrev_b32_sdwa v91, v230, v148 dst_sel:DWORD dst_unused:UNUSED_PAD src0_sel:DWORD src1_sel:BYTE_0
	v_or_b32_e32 v89, v88, v89
	v_or_b32_e32 v88, v90, v91
	v_mov_b32_e32 v90, v84
	v_mov_b32_e32 v91, v80
	v_pk_fma_f32 v[88:89], v[90:91], 0.5, v[88:89] op_sel_hi:[1,0,1]
	v_and_b32_e32 v90, 0x10000, v113
	v_add_u32_e32 v80, 0x8000, v88
	v_lshrrev_b32_e32 v84, 16, v80
	v_and_b32_e32 v80, 0x10000, v112
	v_sub_u32_e32 v80, v152, v80
	v_sub_u32_e32 v90, v150, v90
	v_and_b32_e32 v114, 0xff00, v149
	v_and_b32_e32 v115, 0xff00, v148
	v_and_b32_e32 v80, 0xffff0000, v80
	v_and_b32_e32 v90, 0xffff0000, v90
	v_or_b32_e32 v91, v80, v114
	v_or_b32_e32 v90, v90, v115
	v_mov_b32_e32 v80, v85
	v_pk_fma_f32 v[80:81], v[80:81], 0.5, v[90:91] op_sel_hi:[1,0,1]
	v_and_b32_sdwa v112, v148, s93 dst_sel:DWORD dst_unused:UNUSED_PAD src0_sel:WORD_1 src1_sel:DWORD
	v_add_u32_e32 v85, 0x8000, v80
	v_and_or_b32 v84, v85, s90, v84
	v_and_b32_sdwa v85, v149, s93 dst_sel:DWORD dst_unused:UNUSED_PAD src0_sel:WORD_1 src1_sel:DWORD
	v_lshrrev_b32_e32 v113, 7, v112
	v_lshrrev_b32_e32 v114, 7, v85
	v_sub_u32_sdwa v115, v151, v113 dst_sel:WORD_1 dst_unused:UNUSED_PAD src0_sel:DWORD src1_sel:DWORD
	v_sub_u32_sdwa v113, v153, v114 dst_sel:WORD_1 dst_unused:UNUSED_PAD src0_sel:DWORD src1_sel:DWORD
	v_lshlrev_b32_e32 v85, 8, v85
	v_lshlrev_b32_e32 v112, 8, v112
	v_or_b32_e32 v113, v113, v85
	v_or_b32_e32 v112, v115, v112
	v_mov_b32_e32 v114, v86
	v_mov_b32_e32 v115, v82
; #define PG8_GAS __attribute__((address_space(1)))
; __device__ __forceinline__ float e_x24(unsigned h16, unsigned l8) { return __uint_as_float(((h16 - (l8 >> 7)) << 16) | (l8 << 8)); }
;     __device__ __forceinline__ void operator()(const f32x4 (&acc)[2][2][4][2], const Unit& u, int wr, int wc, int fr, int fq) const {
;     ...
;             for (int m = 0; m < 4; ++m) {
;                 const int row = row0 + ai * HALF + m * 16; const size_t off = (size_t)row * 2048 + col0, loff = (size_t)row * 2048 + lcol; float ss = 0.f;
;                 const u32x4 l4 = L4[m];
;                 u32x4 lo4;
; #pragma unroll
;                 for (int bj = 0; bj < 2; ++bj) {
;                     const u32x4 h4 = H4[m][bj];
;                     u32x4 ho;
; #pragma unroll
;                     for (int j = 0; j < 4; ++j) {
;                         const unsigned lw = l4[2 * bj + (j >> 1)], lb0 = (lw >> (16 * (j & 1))) & 0xffu, lb1 = (lw >> (16 * (j & 1) + 8)) & 0xffu;
;                         const float x0 = e_x24(h4[j] & 0xffffu, lb0) + acc[ai][bj][m][j >> 1][2 * (j & 1)] * scale, x1 = e_x24(h4[j] >> 16, lb1) + acc[ai][bj][m][j >> 1][2 * (j & 1) + 1] * scale;
;                         const unsigned b0 = __float_as_uint(x0), b1 = __float_as_uint(x1);
;                         ho[j] = ((b0 + 0x8000u) >> 16) | ((b1 + 0x8000u) & 0xffff0000u);
;                         const unsigned nb = ((b0 >> 8) & 0xffu) | (b1 & 0xff00u);
;                         if ((j & 1) == 0) lo4[2 * bj + (j >> 1)] = nb; else lo4[2 * bj + (j >> 1)] |= nb << 16;
;                         ss += x0 * x0 + x1 * x1;
;                     }
;                     *(PG8_GAS u32x4*)(hout + off + bj * HALF) = ho;
;                 }
;                 *(PG8_GAS u32x4*)(lout + loff) = lo4;
;                 ss += __shfl_xor(ss, 16); ss += __shfl_xor(ss, 32);
;                 if (fq == 0) __hip_atomic_fetch_add((PG8_GAS unsigned long long*)(rowsq_out + row), (unsigned long long)(ss * 16777216.0f + 0.5f), __ATOMIC_RELAXED, __HIP_MEMORY_SCOPE_AGENT);
	v_pk_fma_f32 v[112:113], v[114:115], 0.5, v[112:113] op_sel_hi:[1,0,1]
	v_lshlrev_b32_sdwa v116, v231, v148 dst_sel:DWORD dst_unused:UNUSED_PAD src0_sel:DWORD src1_sel:BYTE_3
	v_lshlrev_b32_sdwa v117, v231, v149 dst_sel:DWORD dst_unused:UNUSED_PAD src0_sel:DWORD src1_sel:BYTE_3
	v_add_u32_e32 v82, 0x8000, v112
	v_lshrrev_b32_e32 v85, 16, v82
	v_and_b32_e32 v82, 0x10000, v117
	v_and_b32_e32 v86, 0x10000, v116
	v_sub_u32_e32 v82, v153, v82
	v_sub_u32_e32 v86, v151, v86
	v_pk_mul_f32 v[104:105], v[92:93], v[92:93]
	v_pk_mul_f32 v[90:91], v[80:81], v[80:81]
	v_and_b32_e32 v82, 0xffff0000, v82
	v_and_b32_e32 v86, 0xffff0000, v86
	v_lshlrev_b32_sdwa v114, v230, v149 dst_sel:DWORD dst_unused:UNUSED_PAD src0_sel:DWORD src1_sel:BYTE_3
	v_lshlrev_b32_sdwa v116, v230, v148 dst_sel:DWORD dst_unused:UNUSED_PAD src0_sel:DWORD src1_sel:BYTE_3
	v_pk_fma_f32 v[104:105], v[102:103], v[102:103], v[104:105]
	v_pk_fma_f32 v[90:91], v[88:89], v[88:89], v[90:91]
	v_or_b32_e32 v115, v82, v114
	v_or_b32_e32 v114, v86, v116
	v_mov_b32_e32 v82, v87
	v_lshrrev_b32_e32 v88, 8, v88
	v_pk_fma_f32 v[82:83], v[82:83], 0.5, v[114:115] op_sel_hi:[1,0,1]
	v_perm_b32 v80, v80, v88, s94
	v_add_f32_e32 v88, v104, v108
	v_add_u32_e32 v86, 0x8000, v82
	v_add_f32_e32 v88, v105, v88
	v_and_or_b32 v85, v86, s90, v85
	v_pk_mul_f32 v[86:87], v[82:83], v[82:83]
	v_add_f32_e32 v88, v109, v88
	v_pk_fma_f32 v[114:115], v[112:113], v[112:113], v[86:87]
	v_add_f32_e32 v88, v90, v88
	v_add_f32_e32 v88, v114, v88
	v_lshrrev_b32_e32 v102, 8, v102
	v_add_f32_e32 v88, v91, v88
	v_lshrrev_b32_e32 v103, 8, v103
	v_perm_b32 v92, v92, v102, s94
	v_add_f32_e32 v102, v115, v88
	v_perm_b32 v93, v93, v103, s94
	ds_bpermute_b32 v103, v238, v102
	v_add_u32_e32 v86, 0x8000, v89
	v_lshrrev_b32_e32 v86, 16, v86
	v_add_u32_e32 v87, 0x8000, v81
	v_lshrrev_b32_e32 v112, 8, v112
	v_and_or_b32 v86, v87, s90, v86
	v_add_u32_e32 v87, 0x8000, v113
	v_lshrrev_b32_e32 v113, 8, v113
	v_perm_b32 v82, v82, v112, s94
	v_lshrrev_b32_e32 v89, 8, v89
	v_add_u32_e32 v116, 0x8000, v83
	v_perm_b32 v83, v83, v113, s94
	v_perm_b32 v81, v81, v89, s94
	v_lshl_or_b32 v90, v82, 16, v80
	s_waitcnt lgkmcnt(0)
	v_add_f32_e32 v80, v102, v103
	v_lshl_or_b32 v91, v83, 16, v81
	ds_bpermute_b32 v81, v237, v80
	v_lshrrev_b32_e32 v107, 8, v107
	v_lshrrev_b32_e32 v106, 8, v106
	v_lshrrev_b32_e32 v87, 16, v87
	v_perm_b32 v94, v94, v106, s94
	v_perm_b32 v95, v95, v107, s94
	v_lshl_add_u64 v[82:83], s[34:35], 0, v[210:211]
	v_and_or_b32 v87, v116, s90, v87
	v_lshl_or_b32 v89, v95, 16, v93
	v_lshl_or_b32 v88, v94, 16, v92
	v_lshl_add_u64 v[82:83], v[82:83], 0, v[194:195]
	global_store_dwordx4 v[110:111], v[84:87], off offset:256 nt
	global_store_dwordx4 v[82:83], v[88:91], off nt
	s_and_saveexec_b64 s[50:51], s[40:41]
	s_cbranch_execz .LBB0_410
	s_waitcnt lgkmcnt(0)
	v_add_f32_e32 v80, v80, v81
	v_fma_f32 v80, v80, s80, 0.5
	v_trunc_f32_e32 v80, v80
	v_mul_f32_e32 v81, 0x2f800000, v80
	v_floor_f32_e32 v81, v81
	v_fmac_f32_e32 v80, 0xcf800000, v81
	v_cvt_u32_f32_e32 v80, v80
	v_cvt_u32_f32_e32 v81, v81
	v_lshl_add_u64 v[82:83], v[208:209], 3, s[48:49]
	global_atomic_add_x2 v[82:83], v[80:81], off
.LBB0_410:
	s_or_b64 exec, exec, s[50:51]
	v_lshrrev_b32_sdwa v80, v229, v127 dst_sel:DWORD dst_unused:UNUSED_PAD src0_sel:DWORD src1_sel:BYTE_0
	s_waitcnt lgkmcnt(0)
	v_lshrrev_b32_sdwa v81, v229, v126 dst_sel:DWORD dst_unused:UNUSED_PAD src0_sel:DWORD src1_sel:BYTE_0
	v_sub_u32_sdwa v82, v142, v81 dst_sel:WORD_1 dst_unused:UNUSED_PAD src0_sel:DWORD src1_sel:DWORD
	v_sub_u32_sdwa v80, v144, v80 dst_sel:WORD_1 dst_unused:UNUSED_PAD src0_sel:DWORD src1_sel:DWORD
	v_lshlrev_b32_sdwa v81, v230, v127 dst_sel:DWORD dst_unused:UNUSED_PAD src0_sel:DWORD src1_sel:BYTE_0
	v_lshlrev_b32_sdwa v83, v230, v126 dst_sel:DWORD dst_unused:UNUSED_PAD src0_sel:DWORD src1_sel:BYTE_0
	v_or_b32_e32 v81, v80, v81
	v_or_b32_e32 v80, v82, v83
	v_mov_b32_e32 v82, v76
	v_mov_b32_e32 v83, v72
	v_pk_fma_f32 v[80:81], v[82:83], 0.5, v[80:81] op_sel_hi:[1,0,1]
	v_lshlrev_b32_e32 v84, 1, v127
	v_lshlrev_b32_e32 v85, 1, v126
	v_add_u32_e32 v72, 0x8000, v80
	v_lshrrev_b32_e32 v90, 16, v72
	v_and_b32_e32 v72, 0x10000, v84
	v_and_b32_e32 v76, 0x10000, v85
	v_sub_u32_e32 v72, v144, v72
	v_sub_u32_e32 v76, v142, v76
	v_and_b32_e32 v86, 0xff00, v127
	v_and_b32_e32 v87, 0xff00, v126
	v_and_b32_e32 v72, 0xffff0000, v72
	v_and_b32_e32 v76, 0xffff0000, v76
	v_or_b32_e32 v83, v72, v86
	v_or_b32_e32 v82, v76, v87
	v_mov_b32_e32 v72, v77
	v_and_b32_sdwa v84, v126, s93 dst_sel:DWORD dst_unused:UNUSED_PAD src0_sel:WORD_1 src1_sel:DWORD
	v_pk_fma_f32 v[76:77], v[72:73], 0.5, v[82:83] op_sel_hi:[1,0,1]
	v_and_b32_sdwa v73, v127, s93 dst_sel:DWORD dst_unused:UNUSED_PAD src0_sel:WORD_1 src1_sel:DWORD
	v_lshrrev_b32_e32 v85, 7, v84
	v_lshlrev_b32_sdwa v88, v231, v126 dst_sel:DWORD dst_unused:UNUSED_PAD src0_sel:DWORD src1_sel:BYTE_3
	v_lshlrev_b32_sdwa v89, v231, v127 dst_sel:DWORD dst_unused:UNUSED_PAD src0_sel:DWORD src1_sel:BYTE_3
	v_lshrrev_b32_e32 v86, 7, v73
	v_sub_u32_sdwa v87, v143, v85 dst_sel:WORD_1 dst_unused:UNUSED_PAD src0_sel:DWORD src1_sel:DWORD
	v_lshlrev_b32_e32 v84, 8, v84
	v_sub_u32_sdwa v85, v145, v86 dst_sel:WORD_1 dst_unused:UNUSED_PAD src0_sel:DWORD src1_sel:DWORD
	v_lshlrev_b32_e32 v73, 8, v73
	v_or_b32_e32 v84, v87, v84
	v_mov_b32_e32 v86, v78
	v_mov_b32_e32 v87, v74
	v_and_b32_e32 v74, 0x10000, v89
	v_and_b32_e32 v78, 0x10000, v88
	v_or_b32_e32 v85, v85, v73
	v_sub_u32_e32 v74, v145, v74
	v_sub_u32_e32 v78, v143, v78
	v_pk_fma_f32 v[84:85], v[86:87], 0.5, v[84:85] op_sel_hi:[1,0,1]
	v_and_b32_e32 v74, 0xffff0000, v74
	v_and_b32_e32 v78, 0xffff0000, v78
; #define PG8_GAS __attribute__((address_space(1)))
; __device__ __forceinline__ float e_x24(unsigned h16, unsigned l8) { return __uint_as_float(((h16 - (l8 >> 7)) << 16) | (l8 << 8)); }
;     __device__ __forceinline__ void operator()(const f32x4 (&acc)[2][2][4][2], const Unit& u, int wr, int wc, int fr, int fq) const {
;     ...
;             for (int m = 0; m < 4; ++m) {
;                 const int row = row0 + ai * HALF + m * 16; const size_t off = (size_t)row * 2048 + col0, loff = (size_t)row * 2048 + lcol; float ss = 0.f;
;                 const u32x4 l4 = L4[m];
;                 u32x4 lo4;
; #pragma unroll
;                 for (int bj = 0; bj < 2; ++bj) {
;                     const u32x4 h4 = H4[m][bj];
;                     u32x4 ho;
; #pragma unroll
;                     for (int j = 0; j < 4; ++j) {
;                         const unsigned lw = l4[2 * bj + (j >> 1)], lb0 = (lw >> (16 * (j & 1))) & 0xffu, lb1 = (lw >> (16 * (j & 1) + 8)) & 0xffu;
;                         const float x0 = e_x24(h4[j] & 0xffffu, lb0) + acc[ai][bj][m][j >> 1][2 * (j & 1)] * scale, x1 = e_x24(h4[j] >> 16, lb1) + acc[ai][bj][m][j >> 1][2 * (j & 1) + 1] * scale;
;                         const unsigned b0 = __float_as_uint(x0), b1 = __float_as_uint(x1);
;                         ho[j] = ((b0 + 0x8000u) >> 16) | ((b1 + 0x8000u) & 0xffff0000u);
;                         const unsigned nb = ((b0 >> 8) & 0xffu) | (b1 & 0xff00u);
;                         if ((j & 1) == 0) lo4[2 * bj + (j >> 1)] = nb; else lo4[2 * bj + (j >> 1)] |= nb << 16;
;                         ss += x0 * x0 + x1 * x1;
;                     }
;                     *(PG8_GAS u32x4*)(hout + off + bj * HALF) = ho;
;                 }
;                 *(PG8_GAS u32x4*)(lout + loff) = lo4;
;                 ss += __shfl_xor(ss, 16); ss += __shfl_xor(ss, 32);
;                 if (fq == 0) __hip_atomic_fetch_add((PG8_GAS unsigned long long*)(rowsq_out + row), (unsigned long long)(ss * 16777216.0f + 0.5f), __ATOMIC_RELAXED, __HIP_MEMORY_SCOPE_AGENT);
	v_lshlrev_b32_sdwa v86, v230, v127 dst_sel:DWORD dst_unused:UNUSED_PAD src0_sel:DWORD src1_sel:BYTE_3
	v_lshlrev_b32_sdwa v88, v230, v126 dst_sel:DWORD dst_unused:UNUSED_PAD src0_sel:DWORD src1_sel:BYTE_3
	v_or_b32_e32 v87, v74, v86
	v_or_b32_e32 v86, v78, v88
	v_mov_b32_e32 v74, v79
	v_add_u32_e32 v73, 0x8000, v84
	v_pk_fma_f32 v[78:79], v[74:75], 0.5, v[86:87] op_sel_hi:[1,0,1]
	v_lshrrev_b32_e32 v73, 16, v73
	v_add_u32_e32 v74, 0x8000, v78
	v_and_or_b32 v73, v74, s90, v73
	v_pk_mul_f32 v[74:75], v[78:79], v[78:79]
	v_add_u32_e32 v88, 0x8000, v79
	v_pk_fma_f32 v[86:87], v[84:85], v[84:85], v[74:75]
	v_add_u32_e32 v74, 0x8000, v81
	v_lshrrev_b32_e32 v74, 16, v74
	v_add_u32_e32 v75, 0x8000, v77
	v_and_or_b32 v74, v75, s90, v74
	v_add_u32_e32 v75, 0x8000, v85
	v_lshrrev_b32_e32 v75, 16, v75
	v_add_u32_e32 v72, 0x8000, v76
	v_and_or_b32 v75, v88, s90, v75
	v_lshl_add_u64 v[88:89], v[206:207], 1, s[30:31]
	v_and_or_b32 v72, v72, s90, v90
	v_lshl_add_u64 v[88:89], v[196:197], 1, v[88:89]
	global_store_dwordx4 v[88:89], v[72:75], off nt
	v_lshlrev_b32_e32 v90, 1, v129
	v_lshlrev_b32_e32 v91, 1, v128
	v_lshrrev_b32_sdwa v72, v229, v129 dst_sel:DWORD dst_unused:UNUSED_PAD src0_sel:DWORD src1_sel:BYTE_0
	v_lshrrev_b32_sdwa v73, v229, v128 dst_sel:DWORD dst_unused:UNUSED_PAD src0_sel:DWORD src1_sel:BYTE_0
	v_sub_u32_sdwa v74, v130, v73 dst_sel:WORD_1 dst_unused:UNUSED_PAD src0_sel:DWORD src1_sel:DWORD
	v_sub_u32_sdwa v72, v132, v72 dst_sel:WORD_1 dst_unused:UNUSED_PAD src0_sel:DWORD src1_sel:DWORD
	v_lshlrev_b32_sdwa v73, v230, v129 dst_sel:DWORD dst_unused:UNUSED_PAD src0_sel:DWORD src1_sel:BYTE_0
	v_lshlrev_b32_sdwa v75, v230, v128 dst_sel:DWORD dst_unused:UNUSED_PAD src0_sel:DWORD src1_sel:BYTE_0
	v_or_b32_e32 v73, v72, v73
	v_or_b32_e32 v72, v74, v75
	v_mov_b32_e32 v74, v68
	v_mov_b32_e32 v75, v64
	v_pk_fma_f32 v[72:73], v[74:75], 0.5, v[72:73] op_sel_hi:[1,0,1]
	v_and_b32_e32 v74, 0x10000, v91
	v_add_u32_e32 v64, 0x8000, v72
	v_lshrrev_b32_e32 v68, 16, v64
	v_and_b32_e32 v64, 0x10000, v90
	v_sub_u32_e32 v64, v132, v64
	v_sub_u32_e32 v74, v130, v74
	v_and_b32_e32 v92, 0xff00, v129
	v_and_b32_e32 v93, 0xff00, v128
	v_and_b32_e32 v64, 0xffff0000, v64
	v_and_b32_e32 v74, 0xffff0000, v74
	v_or_b32_e32 v75, v64, v92
	v_or_b32_e32 v74, v74, v93
	v_mov_b32_e32 v64, v69
	v_pk_fma_f32 v[64:65], v[64:65], 0.5, v[74:75] op_sel_hi:[1,0,1]
	v_and_b32_sdwa v90, v128, s93 dst_sel:DWORD dst_unused:UNUSED_PAD src0_sel:WORD_1 src1_sel:DWORD
	v_add_u32_e32 v69, 0x8000, v64
	v_and_or_b32 v68, v69, s90, v68
	v_and_b32_sdwa v69, v129, s93 dst_sel:DWORD dst_unused:UNUSED_PAD src0_sel:WORD_1 src1_sel:DWORD
	v_lshrrev_b32_e32 v91, 7, v90
	v_lshrrev_b32_e32 v92, 7, v69
	v_sub_u32_sdwa v93, v131, v91 dst_sel:WORD_1 dst_unused:UNUSED_PAD src0_sel:DWORD src1_sel:DWORD
	v_sub_u32_sdwa v91, v133, v92 dst_sel:WORD_1 dst_unused:UNUSED_PAD src0_sel:DWORD src1_sel:DWORD
	v_lshlrev_b32_e32 v69, 8, v69
	v_lshlrev_b32_e32 v90, 8, v90
	v_or_b32_e32 v91, v91, v69
	v_or_b32_e32 v90, v93, v90
	v_mov_b32_e32 v92, v70
	v_mov_b32_e32 v93, v66
	v_pk_fma_f32 v[90:91], v[92:93], 0.5, v[90:91] op_sel_hi:[1,0,1]
	v_lshlrev_b32_sdwa v94, v231, v128 dst_sel:DWORD dst_unused:UNUSED_PAD src0_sel:DWORD src1_sel:BYTE_3
	v_lshlrev_b32_sdwa v95, v231, v129 dst_sel:DWORD dst_unused:UNUSED_PAD src0_sel:DWORD src1_sel:BYTE_3
	v_add_u32_e32 v66, 0x8000, v90
	v_lshrrev_b32_e32 v69, 16, v66
	v_and_b32_e32 v66, 0x10000, v95
	v_and_b32_e32 v70, 0x10000, v94
	v_sub_u32_e32 v66, v133, v66
	v_sub_u32_e32 v70, v131, v70
	v_pk_mul_f32 v[82:83], v[76:77], v[76:77]
	v_pk_mul_f32 v[74:75], v[64:65], v[64:65]
	v_and_b32_e32 v66, 0xffff0000, v66
	v_and_b32_e32 v70, 0xffff0000, v70
	v_lshlrev_b32_sdwa v92, v230, v129 dst_sel:DWORD dst_unused:UNUSED_PAD src0_sel:DWORD src1_sel:BYTE_3
	v_lshlrev_b32_sdwa v94, v230, v128 dst_sel:DWORD dst_unused:UNUSED_PAD src0_sel:DWORD src1_sel:BYTE_3
	v_pk_fma_f32 v[82:83], v[80:81], v[80:81], v[82:83]
	v_pk_fma_f32 v[74:75], v[72:73], v[72:73], v[74:75]
	v_or_b32_e32 v93, v66, v92
	v_or_b32_e32 v92, v70, v94
	v_mov_b32_e32 v66, v71
	v_lshrrev_b32_e32 v72, 8, v72
	v_pk_fma_f32 v[66:67], v[66:67], 0.5, v[92:93] op_sel_hi:[1,0,1]
	v_perm_b32 v64, v64, v72, s94
	v_add_f32_e32 v72, v82, v86
	v_add_u32_e32 v70, 0x8000, v66
	v_add_f32_e32 v72, v83, v72
	v_and_or_b32 v69, v70, s90, v69
	v_pk_mul_f32 v[70:71], v[66:67], v[66:67]
	v_add_f32_e32 v72, v87, v72
	v_pk_fma_f32 v[92:93], v[90:91], v[90:91], v[70:71]
	v_add_f32_e32 v72, v74, v72
	v_add_f32_e32 v72, v92, v72
	v_lshrrev_b32_e32 v80, 8, v80
	v_add_f32_e32 v72, v75, v72
	v_lshrrev_b32_e32 v81, 8, v81
	v_perm_b32 v76, v76, v80, s94
	v_add_f32_e32 v80, v93, v72
	v_perm_b32 v77, v77, v81, s94
	ds_bpermute_b32 v81, v238, v80
	v_add_u32_e32 v70, 0x8000, v73
	v_lshrrev_b32_e32 v70, 16, v70
	v_add_u32_e32 v71, 0x8000, v65
	v_lshrrev_b32_e32 v90, 8, v90
	v_and_or_b32 v70, v71, s90, v70
	v_add_u32_e32 v71, 0x8000, v91
	v_lshrrev_b32_e32 v91, 8, v91
	v_perm_b32 v66, v66, v90, s94
	v_lshrrev_b32_e32 v73, 8, v73
	v_add_u32_e32 v94, 0x8000, v67
	v_perm_b32 v67, v67, v91, s94
	v_perm_b32 v65, v65, v73, s94
	v_lshl_or_b32 v74, v66, 16, v64
	s_waitcnt lgkmcnt(0)
	v_add_f32_e32 v64, v80, v81
	v_lshl_or_b32 v75, v67, 16, v65
	ds_bpermute_b32 v65, v237, v64
	v_lshrrev_b32_e32 v85, 8, v85
	v_lshrrev_b32_e32 v84, 8, v84
	v_lshrrev_b32_e32 v71, 16, v71
	v_perm_b32 v78, v78, v84, s94
	v_perm_b32 v79, v79, v85, s94
	v_lshl_add_u64 v[66:67], s[34:35], 0, v[206:207]
	v_and_or_b32 v71, v94, s90, v71
	v_lshl_or_b32 v73, v79, 16, v77
	v_lshl_or_b32 v72, v78, 16, v76
	v_lshl_add_u64 v[66:67], v[66:67], 0, v[194:195]
	global_store_dwordx4 v[88:89], v[68:71], off offset:256 nt
	global_store_dwordx4 v[66:67], v[72:75], off nt
	s_and_saveexec_b64 s[50:51], s[40:41]
	s_cbranch_execz .LBB0_412
	s_waitcnt lgkmcnt(0)
	v_add_f32_e32 v64, v64, v65
	v_fma_f32 v64, v64, s80, 0.5
	v_trunc_f32_e32 v64, v64
	v_mul_f32_e32 v65, 0x2f800000, v64
	v_floor_f32_e32 v65, v65
	v_fmac_f32_e32 v64, 0xcf800000, v65
	v_cvt_u32_f32_e32 v64, v64
	v_cvt_u32_f32_e32 v65, v65
	v_lshl_add_u64 v[66:67], v[204:205], 3, s[48:49]
	global_atomic_add_x2 v[66:67], v[64:65], off
; #define PG8_GAS __attribute__((address_space(1)))
; __device__ __forceinline__ float e_x24(unsigned h16, unsigned l8) { return __uint_as_float(((h16 - (l8 >> 7)) << 16) | (l8 << 8)); }
;     __device__ __forceinline__ void operator()(const f32x4 (&acc)[2][2][4][2], const Unit& u, int wr, int wc, int fr, int fq) const {
;     ...
;             u32x4 L4[4], H4[4][2];
; #pragma unroll
;             for (int m = 0; m < 4; ++m) {
;                 const int row = row0 + ai * HALF + m * 16; const size_t off = (size_t)row * 2048 + col0, loff = (size_t)row * 2048 + lcol;
;                 L4[m] = *(const PG8_GAS u32x4*)(lin + loff); H4[m][0] = *(const PG8_GAS u32x4*)(hin + off); H4[m][1] = *(const PG8_GAS u32x4*)(hin + off + HALF);
;             }
; #pragma unroll
;             for (int m = 0; m < 4; ++m) {
;                 const int row = row0 + ai * HALF + m * 16; const size_t off = (size_t)row * 2048 + col0, loff = (size_t)row * 2048 + lcol; float ss = 0.f;
;                 const u32x4 l4 = L4[m];
;                 u32x4 lo4;
; #pragma unroll
;                 for (int bj = 0; bj < 2; ++bj) {
;                     const u32x4 h4 = H4[m][bj];
;                     u32x4 ho;
; #pragma unroll
;                     for (int j = 0; j < 4; ++j) {
;                         const unsigned lw = l4[2 * bj + (j >> 1)], lb0 = (lw >> (16 * (j & 1))) & 0xffu, lb1 = (lw >> (16 * (j & 1) + 8)) & 0xffu;
;                         const float x0 = e_x24(h4[j] & 0xffffu, lb0) + acc[ai][bj][m][j >> 1][2 * (j & 1)] * scale, x1 = e_x24(h4[j] >> 16, lb1) + acc[ai][bj][m][j >> 1][2 * (j & 1) + 1] * scale;
;                         const unsigned b0 = __float_as_uint(x0), b1 = __float_as_uint(x1);
;                         ho[j] = ((b0 + 0x8000u) >> 16) | ((b1 + 0x8000u) & 0xffff0000u);
;                         const unsigned nb = ((b0 >> 8) & 0xffu) | (b1 & 0xff00u);
;                         if ((j & 1) == 0) lo4[2 * bj + (j >> 1)] = nb; else lo4[2 * bj + (j >> 1)] |= nb << 16;
;                         ss += x0 * x0 + x1 * x1;
;                     }
;                     *(PG8_GAS u32x4*)(hout + off + bj * HALF) = ho;
.LBB0_412:
	s_or_b64 exec, exec, s[50:51]
	v_add_u32_e32 v130, 0x80, v198
	v_ashrrev_i32_e32 v131, 31, v130
	v_lshlrev_b64 v[132:133], 11, v[130:131]
	s_waitcnt lgkmcnt(0)
	v_lshl_add_u64 v[64:65], v[202:203], 0, v[132:133]
	global_load_dwordx4 v[106:109], v[64:65], off
	v_lshlrev_b64 v[134:135], 12, v[130:131]
	v_lshl_add_u64 v[64:65], v[200:201], 0, v[134:135]
	global_load_dwordx4 v[114:117], v[64:65], off
	global_load_dwordx4 v[110:113], v[64:65], off offset:256
	v_add_u32_e32 v126, 0x90, v198
	v_ashrrev_i32_e32 v127, 31, v126
	v_lshlrev_b64 v[128:129], 11, v[126:127]
	v_lshl_add_u64 v[64:65], v[202:203], 0, v[128:129]
	v_add_u32_e32 v122, 0xa0, v198
	global_load_dwordx4 v[88:91], v[64:65], off
	v_lshlrev_b64 v[64:65], 12, v[126:127]
	v_ashrrev_i32_e32 v123, 31, v122
	v_lshl_add_u64 v[64:65], v[200:201], 0, v[64:65]
	v_lshlrev_b64 v[124:125], 11, v[122:123]
	global_load_dwordx4 v[102:105], v[64:65], off
	global_load_dwordx4 v[92:95], v[64:65], off offset:256
	v_lshl_add_u64 v[64:65], v[202:203], 0, v[124:125]
	v_add_u32_e32 v118, 0xb0, v198
	global_load_dwordx4 v[76:79], v[64:65], off
	v_lshlrev_b64 v[64:65], 12, v[122:123]
	v_ashrrev_i32_e32 v119, 31, v118
	v_lshl_add_u64 v[64:65], v[200:201], 0, v[64:65]
	v_lshlrev_b64 v[120:121], 11, v[118:119]
	v_lshlrev_b64 v[68:69], 12, v[118:119]
	global_load_dwordx4 v[84:87], v[64:65], off
	global_load_dwordx4 v[80:83], v[64:65], off offset:256
	v_lshl_add_u64 v[64:65], v[202:203], 0, v[120:121]
	v_lshl_add_u64 v[68:69], v[200:201], 0, v[68:69]
	global_load_dwordx4 v[64:67], v[64:65], off
	s_nop 0
	global_load_dwordx4 v[72:75], v[68:69], off
	s_nop 0
	global_load_dwordx4 v[68:71], v[68:69], off offset:256
	v_mov_b32_e32 v143, v58
	v_mov_b32_e32 v142, v62
	s_waitcnt vmcnt(11)
	v_lshrrev_b32_sdwa v136, v229, v107 dst_sel:DWORD dst_unused:UNUSED_PAD src0_sel:DWORD src1_sel:BYTE_0
	v_lshrrev_b32_sdwa v137, v229, v106 dst_sel:DWORD dst_unused:UNUSED_PAD src0_sel:DWORD src1_sel:BYTE_0
	s_waitcnt vmcnt(10)
	v_sub_u32_sdwa v138, v114, v137 dst_sel:WORD_1 dst_unused:UNUSED_PAD src0_sel:DWORD src1_sel:DWORD
	v_sub_u32_sdwa v136, v116, v136 dst_sel:WORD_1 dst_unused:UNUSED_PAD src0_sel:DWORD src1_sel:DWORD
	v_lshlrev_b32_sdwa v137, v230, v107 dst_sel:DWORD dst_unused:UNUSED_PAD src0_sel:DWORD src1_sel:BYTE_0
	v_lshlrev_b32_sdwa v139, v230, v106 dst_sel:DWORD dst_unused:UNUSED_PAD src0_sel:DWORD src1_sel:BYTE_0
	v_or_b32_e32 v137, v136, v137
	v_or_b32_e32 v136, v138, v139
	v_mov_b32_e32 v138, v60
	v_mov_b32_e32 v139, v56
	v_pk_fma_f32 v[136:137], v[138:139], 0.5, v[136:137] op_sel_hi:[1,0,1]
	v_lshlrev_b32_e32 v138, 1, v106
	v_add_u32_e32 v56, 0x8000, v136
	v_lshrrev_b32_e32 v60, 16, v56
	v_lshlrev_b32_e32 v56, 1, v107
	v_and_b32_e32 v56, 0x10000, v56
	v_and_b32_e32 v138, 0x10000, v138
	v_sub_u32_e32 v56, v116, v56
	v_sub_u32_e32 v114, v114, v138
	v_and_b32_e32 v56, 0xffff0000, v56
	v_and_b32_e32 v114, 0xffff0000, v114
	v_and_b32_e32 v116, 0xff00, v107
	v_and_b32_e32 v138, 0xff00, v106
	v_or_b32_e32 v139, v56, v116
	v_or_b32_e32 v138, v114, v138
	v_mov_b32_e32 v56, v61
	v_pk_fma_f32 v[138:139], v[56:57], 0.5, v[138:139] op_sel_hi:[1,0,1]
	v_and_b32_sdwa v57, v107, s93 dst_sel:DWORD dst_unused:UNUSED_PAD src0_sel:WORD_1 src1_sel:DWORD
	v_and_b32_sdwa v114, v106, s93 dst_sel:DWORD dst_unused:UNUSED_PAD src0_sel:WORD_1 src1_sel:DWORD
	v_lshlrev_b32_sdwa v144, v231, v106 dst_sel:DWORD dst_unused:UNUSED_PAD src0_sel:DWORD src1_sel:BYTE_3
	v_lshlrev_b32_sdwa v58, v231, v107 dst_sel:DWORD dst_unused:UNUSED_PAD src0_sel:DWORD src1_sel:BYTE_3
	v_lshrrev_b32_e32 v116, 7, v114
	v_lshrrev_b32_e32 v140, 7, v57
	v_and_b32_e32 v58, 0x10000, v58
	v_and_b32_e32 v62, 0x10000, v144
	v_sub_u32_sdwa v116, v115, v116 dst_sel:WORD_1 dst_unused:UNUSED_PAD src0_sel:DWORD src1_sel:DWORD
	v_sub_u32_sdwa v140, v117, v140 dst_sel:WORD_1 dst_unused:UNUSED_PAD src0_sel:DWORD src1_sel:DWORD
	v_lshlrev_b32_e32 v57, 8, v57
	v_lshlrev_b32_e32 v114, 8, v114
	v_sub_u32_e32 v58, v117, v58
	v_sub_u32_e32 v62, v115, v62
	v_or_b32_e32 v141, v140, v57
	v_or_b32_e32 v140, v116, v114
	v_and_b32_e32 v58, 0xffff0000, v58
	v_and_b32_e32 v62, 0xffff0000, v62
	v_lshlrev_b32_sdwa v107, v230, v107 dst_sel:DWORD dst_unused:UNUSED_PAD src0_sel:DWORD src1_sel:BYTE_3
	v_lshlrev_b32_sdwa v106, v230, v106 dst_sel:DWORD dst_unused:UNUSED_PAD src0_sel:DWORD src1_sel:BYTE_3
	v_pk_fma_f32 v[140:141], v[142:143], 0.5, v[140:141] op_sel_hi:[1,0,1]
	v_or_b32_e32 v107, v58, v107
	v_or_b32_e32 v106, v62, v106
	v_mov_b32_e32 v58, v63
	v_add_u32_e32 v57, 0x8000, v140
	v_pk_fma_f32 v[62:63], v[58:59], 0.5, v[106:107] op_sel_hi:[1,0,1]
	v_lshrrev_b32_e32 v57, 16, v57
	v_add_u32_e32 v58, 0x8000, v62
	v_and_or_b32 v57, v58, s90, v57
	v_pk_mul_f32 v[58:59], v[62:63], v[62:63]
	v_add_u32_e32 v114, 0x8000, v63
	v_pk_fma_f32 v[106:107], v[140:141], v[140:141], v[58:59]
	v_add_u32_e32 v58, 0x8000, v137
	v_lshrrev_b32_e32 v58, 16, v58
	v_add_u32_e32 v59, 0x8000, v139
	v_and_or_b32 v58, v59, s90, v58
	v_add_u32_e32 v59, 0x8000, v141
	v_lshrrev_b32_e32 v59, 16, v59
	v_add_u32_e32 v56, 0x8000, v138
	v_and_or_b32 v59, v114, s90, v59
	v_lshl_add_u64 v[114:115], s[30:31], 0, v[134:135]
	v_and_or_b32 v56, v56, s90, v60
	v_lshl_add_u64 v[114:115], v[196:197], 1, v[114:115]
	global_store_dwordx4 v[114:115], v[56:59], off nt
	v_lshlrev_b32_sdwa v142, v231, v108 dst_sel:DWORD dst_unused:UNUSED_PAD src0_sel:DWORD src1_sel:BYTE_3
	v_mov_b32_e32 v135, v50
	v_lshrrev_b32_sdwa v56, v229, v109 dst_sel:DWORD dst_unused:UNUSED_PAD src0_sel:DWORD src1_sel:BYTE_0
	v_lshrrev_b32_sdwa v57, v229, v108 dst_sel:DWORD dst_unused:UNUSED_PAD src0_sel:DWORD src1_sel:BYTE_0
	s_waitcnt vmcnt(10)
; #define PG8_GAS __attribute__((address_space(1)))
; __device__ __forceinline__ float e_x24(unsigned h16, unsigned l8) { return __uint_as_float(((h16 - (l8 >> 7)) << 16) | (l8 << 8)); }
;     __device__ __forceinline__ void operator()(const f32x4 (&acc)[2][2][4][2], const Unit& u, int wr, int wc, int fr, int fq) const {
;     ...
;             for (int m = 0; m < 4; ++m) {
;                 const int row = row0 + ai * HALF + m * 16; const size_t off = (size_t)row * 2048 + col0, loff = (size_t)row * 2048 + lcol; float ss = 0.f;
;                 const u32x4 l4 = L4[m];
;                 u32x4 lo4;
; #pragma unroll
;                 for (int bj = 0; bj < 2; ++bj) {
;                     const u32x4 h4 = H4[m][bj];
;                     u32x4 ho;
; #pragma unroll
;                     for (int j = 0; j < 4; ++j) {
;                         const unsigned lw = l4[2 * bj + (j >> 1)], lb0 = (lw >> (16 * (j & 1))) & 0xffu, lb1 = (lw >> (16 * (j & 1) + 8)) & 0xffu;
;                         const float x0 = e_x24(h4[j] & 0xffffu, lb0) + acc[ai][bj][m][j >> 1][2 * (j & 1)] * scale, x1 = e_x24(h4[j] >> 16, lb1) + acc[ai][bj][m][j >> 1][2 * (j & 1) + 1] * scale;
;                         const unsigned b0 = __float_as_uint(x0), b1 = __float_as_uint(x1);
;                         ho[j] = ((b0 + 0x8000u) >> 16) | ((b1 + 0x8000u) & 0xffff0000u);
;                         const unsigned nb = ((b0 >> 8) & 0xffu) | (b1 & 0xff00u);
;                         if ((j & 1) == 0) lo4[2 * bj + (j >> 1)] = nb; else lo4[2 * bj + (j >> 1)] |= nb << 16;
;                         ss += x0 * x0 + x1 * x1;
;                     }
;                     *(PG8_GAS u32x4*)(hout + off + bj * HALF) = ho;
;                 }
;                 *(PG8_GAS u32x4*)(lout + loff) = lo4;
;                 ss += __shfl_xor(ss, 16); ss += __shfl_xor(ss, 32);
;                 if (fq == 0) __hip_atomic_fetch_add((PG8_GAS unsigned long long*)(rowsq_out + row), (unsigned long long)(ss * 16777216.0f + 0.5f), __ATOMIC_RELAXED, __HIP_MEMORY_SCOPE_AGENT);
	v_sub_u32_sdwa v58, v110, v57 dst_sel:WORD_1 dst_unused:UNUSED_PAD src0_sel:DWORD src1_sel:DWORD
	v_sub_u32_sdwa v56, v112, v56 dst_sel:WORD_1 dst_unused:UNUSED_PAD src0_sel:DWORD src1_sel:DWORD
	v_lshlrev_b32_sdwa v57, v230, v109 dst_sel:DWORD dst_unused:UNUSED_PAD src0_sel:DWORD src1_sel:BYTE_0
	v_lshlrev_b32_sdwa v59, v230, v108 dst_sel:DWORD dst_unused:UNUSED_PAD src0_sel:DWORD src1_sel:BYTE_0
	v_or_b32_e32 v57, v56, v57
	v_or_b32_e32 v56, v58, v59
	v_mov_b32_e32 v58, v52
	v_mov_b32_e32 v59, v48
	v_pk_fma_f32 v[56:57], v[58:59], 0.5, v[56:57] op_sel_hi:[1,0,1]
	v_lshlrev_b32_e32 v52, 1, v108
	v_add_u32_e32 v48, 0x8000, v56
	v_lshrrev_b32_e32 v116, 16, v48
	v_lshlrev_b32_e32 v48, 1, v109
	v_and_b32_e32 v48, 0x10000, v48
	v_and_b32_e32 v52, 0x10000, v52
	v_sub_u32_e32 v48, v112, v48
	v_sub_u32_e32 v52, v110, v52
	v_and_b32_e32 v48, 0xffff0000, v48
	v_and_b32_e32 v52, 0xffff0000, v52
	v_and_b32_e32 v58, 0xff00, v109
	v_and_b32_e32 v110, 0xff00, v108
	v_or_b32_e32 v59, v48, v58
	v_or_b32_e32 v58, v52, v110
	v_mov_b32_e32 v48, v53
	v_pk_fma_f32 v[52:53], v[48:49], 0.5, v[58:59] op_sel_hi:[1,0,1]
	v_and_b32_sdwa v49, v109, s93 dst_sel:DWORD dst_unused:UNUSED_PAD src0_sel:WORD_1 src1_sel:DWORD
	v_add_u32_e32 v48, 0x8000, v52
	v_and_b32_sdwa v110, v108, s93 dst_sel:DWORD dst_unused:UNUSED_PAD src0_sel:WORD_1 src1_sel:DWORD
	v_lshlrev_b32_sdwa v50, v231, v109 dst_sel:DWORD dst_unused:UNUSED_PAD src0_sel:DWORD src1_sel:BYTE_3
	v_and_or_b32 v48, v48, s90, v116
	v_lshrrev_b32_e32 v112, 7, v110
	v_lshrrev_b32_e32 v116, 7, v49
	v_mov_b32_e32 v134, v54
	v_and_b32_e32 v50, 0x10000, v50
	v_and_b32_e32 v54, 0x10000, v142
	v_sub_u32_sdwa v112, v111, v112 dst_sel:WORD_1 dst_unused:UNUSED_PAD src0_sel:DWORD src1_sel:DWORD
	v_sub_u32_sdwa v116, v113, v116 dst_sel:WORD_1 dst_unused:UNUSED_PAD src0_sel:DWORD src1_sel:DWORD
	v_lshlrev_b32_e32 v49, 8, v49
	v_lshlrev_b32_e32 v110, 8, v110
	v_sub_u32_e32 v50, v113, v50
	v_sub_u32_e32 v54, v111, v54
	v_or_b32_e32 v117, v116, v49
	v_or_b32_e32 v116, v112, v110
	v_and_b32_e32 v50, 0xffff0000, v50
	v_and_b32_e32 v54, 0xffff0000, v54
	v_lshlrev_b32_sdwa v109, v230, v109 dst_sel:DWORD dst_unused:UNUSED_PAD src0_sel:DWORD src1_sel:BYTE_3
	v_lshlrev_b32_sdwa v108, v230, v108 dst_sel:DWORD dst_unused:UNUSED_PAD src0_sel:DWORD src1_sel:BYTE_3
	v_pk_fma_f32 v[116:117], v[134:135], 0.5, v[116:117] op_sel_hi:[1,0,1]
	v_or_b32_e32 v109, v50, v109
	v_or_b32_e32 v108, v54, v108
	v_mov_b32_e32 v50, v55
	v_add_u32_e32 v49, 0x8000, v116
	v_pk_fma_f32 v[54:55], v[50:51], 0.5, v[108:109] op_sel_hi:[1,0,1]
	v_lshrrev_b32_e32 v49, 16, v49
	v_add_u32_e32 v50, 0x8000, v54
	v_pk_mul_f32 v[60:61], v[138:139], v[138:139]
	v_pk_mul_f32 v[58:59], v[52:53], v[52:53]
	v_and_or_b32 v49, v50, s90, v49
	v_pk_mul_f32 v[50:51], v[54:55], v[54:55]
	v_pk_fma_f32 v[60:61], v[136:137], v[136:137], v[60:61]
	v_pk_fma_f32 v[58:59], v[56:57], v[56:57], v[58:59]
	v_pk_fma_f32 v[108:109], v[116:117], v[116:117], v[50:51]
	v_add_u32_e32 v50, 0x8000, v57
	v_lshrrev_b32_e32 v56, 8, v56
	v_lshrrev_b32_e32 v50, 16, v50
	v_add_u32_e32 v51, 0x8000, v53
	v_perm_b32 v52, v52, v56, s94
	v_add_f32_e32 v56, v60, v106
	v_and_or_b32 v50, v51, s90, v50
	v_add_u32_e32 v51, 0x8000, v117
	v_add_f32_e32 v56, v61, v56
	v_lshrrev_b32_e32 v51, 16, v51
	v_add_u32_e32 v110, 0x8000, v55
	v_add_f32_e32 v56, v107, v56
	v_and_or_b32 v51, v110, s90, v51
	v_lshrrev_b32_e32 v110, 8, v117
	v_lshrrev_b32_e32 v111, 8, v116
	v_add_f32_e32 v56, v58, v56
	v_lshrrev_b32_e32 v112, 8, v141
	v_lshrrev_b32_e32 v113, 8, v140
	v_perm_b32 v54, v54, v111, s94
	v_perm_b32 v55, v55, v110, s94
	v_lshrrev_b32_e32 v57, 8, v57
	v_lshrrev_b32_e32 v110, 8, v137
	v_lshrrev_b32_e32 v111, 8, v136
	v_add_f32_e32 v56, v108, v56
	v_perm_b32 v62, v62, v113, s94
	v_perm_b32 v63, v63, v112, s94
	v_perm_b32 v111, v138, v111, s94
	v_perm_b32 v110, v139, v110, s94
	v_perm_b32 v53, v53, v57, s94
	v_add_f32_e32 v56, v59, v56
	global_store_dwordx4 v[114:115], v[48:51], off offset:256 nt
	v_lshl_or_b32 v55, v55, 16, v53
	v_lshl_or_b32 v54, v54, 16, v52
	v_lshl_add_u64 v[48:49], s[34:35], 0, v[132:133]
	v_lshl_or_b32 v53, v63, 16, v110
	v_lshl_or_b32 v52, v62, 16, v111
	v_add_f32_e32 v56, v109, v56
	v_lshl_add_u64 v[48:49], v[48:49], 0, v[194:195]
	global_store_dwordx4 v[48:49], v[52:55], off nt
	ds_bpermute_b32 v48, v238, v56
	s_waitcnt lgkmcnt(0)
	v_add_f32_e32 v48, v56, v48
	ds_bpermute_b32 v49, v237, v48
	s_and_saveexec_b64 s[50:51], s[40:41]
	s_cbranch_execz .LBB0_414
	s_waitcnt lgkmcnt(0)
	v_add_f32_e32 v48, v48, v49
	v_fma_f32 v48, v48, s80, 0.5
	v_trunc_f32_e32 v48, v48
	v_mul_f32_e32 v49, 0x2f800000, v48
	v_floor_f32_e32 v49, v49
	v_fmac_f32_e32 v48, 0xcf800000, v49
	v_cvt_u32_f32_e32 v48, v48
	v_cvt_u32_f32_e32 v49, v49
	v_lshl_add_u64 v[50:51], v[130:131], 3, s[48:49]
	global_atomic_add_x2 v[50:51], v[48:49], off
; #define PG8_GAS __attribute__((address_space(1)))
; __device__ __forceinline__ float e_x24(unsigned h16, unsigned l8) { return __uint_as_float(((h16 - (l8 >> 7)) << 16) | (l8 << 8)); }
;     __device__ __forceinline__ void operator()(const f32x4 (&acc)[2][2][4][2], const Unit& u, int wr, int wc, int fr, int fq) const {
;     ...
;             for (int m = 0; m < 4; ++m) {
;                 const int row = row0 + ai * HALF + m * 16; const size_t off = (size_t)row * 2048 + col0, loff = (size_t)row * 2048 + lcol; float ss = 0.f;
;                 const u32x4 l4 = L4[m];
;                 u32x4 lo4;
; #pragma unroll
;                 for (int bj = 0; bj < 2; ++bj) {
;                     const u32x4 h4 = H4[m][bj];
;                     u32x4 ho;
; #pragma unroll
;                     for (int j = 0; j < 4; ++j) {
;                         const unsigned lw = l4[2 * bj + (j >> 1)], lb0 = (lw >> (16 * (j & 1))) & 0xffu, lb1 = (lw >> (16 * (j & 1) + 8)) & 0xffu;
;                         const float x0 = e_x24(h4[j] & 0xffffu, lb0) + acc[ai][bj][m][j >> 1][2 * (j & 1)] * scale, x1 = e_x24(h4[j] >> 16, lb1) + acc[ai][bj][m][j >> 1][2 * (j & 1) + 1] * scale;
;                         const unsigned b0 = __float_as_uint(x0), b1 = __float_as_uint(x1);
;                         ho[j] = ((b0 + 0x8000u) >> 16) | ((b1 + 0x8000u) & 0xffff0000u);
;                         const unsigned nb = ((b0 >> 8) & 0xffu) | (b1 & 0xff00u);
;                         if ((j & 1) == 0) lo4[2 * bj + (j >> 1)] = nb; else lo4[2 * bj + (j >> 1)] |= nb << 16;
;                         ss += x0 * x0 + x1 * x1;
;                     }
;                     *(PG8_GAS u32x4*)(hout + off + bj * HALF) = ho;
.LBB0_414:
	s_or_b64 exec, exec, s[50:51]
	s_waitcnt vmcnt(11)
	v_lshrrev_b32_sdwa v48, v229, v89 dst_sel:DWORD dst_unused:UNUSED_PAD src0_sel:DWORD src1_sel:BYTE_0
	s_waitcnt lgkmcnt(0)
	v_lshrrev_b32_sdwa v49, v229, v88 dst_sel:DWORD dst_unused:UNUSED_PAD src0_sel:DWORD src1_sel:BYTE_0
	s_waitcnt vmcnt(10)
	v_sub_u32_sdwa v50, v102, v49 dst_sel:WORD_1 dst_unused:UNUSED_PAD src0_sel:DWORD src1_sel:DWORD
	v_sub_u32_sdwa v48, v104, v48 dst_sel:WORD_1 dst_unused:UNUSED_PAD src0_sel:DWORD src1_sel:DWORD
	v_lshlrev_b32_sdwa v49, v230, v89 dst_sel:DWORD dst_unused:UNUSED_PAD src0_sel:DWORD src1_sel:BYTE_0
	v_lshlrev_b32_sdwa v51, v230, v88 dst_sel:DWORD dst_unused:UNUSED_PAD src0_sel:DWORD src1_sel:BYTE_0
	v_or_b32_e32 v49, v48, v49
	v_or_b32_e32 v48, v50, v51
	v_mov_b32_e32 v50, v44
	v_mov_b32_e32 v51, v40
	v_pk_fma_f32 v[48:49], v[50:51], 0.5, v[48:49] op_sel_hi:[1,0,1]
	v_lshlrev_b32_e32 v52, 1, v89
	v_lshlrev_b32_e32 v53, 1, v88
	v_add_u32_e32 v40, 0x8000, v48
	v_lshrrev_b32_e32 v58, 16, v40
	v_and_b32_e32 v40, 0x10000, v52
	v_and_b32_e32 v44, 0x10000, v53
	v_sub_u32_e32 v40, v104, v40
	v_sub_u32_e32 v44, v102, v44
	v_and_b32_e32 v54, 0xff00, v89
	v_and_b32_e32 v55, 0xff00, v88
	v_and_b32_e32 v40, 0xffff0000, v40
	v_and_b32_e32 v44, 0xffff0000, v44
	v_or_b32_e32 v51, v40, v54
	v_or_b32_e32 v50, v44, v55
	v_mov_b32_e32 v40, v45
	v_and_b32_sdwa v52, v88, s93 dst_sel:DWORD dst_unused:UNUSED_PAD src0_sel:WORD_1 src1_sel:DWORD
	v_pk_fma_f32 v[44:45], v[40:41], 0.5, v[50:51] op_sel_hi:[1,0,1]
	v_and_b32_sdwa v41, v89, s93 dst_sel:DWORD dst_unused:UNUSED_PAD src0_sel:WORD_1 src1_sel:DWORD
	v_lshrrev_b32_e32 v53, 7, v52
	v_lshlrev_b32_sdwa v56, v231, v88 dst_sel:DWORD dst_unused:UNUSED_PAD src0_sel:DWORD src1_sel:BYTE_3
	v_lshlrev_b32_sdwa v57, v231, v89 dst_sel:DWORD dst_unused:UNUSED_PAD src0_sel:DWORD src1_sel:BYTE_3
	v_lshrrev_b32_e32 v54, 7, v41
	v_sub_u32_sdwa v55, v103, v53 dst_sel:WORD_1 dst_unused:UNUSED_PAD src0_sel:DWORD src1_sel:DWORD
	v_lshlrev_b32_e32 v52, 8, v52
	v_sub_u32_sdwa v53, v105, v54 dst_sel:WORD_1 dst_unused:UNUSED_PAD src0_sel:DWORD src1_sel:DWORD
	v_lshlrev_b32_e32 v41, 8, v41
	v_or_b32_e32 v52, v55, v52
	v_mov_b32_e32 v54, v46
	v_mov_b32_e32 v55, v42
	v_and_b32_e32 v42, 0x10000, v57
	v_and_b32_e32 v46, 0x10000, v56
	v_or_b32_e32 v53, v53, v41
	v_sub_u32_e32 v42, v105, v42
	v_sub_u32_e32 v46, v103, v46
	v_pk_fma_f32 v[52:53], v[54:55], 0.5, v[52:53] op_sel_hi:[1,0,1]
	v_and_b32_e32 v42, 0xffff0000, v42
	v_and_b32_e32 v46, 0xffff0000, v46
	v_lshlrev_b32_sdwa v54, v230, v89 dst_sel:DWORD dst_unused:UNUSED_PAD src0_sel:DWORD src1_sel:BYTE_3
	v_lshlrev_b32_sdwa v56, v230, v88 dst_sel:DWORD dst_unused:UNUSED_PAD src0_sel:DWORD src1_sel:BYTE_3
	v_or_b32_e32 v55, v42, v54
	v_or_b32_e32 v54, v46, v56
	v_mov_b32_e32 v42, v47
	v_add_u32_e32 v41, 0x8000, v52
	v_pk_fma_f32 v[46:47], v[42:43], 0.5, v[54:55] op_sel_hi:[1,0,1]
	v_lshrrev_b32_e32 v41, 16, v41
	v_add_u32_e32 v42, 0x8000, v46
	v_and_or_b32 v41, v42, s90, v41
	v_pk_mul_f32 v[42:43], v[46:47], v[46:47]
	v_add_u32_e32 v56, 0x8000, v47
	v_pk_fma_f32 v[54:55], v[52:53], v[52:53], v[42:43]
	v_add_u32_e32 v42, 0x8000, v49
	v_lshrrev_b32_e32 v42, 16, v42
	v_add_u32_e32 v43, 0x8000, v45
	v_and_or_b32 v42, v43, s90, v42
	v_add_u32_e32 v43, 0x8000, v53
	v_lshrrev_b32_e32 v43, 16, v43
	v_add_u32_e32 v40, 0x8000, v44
	v_and_or_b32 v43, v56, s90, v43
	v_lshl_add_u64 v[56:57], v[128:129], 1, s[30:31]
	v_and_or_b32 v40, v40, s90, v58
	v_lshl_add_u64 v[56:57], v[196:197], 1, v[56:57]
	global_store_dwordx4 v[56:57], v[40:43], off nt
	v_lshlrev_b32_e32 v58, 1, v91
	v_lshlrev_b32_e32 v59, 1, v90
	v_lshrrev_b32_sdwa v40, v229, v91 dst_sel:DWORD dst_unused:UNUSED_PAD src0_sel:DWORD src1_sel:BYTE_0
	v_lshrrev_b32_sdwa v41, v229, v90 dst_sel:DWORD dst_unused:UNUSED_PAD src0_sel:DWORD src1_sel:BYTE_0
	s_waitcnt vmcnt(10)
	v_sub_u32_sdwa v42, v92, v41 dst_sel:WORD_1 dst_unused:UNUSED_PAD src0_sel:DWORD src1_sel:DWORD
	v_sub_u32_sdwa v40, v94, v40 dst_sel:WORD_1 dst_unused:UNUSED_PAD src0_sel:DWORD src1_sel:DWORD
	v_lshlrev_b32_sdwa v41, v230, v91 dst_sel:DWORD dst_unused:UNUSED_PAD src0_sel:DWORD src1_sel:BYTE_0
	v_lshlrev_b32_sdwa v43, v230, v90 dst_sel:DWORD dst_unused:UNUSED_PAD src0_sel:DWORD src1_sel:BYTE_0
	v_or_b32_e32 v41, v40, v41
	v_or_b32_e32 v40, v42, v43
	v_mov_b32_e32 v42, v36
	v_mov_b32_e32 v43, v32
	v_pk_fma_f32 v[40:41], v[42:43], 0.5, v[40:41] op_sel_hi:[1,0,1]
	v_and_b32_e32 v42, 0x10000, v59
	v_add_u32_e32 v32, 0x8000, v40
	v_lshrrev_b32_e32 v36, 16, v32
	v_and_b32_e32 v32, 0x10000, v58
	v_sub_u32_e32 v32, v94, v32
	v_sub_u32_e32 v42, v92, v42
	v_and_b32_e32 v60, 0xff00, v91
	v_and_b32_e32 v61, 0xff00, v90
	v_and_b32_e32 v32, 0xffff0000, v32
	v_and_b32_e32 v42, 0xffff0000, v42
	v_or_b32_e32 v43, v32, v60
	v_or_b32_e32 v42, v42, v61
	v_mov_b32_e32 v32, v37
	v_pk_fma_f32 v[32:33], v[32:33], 0.5, v[42:43] op_sel_hi:[1,0,1]
	v_and_b32_sdwa v58, v90, s93 dst_sel:DWORD dst_unused:UNUSED_PAD src0_sel:WORD_1 src1_sel:DWORD
	v_add_u32_e32 v37, 0x8000, v32
	v_and_or_b32 v36, v37, s90, v36
	v_and_b32_sdwa v37, v91, s93 dst_sel:DWORD dst_unused:UNUSED_PAD src0_sel:WORD_1 src1_sel:DWORD
	v_lshrrev_b32_e32 v59, 7, v58
	v_lshrrev_b32_e32 v60, 7, v37
	v_sub_u32_sdwa v61, v93, v59 dst_sel:WORD_1 dst_unused:UNUSED_PAD src0_sel:DWORD src1_sel:DWORD
	v_sub_u32_sdwa v59, v95, v60 dst_sel:WORD_1 dst_unused:UNUSED_PAD src0_sel:DWORD src1_sel:DWORD
	v_lshlrev_b32_e32 v37, 8, v37
	v_lshlrev_b32_e32 v58, 8, v58
	v_or_b32_e32 v59, v59, v37
	v_or_b32_e32 v58, v61, v58
	v_mov_b32_e32 v60, v38
	v_mov_b32_e32 v61, v34
	v_pk_fma_f32 v[58:59], v[60:61], 0.5, v[58:59] op_sel_hi:[1,0,1]
; #define PG8_GAS __attribute__((address_space(1)))
; __device__ __forceinline__ float e_x24(unsigned h16, unsigned l8) { return __uint_as_float(((h16 - (l8 >> 7)) << 16) | (l8 << 8)); }
;     __device__ __forceinline__ void operator()(const f32x4 (&acc)[2][2][4][2], const Unit& u, int wr, int wc, int fr, int fq) const {
;     ...
;             for (int m = 0; m < 4; ++m) {
;                 const int row = row0 + ai * HALF + m * 16; const size_t off = (size_t)row * 2048 + col0, loff = (size_t)row * 2048 + lcol; float ss = 0.f;
;                 const u32x4 l4 = L4[m];
;                 u32x4 lo4;
; #pragma unroll
;                 for (int bj = 0; bj < 2; ++bj) {
;                     const u32x4 h4 = H4[m][bj];
;                     u32x4 ho;
; #pragma unroll
;                     for (int j = 0; j < 4; ++j) {
;                         const unsigned lw = l4[2 * bj + (j >> 1)], lb0 = (lw >> (16 * (j & 1))) & 0xffu, lb1 = (lw >> (16 * (j & 1) + 8)) & 0xffu;
;                         const float x0 = e_x24(h4[j] & 0xffffu, lb0) + acc[ai][bj][m][j >> 1][2 * (j & 1)] * scale, x1 = e_x24(h4[j] >> 16, lb1) + acc[ai][bj][m][j >> 1][2 * (j & 1) + 1] * scale;
;                         const unsigned b0 = __float_as_uint(x0), b1 = __float_as_uint(x1);
;                         ho[j] = ((b0 + 0x8000u) >> 16) | ((b1 + 0x8000u) & 0xffff0000u);
;                         const unsigned nb = ((b0 >> 8) & 0xffu) | (b1 & 0xff00u);
;                         if ((j & 1) == 0) lo4[2 * bj + (j >> 1)] = nb; else lo4[2 * bj + (j >> 1)] |= nb << 16;
;                         ss += x0 * x0 + x1 * x1;
;                     }
;                     *(PG8_GAS u32x4*)(hout + off + bj * HALF) = ho;
;                 }
;                 *(PG8_GAS u32x4*)(lout + loff) = lo4;
;                 ss += __shfl_xor(ss, 16); ss += __shfl_xor(ss, 32);
;                 if (fq == 0) __hip_atomic_fetch_add((PG8_GAS unsigned long long*)(rowsq_out + row), (unsigned long long)(ss * 16777216.0f + 0.5f), __ATOMIC_RELAXED, __HIP_MEMORY_SCOPE_AGENT);
	v_lshlrev_b32_sdwa v62, v231, v90 dst_sel:DWORD dst_unused:UNUSED_PAD src0_sel:DWORD src1_sel:BYTE_3
	v_lshlrev_b32_sdwa v63, v231, v91 dst_sel:DWORD dst_unused:UNUSED_PAD src0_sel:DWORD src1_sel:BYTE_3
	v_add_u32_e32 v34, 0x8000, v58
	v_lshrrev_b32_e32 v37, 16, v34
	v_and_b32_e32 v34, 0x10000, v63
	v_and_b32_e32 v38, 0x10000, v62
	v_sub_u32_e32 v34, v95, v34
	v_sub_u32_e32 v38, v93, v38
	v_pk_mul_f32 v[50:51], v[44:45], v[44:45]
	v_pk_mul_f32 v[42:43], v[32:33], v[32:33]
	v_and_b32_e32 v34, 0xffff0000, v34
	v_and_b32_e32 v38, 0xffff0000, v38
	v_lshlrev_b32_sdwa v60, v230, v91 dst_sel:DWORD dst_unused:UNUSED_PAD src0_sel:DWORD src1_sel:BYTE_3
	v_lshlrev_b32_sdwa v62, v230, v90 dst_sel:DWORD dst_unused:UNUSED_PAD src0_sel:DWORD src1_sel:BYTE_3
	v_pk_fma_f32 v[50:51], v[48:49], v[48:49], v[50:51]
	v_pk_fma_f32 v[42:43], v[40:41], v[40:41], v[42:43]
	v_or_b32_e32 v61, v34, v60
	v_or_b32_e32 v60, v38, v62
	v_mov_b32_e32 v34, v39
	v_lshrrev_b32_e32 v40, 8, v40
	v_pk_fma_f32 v[34:35], v[34:35], 0.5, v[60:61] op_sel_hi:[1,0,1]
	v_perm_b32 v32, v32, v40, s94
	v_add_f32_e32 v40, v50, v54
	v_add_u32_e32 v38, 0x8000, v34
	v_add_f32_e32 v40, v51, v40
	v_and_or_b32 v37, v38, s90, v37
	v_pk_mul_f32 v[38:39], v[34:35], v[34:35]
	v_add_f32_e32 v40, v55, v40
	v_pk_fma_f32 v[60:61], v[58:59], v[58:59], v[38:39]
	v_add_f32_e32 v40, v42, v40
	v_add_f32_e32 v40, v60, v40
	v_lshrrev_b32_e32 v48, 8, v48
	v_add_f32_e32 v40, v43, v40
	v_lshrrev_b32_e32 v49, 8, v49
	v_perm_b32 v44, v44, v48, s94
	v_add_f32_e32 v48, v61, v40
	v_perm_b32 v45, v45, v49, s94
	ds_bpermute_b32 v49, v238, v48
	v_add_u32_e32 v38, 0x8000, v41
	v_lshrrev_b32_e32 v38, 16, v38
	v_add_u32_e32 v39, 0x8000, v33
	v_lshrrev_b32_e32 v58, 8, v58
	v_and_or_b32 v38, v39, s90, v38
	v_add_u32_e32 v39, 0x8000, v59
	v_lshrrev_b32_e32 v59, 8, v59
	v_perm_b32 v34, v34, v58, s94
	v_lshrrev_b32_e32 v41, 8, v41
	v_add_u32_e32 v62, 0x8000, v35
	v_perm_b32 v35, v35, v59, s94
	v_perm_b32 v33, v33, v41, s94
	v_lshl_or_b32 v42, v34, 16, v32
	s_waitcnt lgkmcnt(0)
	v_add_f32_e32 v32, v48, v49
	v_lshl_or_b32 v43, v35, 16, v33
	ds_bpermute_b32 v33, v237, v32
	v_lshrrev_b32_e32 v53, 8, v53
	v_lshrrev_b32_e32 v52, 8, v52
	v_lshrrev_b32_e32 v39, 16, v39
	v_perm_b32 v46, v46, v52, s94
	v_perm_b32 v47, v47, v53, s94
	v_lshl_add_u64 v[34:35], s[34:35], 0, v[128:129]
	v_and_or_b32 v39, v62, s90, v39
	v_lshl_or_b32 v41, v47, 16, v45
	v_lshl_or_b32 v40, v46, 16, v44
	v_lshl_add_u64 v[34:35], v[34:35], 0, v[194:195]
	global_store_dwordx4 v[56:57], v[36:39], off offset:256 nt
	global_store_dwordx4 v[34:35], v[40:43], off nt
	s_and_saveexec_b64 s[50:51], s[40:41]
	s_cbranch_execz .LBB0_416
	s_waitcnt lgkmcnt(0)
	v_add_f32_e32 v32, v32, v33
	v_fma_f32 v32, v32, s80, 0.5
	v_trunc_f32_e32 v32, v32
	v_mul_f32_e32 v33, 0x2f800000, v32
	v_floor_f32_e32 v33, v33
	v_fmac_f32_e32 v32, 0xcf800000, v33
	v_cvt_u32_f32_e32 v32, v32
	v_cvt_u32_f32_e32 v33, v33
	v_lshl_add_u64 v[34:35], v[126:127], 3, s[48:49]
	global_atomic_add_x2 v[34:35], v[32:33], off
.LBB0_416:
	s_or_b64 exec, exec, s[50:51]
	s_waitcnt vmcnt(11)
	v_lshrrev_b32_sdwa v32, v229, v77 dst_sel:DWORD dst_unused:UNUSED_PAD src0_sel:DWORD src1_sel:BYTE_0
	s_waitcnt lgkmcnt(0)
	v_lshrrev_b32_sdwa v33, v229, v76 dst_sel:DWORD dst_unused:UNUSED_PAD src0_sel:DWORD src1_sel:BYTE_0
	s_waitcnt vmcnt(10)
	v_sub_u32_sdwa v34, v84, v33 dst_sel:WORD_1 dst_unused:UNUSED_PAD src0_sel:DWORD src1_sel:DWORD
	v_sub_u32_sdwa v32, v86, v32 dst_sel:WORD_1 dst_unused:UNUSED_PAD src0_sel:DWORD src1_sel:DWORD
	v_lshlrev_b32_sdwa v33, v230, v77 dst_sel:DWORD dst_unused:UNUSED_PAD src0_sel:DWORD src1_sel:BYTE_0
	v_lshlrev_b32_sdwa v35, v230, v76 dst_sel:DWORD dst_unused:UNUSED_PAD src0_sel:DWORD src1_sel:BYTE_0
	v_or_b32_e32 v33, v32, v33
	v_or_b32_e32 v32, v34, v35
	v_mov_b32_e32 v34, v28
	v_mov_b32_e32 v35, v24
	v_pk_fma_f32 v[32:33], v[34:35], 0.5, v[32:33] op_sel_hi:[1,0,1]
	v_lshlrev_b32_e32 v36, 1, v77
	v_lshlrev_b32_e32 v37, 1, v76
	v_add_u32_e32 v24, 0x8000, v32
	v_lshrrev_b32_e32 v42, 16, v24
	v_and_b32_e32 v24, 0x10000, v36
	v_and_b32_e32 v28, 0x10000, v37
	v_sub_u32_e32 v24, v86, v24
	v_sub_u32_e32 v28, v84, v28
	v_and_b32_e32 v38, 0xff00, v77
	v_and_b32_e32 v39, 0xff00, v76
	v_and_b32_e32 v24, 0xffff0000, v24
	v_and_b32_e32 v28, 0xffff0000, v28
	v_or_b32_e32 v35, v24, v38
	v_or_b32_e32 v34, v28, v39
	v_mov_b32_e32 v24, v29
	v_and_b32_sdwa v36, v76, s93 dst_sel:DWORD dst_unused:UNUSED_PAD src0_sel:WORD_1 src1_sel:DWORD
	v_pk_fma_f32 v[28:29], v[24:25], 0.5, v[34:35] op_sel_hi:[1,0,1]
	v_and_b32_sdwa v25, v77, s93 dst_sel:DWORD dst_unused:UNUSED_PAD src0_sel:WORD_1 src1_sel:DWORD
	v_lshrrev_b32_e32 v37, 7, v36
	v_lshlrev_b32_sdwa v40, v231, v76 dst_sel:DWORD dst_unused:UNUSED_PAD src0_sel:DWORD src1_sel:BYTE_3
	v_lshlrev_b32_sdwa v41, v231, v77 dst_sel:DWORD dst_unused:UNUSED_PAD src0_sel:DWORD src1_sel:BYTE_3
	v_lshrrev_b32_e32 v38, 7, v25
	v_sub_u32_sdwa v39, v85, v37 dst_sel:WORD_1 dst_unused:UNUSED_PAD src0_sel:DWORD src1_sel:DWORD
	v_lshlrev_b32_e32 v36, 8, v36
	v_sub_u32_sdwa v37, v87, v38 dst_sel:WORD_1 dst_unused:UNUSED_PAD src0_sel:DWORD src1_sel:DWORD
	v_lshlrev_b32_e32 v25, 8, v25
	v_or_b32_e32 v36, v39, v36
	v_mov_b32_e32 v38, v30
	v_mov_b32_e32 v39, v26
	v_and_b32_e32 v26, 0x10000, v41
	v_and_b32_e32 v30, 0x10000, v40
	v_or_b32_e32 v37, v37, v25
	v_sub_u32_e32 v26, v87, v26
	v_sub_u32_e32 v30, v85, v30
	v_pk_fma_f32 v[36:37], v[38:39], 0.5, v[36:37] op_sel_hi:[1,0,1]
	v_and_b32_e32 v26, 0xffff0000, v26
	v_and_b32_e32 v30, 0xffff0000, v30
	v_lshlrev_b32_sdwa v38, v230, v77 dst_sel:DWORD dst_unused:UNUSED_PAD src0_sel:DWORD src1_sel:BYTE_3
	v_lshlrev_b32_sdwa v40, v230, v76 dst_sel:DWORD dst_unused:UNUSED_PAD src0_sel:DWORD src1_sel:BYTE_3
	v_or_b32_e32 v39, v26, v38
	v_or_b32_e32 v38, v30, v40
	v_mov_b32_e32 v26, v31
	v_add_u32_e32 v25, 0x8000, v36
	v_pk_fma_f32 v[30:31], v[26:27], 0.5, v[38:39] op_sel_hi:[1,0,1]
	v_lshrrev_b32_e32 v25, 16, v25
	v_add_u32_e32 v26, 0x8000, v30
	v_and_or_b32 v25, v26, s90, v25
	v_pk_mul_f32 v[26:27], v[30:31], v[30:31]
	v_add_u32_e32 v40, 0x8000, v31
	v_pk_fma_f32 v[38:39], v[36:37], v[36:37], v[26:27]
	v_add_u32_e32 v26, 0x8000, v33
	v_lshrrev_b32_e32 v26, 16, v26
	v_add_u32_e32 v27, 0x8000, v29
	v_and_or_b32 v26, v27, s90, v26
	v_add_u32_e32 v27, 0x8000, v37
	v_lshrrev_b32_e32 v27, 16, v27
	v_add_u32_e32 v24, 0x8000, v28
	v_and_or_b32 v27, v40, s90, v27
	v_lshl_add_u64 v[40:41], v[124:125], 1, s[30:31]
	v_and_or_b32 v24, v24, s90, v42
	v_lshl_add_u64 v[40:41], v[196:197], 1, v[40:41]
	global_store_dwordx4 v[40:41], v[24:27], off nt
	v_lshlrev_b32_e32 v42, 1, v79
	v_lshlrev_b32_e32 v43, 1, v78
	v_lshrrev_b32_sdwa v24, v229, v79 dst_sel:DWORD dst_unused:UNUSED_PAD src0_sel:DWORD src1_sel:BYTE_0
	v_lshrrev_b32_sdwa v25, v229, v78 dst_sel:DWORD dst_unused:UNUSED_PAD src0_sel:DWORD src1_sel:BYTE_0
	s_waitcnt vmcnt(10)
; #define PG8_GAS __attribute__((address_space(1)))
; __device__ __forceinline__ float e_x24(unsigned h16, unsigned l8) { return __uint_as_float(((h16 - (l8 >> 7)) << 16) | (l8 << 8)); }
;     __device__ __forceinline__ void operator()(const f32x4 (&acc)[2][2][4][2], const Unit& u, int wr, int wc, int fr, int fq) const {
;     ...
;             for (int m = 0; m < 4; ++m) {
;                 const int row = row0 + ai * HALF + m * 16; const size_t off = (size_t)row * 2048 + col0, loff = (size_t)row * 2048 + lcol; float ss = 0.f;
;                 const u32x4 l4 = L4[m];
;                 u32x4 lo4;
; #pragma unroll
;                 for (int bj = 0; bj < 2; ++bj) {
;                     const u32x4 h4 = H4[m][bj];
;                     u32x4 ho;
; #pragma unroll
;                     for (int j = 0; j < 4; ++j) {
;                         const unsigned lw = l4[2 * bj + (j >> 1)], lb0 = (lw >> (16 * (j & 1))) & 0xffu, lb1 = (lw >> (16 * (j & 1) + 8)) & 0xffu;
;                         const float x0 = e_x24(h4[j] & 0xffffu, lb0) + acc[ai][bj][m][j >> 1][2 * (j & 1)] * scale, x1 = e_x24(h4[j] >> 16, lb1) + acc[ai][bj][m][j >> 1][2 * (j & 1) + 1] * scale;
;                         const unsigned b0 = __float_as_uint(x0), b1 = __float_as_uint(x1);
;                         ho[j] = ((b0 + 0x8000u) >> 16) | ((b1 + 0x8000u) & 0xffff0000u);
;                         const unsigned nb = ((b0 >> 8) & 0xffu) | (b1 & 0xff00u);
;                         if ((j & 1) == 0) lo4[2 * bj + (j >> 1)] = nb; else lo4[2 * bj + (j >> 1)] |= nb << 16;
;                         ss += x0 * x0 + x1 * x1;
;                     }
;                     *(PG8_GAS u32x4*)(hout + off + bj * HALF) = ho;
;                 }
;                 *(PG8_GAS u32x4*)(lout + loff) = lo4;
;                 ss += __shfl_xor(ss, 16); ss += __shfl_xor(ss, 32);
;                 if (fq == 0) __hip_atomic_fetch_add((PG8_GAS unsigned long long*)(rowsq_out + row), (unsigned long long)(ss * 16777216.0f + 0.5f), __ATOMIC_RELAXED, __HIP_MEMORY_SCOPE_AGENT);
	v_sub_u32_sdwa v26, v80, v25 dst_sel:WORD_1 dst_unused:UNUSED_PAD src0_sel:DWORD src1_sel:DWORD
	v_sub_u32_sdwa v24, v82, v24 dst_sel:WORD_1 dst_unused:UNUSED_PAD src0_sel:DWORD src1_sel:DWORD
	v_lshlrev_b32_sdwa v25, v230, v79 dst_sel:DWORD dst_unused:UNUSED_PAD src0_sel:DWORD src1_sel:BYTE_0
	v_lshlrev_b32_sdwa v27, v230, v78 dst_sel:DWORD dst_unused:UNUSED_PAD src0_sel:DWORD src1_sel:BYTE_0
	v_or_b32_e32 v25, v24, v25
	v_or_b32_e32 v24, v26, v27
	v_mov_b32_e32 v26, v20
	v_mov_b32_e32 v27, v16
	v_pk_fma_f32 v[24:25], v[26:27], 0.5, v[24:25] op_sel_hi:[1,0,1]
	v_and_b32_e32 v26, 0x10000, v43
	v_add_u32_e32 v16, 0x8000, v24
	v_lshrrev_b32_e32 v20, 16, v16
	v_and_b32_e32 v16, 0x10000, v42
	v_sub_u32_e32 v16, v82, v16
	v_sub_u32_e32 v26, v80, v26
	v_and_b32_e32 v44, 0xff00, v79
	v_and_b32_e32 v45, 0xff00, v78
	v_and_b32_e32 v16, 0xffff0000, v16
	v_and_b32_e32 v26, 0xffff0000, v26
	v_or_b32_e32 v27, v16, v44
	v_or_b32_e32 v26, v26, v45
	v_mov_b32_e32 v16, v21
	v_pk_fma_f32 v[16:17], v[16:17], 0.5, v[26:27] op_sel_hi:[1,0,1]
	v_and_b32_sdwa v42, v78, s93 dst_sel:DWORD dst_unused:UNUSED_PAD src0_sel:WORD_1 src1_sel:DWORD
	v_add_u32_e32 v21, 0x8000, v16
	v_and_or_b32 v20, v21, s90, v20
	v_and_b32_sdwa v21, v79, s93 dst_sel:DWORD dst_unused:UNUSED_PAD src0_sel:WORD_1 src1_sel:DWORD
	v_lshrrev_b32_e32 v43, 7, v42
	v_lshrrev_b32_e32 v44, 7, v21
	v_sub_u32_sdwa v45, v81, v43 dst_sel:WORD_1 dst_unused:UNUSED_PAD src0_sel:DWORD src1_sel:DWORD
	v_sub_u32_sdwa v43, v83, v44 dst_sel:WORD_1 dst_unused:UNUSED_PAD src0_sel:DWORD src1_sel:DWORD
	v_lshlrev_b32_e32 v21, 8, v21
	v_lshlrev_b32_e32 v42, 8, v42
	v_or_b32_e32 v43, v43, v21
	v_or_b32_e32 v42, v45, v42
	v_mov_b32_e32 v44, v22
	v_mov_b32_e32 v45, v18
	v_pk_fma_f32 v[42:43], v[44:45], 0.5, v[42:43] op_sel_hi:[1,0,1]
	v_lshlrev_b32_sdwa v46, v231, v78 dst_sel:DWORD dst_unused:UNUSED_PAD src0_sel:DWORD src1_sel:BYTE_3
	v_lshlrev_b32_sdwa v47, v231, v79 dst_sel:DWORD dst_unused:UNUSED_PAD src0_sel:DWORD src1_sel:BYTE_3
	v_add_u32_e32 v18, 0x8000, v42
	v_lshrrev_b32_e32 v21, 16, v18
	v_and_b32_e32 v18, 0x10000, v47
	v_and_b32_e32 v22, 0x10000, v46
	v_sub_u32_e32 v18, v83, v18
	v_sub_u32_e32 v22, v81, v22
	v_pk_mul_f32 v[34:35], v[28:29], v[28:29]
	v_pk_mul_f32 v[26:27], v[16:17], v[16:17]
	v_and_b32_e32 v18, 0xffff0000, v18
	v_and_b32_e32 v22, 0xffff0000, v22
	v_lshlrev_b32_sdwa v44, v230, v79 dst_sel:DWORD dst_unused:UNUSED_PAD src0_sel:DWORD src1_sel:BYTE_3
	v_lshlrev_b32_sdwa v46, v230, v78 dst_sel:DWORD dst_unused:UNUSED_PAD src0_sel:DWORD src1_sel:BYTE_3
	v_pk_fma_f32 v[34:35], v[32:33], v[32:33], v[34:35]
	v_pk_fma_f32 v[26:27], v[24:25], v[24:25], v[26:27]
	v_or_b32_e32 v45, v18, v44
	v_or_b32_e32 v44, v22, v46
	v_mov_b32_e32 v18, v23
	v_lshrrev_b32_e32 v24, 8, v24
	v_pk_fma_f32 v[18:19], v[18:19], 0.5, v[44:45] op_sel_hi:[1,0,1]
	v_perm_b32 v16, v16, v24, s94
	v_add_f32_e32 v24, v34, v38
	v_add_u32_e32 v22, 0x8000, v18
	v_add_f32_e32 v24, v35, v24
	v_and_or_b32 v21, v22, s90, v21
	v_pk_mul_f32 v[22:23], v[18:19], v[18:19]
	v_add_f32_e32 v24, v39, v24
	v_pk_fma_f32 v[44:45], v[42:43], v[42:43], v[22:23]
	v_add_f32_e32 v24, v26, v24
	v_add_f32_e32 v24, v44, v24
	v_lshrrev_b32_e32 v32, 8, v32
	v_add_f32_e32 v24, v27, v24
	v_lshrrev_b32_e32 v33, 8, v33
	v_perm_b32 v28, v28, v32, s94
	v_add_f32_e32 v32, v45, v24
	v_perm_b32 v29, v29, v33, s94
	ds_bpermute_b32 v33, v238, v32
	v_add_u32_e32 v22, 0x8000, v25
	v_lshrrev_b32_e32 v22, 16, v22
	v_add_u32_e32 v23, 0x8000, v17
	v_lshrrev_b32_e32 v42, 8, v42
	v_and_or_b32 v22, v23, s90, v22
	v_add_u32_e32 v23, 0x8000, v43
	v_lshrrev_b32_e32 v43, 8, v43
	v_perm_b32 v18, v18, v42, s94
	v_lshrrev_b32_e32 v25, 8, v25
	v_add_u32_e32 v46, 0x8000, v19
	v_perm_b32 v19, v19, v43, s94
	v_perm_b32 v17, v17, v25, s94
	v_lshl_or_b32 v26, v18, 16, v16
	s_waitcnt lgkmcnt(0)
	v_add_f32_e32 v16, v32, v33
	v_lshl_or_b32 v27, v19, 16, v17
	ds_bpermute_b32 v17, v237, v16
	v_lshrrev_b32_e32 v37, 8, v37
	v_lshrrev_b32_e32 v36, 8, v36
	v_lshrrev_b32_e32 v23, 16, v23
	v_perm_b32 v30, v30, v36, s94
	v_perm_b32 v31, v31, v37, s94
	v_lshl_add_u64 v[18:19], s[34:35], 0, v[124:125]
	v_and_or_b32 v23, v46, s90, v23
	v_lshl_or_b32 v25, v31, 16, v29
	v_lshl_or_b32 v24, v30, 16, v28
	v_lshl_add_u64 v[18:19], v[18:19], 0, v[194:195]
	global_store_dwordx4 v[40:41], v[20:23], off offset:256 nt
	global_store_dwordx4 v[18:19], v[24:27], off nt
	s_and_saveexec_b64 s[50:51], s[40:41]
	s_cbranch_execz .LBB0_418
	s_waitcnt lgkmcnt(0)
	v_add_f32_e32 v16, v16, v17
	v_fma_f32 v16, v16, s80, 0.5
	v_trunc_f32_e32 v16, v16
	v_mul_f32_e32 v17, 0x2f800000, v16
	v_floor_f32_e32 v17, v17
	v_fmac_f32_e32 v16, 0xcf800000, v17
	v_cvt_u32_f32_e32 v16, v16
	v_cvt_u32_f32_e32 v17, v17
	v_lshl_add_u64 v[18:19], v[122:123], 3, s[48:49]
	global_atomic_add_x2 v[18:19], v[16:17], off
; #define PG8_GAS __attribute__((address_space(1)))
; __device__ __forceinline__ float e_x24(unsigned h16, unsigned l8) { return __uint_as_float(((h16 - (l8 >> 7)) << 16) | (l8 << 8)); }
;     __device__ __forceinline__ void operator()(const f32x4 (&acc)[2][2][4][2], const Unit& u, int wr, int wc, int fr, int fq) const {
;     ...
;             for (int m = 0; m < 4; ++m) {
;                 const int row = row0 + ai * HALF + m * 16; const size_t off = (size_t)row * 2048 + col0, loff = (size_t)row * 2048 + lcol; float ss = 0.f;
;                 const u32x4 l4 = L4[m];
;                 u32x4 lo4;
; #pragma unroll
;                 for (int bj = 0; bj < 2; ++bj) {
;                     const u32x4 h4 = H4[m][bj];
;                     u32x4 ho;
; #pragma unroll
;                     for (int j = 0; j < 4; ++j) {
;                         const unsigned lw = l4[2 * bj + (j >> 1)], lb0 = (lw >> (16 * (j & 1))) & 0xffu, lb1 = (lw >> (16 * (j & 1) + 8)) & 0xffu;
;                         const float x0 = e_x24(h4[j] & 0xffffu, lb0) + acc[ai][bj][m][j >> 1][2 * (j & 1)] * scale, x1 = e_x24(h4[j] >> 16, lb1) + acc[ai][bj][m][j >> 1][2 * (j & 1) + 1] * scale;
;                         const unsigned b0 = __float_as_uint(x0), b1 = __float_as_uint(x1);
;                         ho[j] = ((b0 + 0x8000u) >> 16) | ((b1 + 0x8000u) & 0xffff0000u);
;                         const unsigned nb = ((b0 >> 8) & 0xffu) | (b1 & 0xff00u);
;                         if ((j & 1) == 0) lo4[2 * bj + (j >> 1)] = nb; else lo4[2 * bj + (j >> 1)] |= nb << 16;
;                         ss += x0 * x0 + x1 * x1;
;                     }
;                     *(PG8_GAS u32x4*)(hout + off + bj * HALF) = ho;
.LBB0_418:
	s_or_b64 exec, exec, s[50:51]
	s_waitcnt vmcnt(11)
	v_lshrrev_b32_sdwa v16, v229, v65 dst_sel:DWORD dst_unused:UNUSED_PAD src0_sel:DWORD src1_sel:BYTE_0
	s_waitcnt lgkmcnt(0)
	v_lshrrev_b32_sdwa v17, v229, v64 dst_sel:DWORD dst_unused:UNUSED_PAD src0_sel:DWORD src1_sel:BYTE_0
	s_waitcnt vmcnt(10)
	v_sub_u32_sdwa v18, v72, v17 dst_sel:WORD_1 dst_unused:UNUSED_PAD src0_sel:DWORD src1_sel:DWORD
	v_sub_u32_sdwa v16, v74, v16 dst_sel:WORD_1 dst_unused:UNUSED_PAD src0_sel:DWORD src1_sel:DWORD
	v_lshlrev_b32_sdwa v17, v230, v65 dst_sel:DWORD dst_unused:UNUSED_PAD src0_sel:DWORD src1_sel:BYTE_0
	v_lshlrev_b32_sdwa v19, v230, v64 dst_sel:DWORD dst_unused:UNUSED_PAD src0_sel:DWORD src1_sel:BYTE_0
	v_or_b32_e32 v17, v16, v17
	v_or_b32_e32 v16, v18, v19
	v_mov_b32_e32 v18, v12
	v_mov_b32_e32 v19, v8
	v_pk_fma_f32 v[16:17], v[18:19], 0.5, v[16:17] op_sel_hi:[1,0,1]
	v_lshlrev_b32_e32 v20, 1, v65
	v_lshlrev_b32_e32 v21, 1, v64
	v_add_u32_e32 v8, 0x8000, v16
	v_lshrrev_b32_e32 v26, 16, v8
	v_and_b32_e32 v8, 0x10000, v20
	v_and_b32_e32 v12, 0x10000, v21
	v_sub_u32_e32 v8, v74, v8
	v_sub_u32_e32 v12, v72, v12
	v_and_b32_e32 v22, 0xff00, v65
	v_and_b32_e32 v23, 0xff00, v64
	v_and_b32_e32 v8, 0xffff0000, v8
	v_and_b32_e32 v12, 0xffff0000, v12
	v_or_b32_e32 v19, v8, v22
	v_or_b32_e32 v18, v12, v23
	v_mov_b32_e32 v8, v13
	v_and_b32_sdwa v20, v64, s93 dst_sel:DWORD dst_unused:UNUSED_PAD src0_sel:WORD_1 src1_sel:DWORD
	v_pk_fma_f32 v[12:13], v[8:9], 0.5, v[18:19] op_sel_hi:[1,0,1]
	v_and_b32_sdwa v9, v65, s93 dst_sel:DWORD dst_unused:UNUSED_PAD src0_sel:WORD_1 src1_sel:DWORD
	v_lshrrev_b32_e32 v21, 7, v20
	v_lshlrev_b32_sdwa v24, v231, v64 dst_sel:DWORD dst_unused:UNUSED_PAD src0_sel:DWORD src1_sel:BYTE_3
	v_lshlrev_b32_sdwa v25, v231, v65 dst_sel:DWORD dst_unused:UNUSED_PAD src0_sel:DWORD src1_sel:BYTE_3
	v_lshrrev_b32_e32 v22, 7, v9
	v_sub_u32_sdwa v23, v73, v21 dst_sel:WORD_1 dst_unused:UNUSED_PAD src0_sel:DWORD src1_sel:DWORD
	v_lshlrev_b32_e32 v20, 8, v20
	v_sub_u32_sdwa v21, v75, v22 dst_sel:WORD_1 dst_unused:UNUSED_PAD src0_sel:DWORD src1_sel:DWORD
	v_lshlrev_b32_e32 v9, 8, v9
	v_or_b32_e32 v20, v23, v20
	v_mov_b32_e32 v22, v14
	v_mov_b32_e32 v23, v10
	v_and_b32_e32 v10, 0x10000, v25
	v_and_b32_e32 v14, 0x10000, v24
	v_or_b32_e32 v21, v21, v9
	v_sub_u32_e32 v10, v75, v10
	v_sub_u32_e32 v14, v73, v14
	v_pk_fma_f32 v[20:21], v[22:23], 0.5, v[20:21] op_sel_hi:[1,0,1]
	v_and_b32_e32 v10, 0xffff0000, v10
	v_and_b32_e32 v14, 0xffff0000, v14
	v_lshlrev_b32_sdwa v22, v230, v65 dst_sel:DWORD dst_unused:UNUSED_PAD src0_sel:DWORD src1_sel:BYTE_3
	v_lshlrev_b32_sdwa v24, v230, v64 dst_sel:DWORD dst_unused:UNUSED_PAD src0_sel:DWORD src1_sel:BYTE_3
	v_or_b32_e32 v23, v10, v22
	v_or_b32_e32 v22, v14, v24
	v_mov_b32_e32 v10, v15
	v_add_u32_e32 v9, 0x8000, v20
	v_pk_fma_f32 v[14:15], v[10:11], 0.5, v[22:23] op_sel_hi:[1,0,1]
	v_lshrrev_b32_e32 v9, 16, v9
	v_add_u32_e32 v10, 0x8000, v14
	v_and_or_b32 v9, v10, s90, v9
	v_pk_mul_f32 v[10:11], v[14:15], v[14:15]
	v_add_u32_e32 v24, 0x8000, v15
	v_pk_fma_f32 v[22:23], v[20:21], v[20:21], v[10:11]
	v_add_u32_e32 v10, 0x8000, v17
	v_lshrrev_b32_e32 v10, 16, v10
	v_add_u32_e32 v11, 0x8000, v13
	v_and_or_b32 v10, v11, s90, v10
	v_add_u32_e32 v11, 0x8000, v21
	v_lshrrev_b32_e32 v11, 16, v11
	v_add_u32_e32 v8, 0x8000, v12
	v_and_or_b32 v11, v24, s90, v11
	v_lshl_add_u64 v[24:25], v[120:121], 1, s[30:31]
	v_and_or_b32 v8, v8, s90, v26
	v_lshl_add_u64 v[24:25], v[196:197], 1, v[24:25]
	global_store_dwordx4 v[24:25], v[8:11], off nt
	v_lshlrev_b32_e32 v26, 1, v67
	v_lshlrev_b32_e32 v27, 1, v66
	v_lshrrev_b32_sdwa v8, v229, v67 dst_sel:DWORD dst_unused:UNUSED_PAD src0_sel:DWORD src1_sel:BYTE_0
	v_lshrrev_b32_sdwa v9, v229, v66 dst_sel:DWORD dst_unused:UNUSED_PAD src0_sel:DWORD src1_sel:BYTE_0
	s_waitcnt vmcnt(10)
; #define PG8_GAS __attribute__((address_space(1)))
; __device__ __forceinline__ float e_x24(unsigned h16, unsigned l8) { return __uint_as_float(((h16 - (l8 >> 7)) << 16) | (l8 << 8)); }
;     __device__ __forceinline__ void operator()(const f32x4 (&acc)[2][2][4][2], const Unit& u, int wr, int wc, int fr, int fq) const {
;     ...
;             for (int m = 0; m < 4; ++m) {
;                 const int row = row0 + ai * HALF + m * 16; const size_t off = (size_t)row * 2048 + col0, loff = (size_t)row * 2048 + lcol; float ss = 0.f;
;                 const u32x4 l4 = L4[m];
;                 u32x4 lo4;
; #pragma unroll
;                 for (int bj = 0; bj < 2; ++bj) {
;                     const u32x4 h4 = H4[m][bj];
;                     u32x4 ho;
; #pragma unroll
;                     for (int j = 0; j < 4; ++j) {
;                         const unsigned lw = l4[2 * bj + (j >> 1)], lb0 = (lw >> (16 * (j & 1))) & 0xffu, lb1 = (lw >> (16 * (j & 1) + 8)) & 0xffu;
;                         const float x0 = e_x24(h4[j] & 0xffffu, lb0) + acc[ai][bj][m][j >> 1][2 * (j & 1)] * scale, x1 = e_x24(h4[j] >> 16, lb1) + acc[ai][bj][m][j >> 1][2 * (j & 1) + 1] * scale;
;                         const unsigned b0 = __float_as_uint(x0), b1 = __float_as_uint(x1);
;                         ho[j] = ((b0 + 0x8000u) >> 16) | ((b1 + 0x8000u) & 0xffff0000u);
;                         const unsigned nb = ((b0 >> 8) & 0xffu) | (b1 & 0xff00u);
;                         if ((j & 1) == 0) lo4[2 * bj + (j >> 1)] = nb; else lo4[2 * bj + (j >> 1)] |= nb << 16;
;                         ss += x0 * x0 + x1 * x1;
;                     }
;                     *(PG8_GAS u32x4*)(hout + off + bj * HALF) = ho;
;                 }
;                 *(PG8_GAS u32x4*)(lout + loff) = lo4;
;                 ss += __shfl_xor(ss, 16); ss += __shfl_xor(ss, 32);
;                 if (fq == 0) __hip_atomic_fetch_add((PG8_GAS unsigned long long*)(rowsq_out + row), (unsigned long long)(ss * 16777216.0f + 0.5f), __ATOMIC_RELAXED, __HIP_MEMORY_SCOPE_AGENT);
	v_sub_u32_sdwa v10, v68, v9 dst_sel:WORD_1 dst_unused:UNUSED_PAD src0_sel:DWORD src1_sel:DWORD
	v_sub_u32_sdwa v8, v70, v8 dst_sel:WORD_1 dst_unused:UNUSED_PAD src0_sel:DWORD src1_sel:DWORD
	v_lshlrev_b32_sdwa v9, v230, v67 dst_sel:DWORD dst_unused:UNUSED_PAD src0_sel:DWORD src1_sel:BYTE_0
	v_lshlrev_b32_sdwa v11, v230, v66 dst_sel:DWORD dst_unused:UNUSED_PAD src0_sel:DWORD src1_sel:BYTE_0
	v_or_b32_e32 v9, v8, v9
	v_or_b32_e32 v8, v10, v11
	v_mov_b32_e32 v10, v4
	v_mov_b32_e32 v11, v0
	v_pk_fma_f32 v[8:9], v[10:11], 0.5, v[8:9] op_sel_hi:[1,0,1]
	v_and_b32_e32 v10, 0x10000, v27
	v_add_u32_e32 v0, 0x8000, v8
	v_lshrrev_b32_e32 v4, 16, v0
	v_and_b32_e32 v0, 0x10000, v26
	v_sub_u32_e32 v0, v70, v0
	v_sub_u32_e32 v10, v68, v10
	v_and_b32_e32 v28, 0xff00, v67
	v_and_b32_e32 v29, 0xff00, v66
	v_and_b32_e32 v0, 0xffff0000, v0
	v_and_b32_e32 v10, 0xffff0000, v10
	v_or_b32_e32 v11, v0, v28
	v_or_b32_e32 v10, v10, v29
	v_mov_b32_e32 v0, v5
	v_pk_fma_f32 v[0:1], v[0:1], 0.5, v[10:11] op_sel_hi:[1,0,1]
	v_and_b32_sdwa v26, v66, s93 dst_sel:DWORD dst_unused:UNUSED_PAD src0_sel:WORD_1 src1_sel:DWORD
	v_add_u32_e32 v5, 0x8000, v0
	v_and_or_b32 v4, v5, s90, v4
	v_and_b32_sdwa v5, v67, s93 dst_sel:DWORD dst_unused:UNUSED_PAD src0_sel:WORD_1 src1_sel:DWORD
	v_lshrrev_b32_e32 v27, 7, v26
	v_lshrrev_b32_e32 v28, 7, v5
	v_sub_u32_sdwa v29, v69, v27 dst_sel:WORD_1 dst_unused:UNUSED_PAD src0_sel:DWORD src1_sel:DWORD
	v_sub_u32_sdwa v27, v71, v28 dst_sel:WORD_1 dst_unused:UNUSED_PAD src0_sel:DWORD src1_sel:DWORD
	v_lshlrev_b32_e32 v5, 8, v5
	v_lshlrev_b32_e32 v26, 8, v26
	v_or_b32_e32 v27, v27, v5
	v_or_b32_e32 v26, v29, v26
	v_mov_b32_e32 v28, v6
	v_mov_b32_e32 v29, v2
	v_pk_fma_f32 v[26:27], v[28:29], 0.5, v[26:27] op_sel_hi:[1,0,1]
	v_lshlrev_b32_sdwa v30, v231, v66 dst_sel:DWORD dst_unused:UNUSED_PAD src0_sel:DWORD src1_sel:BYTE_3
	v_lshlrev_b32_sdwa v31, v231, v67 dst_sel:DWORD dst_unused:UNUSED_PAD src0_sel:DWORD src1_sel:BYTE_3
	v_add_u32_e32 v2, 0x8000, v26
	v_lshrrev_b32_e32 v5, 16, v2
	v_and_b32_e32 v2, 0x10000, v31
	v_and_b32_e32 v6, 0x10000, v30
	v_sub_u32_e32 v2, v71, v2
	v_sub_u32_e32 v6, v69, v6
	v_pk_mul_f32 v[18:19], v[12:13], v[12:13]
	v_pk_mul_f32 v[10:11], v[0:1], v[0:1]
	v_and_b32_e32 v2, 0xffff0000, v2
	v_and_b32_e32 v6, 0xffff0000, v6
	v_lshlrev_b32_sdwa v28, v230, v67 dst_sel:DWORD dst_unused:UNUSED_PAD src0_sel:DWORD src1_sel:BYTE_3
	v_lshlrev_b32_sdwa v30, v230, v66 dst_sel:DWORD dst_unused:UNUSED_PAD src0_sel:DWORD src1_sel:BYTE_3
	v_pk_fma_f32 v[18:19], v[16:17], v[16:17], v[18:19]
	v_pk_fma_f32 v[10:11], v[8:9], v[8:9], v[10:11]
	v_or_b32_e32 v29, v2, v28
	v_or_b32_e32 v28, v6, v30
	v_mov_b32_e32 v2, v7
	v_lshrrev_b32_e32 v8, 8, v8
	v_pk_fma_f32 v[2:3], v[2:3], 0.5, v[28:29] op_sel_hi:[1,0,1]
	v_perm_b32 v0, v0, v8, s94
	v_add_f32_e32 v8, v18, v22
	v_add_u32_e32 v6, 0x8000, v2
	v_add_f32_e32 v8, v19, v8
	v_and_or_b32 v5, v6, s90, v5
	v_pk_mul_f32 v[6:7], v[2:3], v[2:3]
	v_add_f32_e32 v8, v23, v8
	v_pk_fma_f32 v[28:29], v[26:27], v[26:27], v[6:7]
	v_add_f32_e32 v8, v10, v8
	v_add_f32_e32 v8, v28, v8
	v_lshrrev_b32_e32 v16, 8, v16
	v_add_f32_e32 v8, v11, v8
	v_lshrrev_b32_e32 v17, 8, v17
	v_perm_b32 v12, v12, v16, s94
	v_add_f32_e32 v16, v29, v8
	v_perm_b32 v13, v13, v17, s94
	ds_bpermute_b32 v17, v238, v16
	v_add_u32_e32 v6, 0x8000, v9
	v_lshrrev_b32_e32 v6, 16, v6
	v_add_u32_e32 v7, 0x8000, v1
	v_lshrrev_b32_e32 v26, 8, v26
	v_and_or_b32 v6, v7, s90, v6
	v_add_u32_e32 v7, 0x8000, v27
	v_lshrrev_b32_e32 v27, 8, v27
	v_perm_b32 v2, v2, v26, s94
	v_lshrrev_b32_e32 v9, 8, v9
	v_add_u32_e32 v30, 0x8000, v3
	v_perm_b32 v3, v3, v27, s94
	v_perm_b32 v1, v1, v9, s94
	v_lshl_or_b32 v10, v2, 16, v0
	s_waitcnt lgkmcnt(0)
	v_add_f32_e32 v0, v16, v17
	v_lshl_or_b32 v11, v3, 16, v1
	ds_bpermute_b32 v1, v237, v0
	v_lshrrev_b32_e32 v21, 8, v21
	v_lshrrev_b32_e32 v20, 8, v20
	v_lshrrev_b32_e32 v7, 16, v7
	v_perm_b32 v14, v14, v20, s94
	v_perm_b32 v15, v15, v21, s94
	v_lshl_add_u64 v[2:3], s[34:35], 0, v[120:121]
	v_and_or_b32 v7, v30, s90, v7
	v_lshl_or_b32 v9, v15, 16, v13
	v_lshl_or_b32 v8, v14, 16, v12
	v_lshl_add_u64 v[2:3], v[2:3], 0, v[194:195]
	global_store_dwordx4 v[24:25], v[4:7], off offset:256 nt
	global_store_dwordx4 v[2:3], v[8:11], off nt
	s_and_saveexec_b64 s[50:51], s[40:41]
	s_cbranch_execz .LBB0_391
	s_waitcnt lgkmcnt(0)
	v_add_f32_e32 v0, v0, v1
	v_fma_f32 v0, v0, s80, 0.5
	v_trunc_f32_e32 v0, v0
	v_mul_f32_e32 v1, 0x2f800000, v0
	v_floor_f32_e32 v1, v1
	v_fmac_f32_e32 v0, 0xcf800000, v1
	v_cvt_u32_f32_e32 v0, v0
	v_cvt_u32_f32_e32 v1, v1
	v_lshl_add_u64 v[2:3], v[118:119], 3, s[48:49]
	global_atomic_add_x2 v[2:3], v[0:1], off
	s_branch .LBB0_391

; #define PG8_STAGE(bufoff, gbase, voff) do { _Pragma("unroll") for (int _i = 0; _i < 2; ++_i) \
;         __builtin_amdgcn_global_load_lds((const unsigned*)((const char*)(gbase) + (voff)[_i]), (PG8_LAS unsigned*)(lds + (bufoff) + ldsw + _i * 8192), 16, 0, 0); } while (0)
; #define PG8_LDA(dst, b, h) do { _Pragma("unroll") for (int m = 0; m < 4; ++m) _Pragma("unroll") for (int k = 0; k < 2; ++k) dst[m][k] = *(const PG8_LAS bf16x8*)(lds + PG8_SA(b, h) + aoff + m * 2048 + k * 1024); } while (0)
; #define PG8_LDB(dst, b, h) do { _Pragma("unroll") for (int n = 0; n < 2; ++n) _Pragma("unroll") for (int k = 0; k < 2; ++k) dst[n][k] = *(const PG8_LAS bf16x8*)(lds + PG8_SB(b, h) + boff + n * 2048 + k * 1024); } while (0)
; #define PG8_MMA(ai, bj, At, Bt) do { __builtin_amdgcn_s_setprio(1); _Pragma("unroll") for (int m = 0; m < 4; ++m) _Pragma("unroll") for (int n = 0; n < 2; ++n) _Pragma("unroll") for (int k = 0; k < 2; ++k) \
;         acc[ai][bj][m][n] = __builtin_amdgcn_mfma_f32_16x16x32_bf16(Bt[n][k], At[m][k], acc[ai][bj][m][n], 0, 0, 0); __builtin_amdgcn_s_setprio(0); } while (0)
; #define PG8_WAIT_V(n) asm volatile("s_waitcnt vmcnt(" #n ")" ::: "memory")
; #define PG8_WAIT_L(n) asm volatile("s_waitcnt lgkmcnt(" #n ")" ::: "memory")
; #define PG8_BAR __builtin_amdgcn_s_barrier()
; #define PG8_SCHED __builtin_amdgcn_sched_barrier(0)
; template <class Epi, class Sched, bool ALIGN_EPI = false, bool SP2 = false>
; __device__ __forceinline__ void gemm_phase(PG8_LAS unsigned char* lds, const Gemm g, const Sched& S, const Epi& E, const int tid) {
;     ...
;             PG8_LDB(B0, 0, 0); PG8_LDB(B1, 0, 1); PG8_SCHED; PG8_LDA(At, 0, 0); PG8_STAGE(PG8_SA(1, 1), a1 + hstep, voffA);
;             PG8_WAIT_V(8); PG8_WAIT_L(0); PG8_BAR; PG8_MMA(0, 0, At, B0); PG8_MMA(0, 1, At, B1); PG8_BAR; PG8_SCHED;
;             PG8_LDA(At, 0, 1); PG8_STAGE(PG8_SB(0, 0), b2, voffB); PG8_STAGE(PG8_SB(0, 1), b2 + hstep, voffB); PG8_STAGE(PG8_SA(0, 0), a2, voffA);
;             PG8_WAIT_V(8); PG8_WAIT_L(0); PG8_BAR; PG8_MMA(1, 0, At, B0); PG8_MMA(1, 1, At, B1); PG8_BAR; PG8_SCHED;
.LBB0_1199:
	s_add_u32 s56, s54, 0xfff80080
	s_addc_u32 s57, s55, -1
	s_add_i32 s77, 0, 0x10000
	s_cmp_eq_u32 s76, 28
	s_cselect_b32 s59, s49, s57
	s_cselect_b32 s58, s71, s56
	s_cselect_b32 s57, s47, s75
	s_cselect_b32 s56, s72, s73
	s_add_i32 s80, 0, 0x14000
	v_add_u32_e32 v146, s77, v233
	v_add_u32_e32 v162, s80, v233
	ds_read_b128 v[126:129], v146
	ds_read_b128 v[130:133], v146 offset:1024
	ds_read_b128 v[142:145], v146 offset:2048
	ds_read_b128 v[146:149], v146 offset:3072
	ds_read_b128 v[150:153], v162
	ds_read_b128 v[154:157], v162 offset:1024
	ds_read_b128 v[158:161], v162 offset:2048
	ds_read_b128 v[162:165], v162 offset:3072
	v_lshl_add_u64 v[210:211], s[54:55], 0, v[192:193]
	s_add_i32 m0, s62, 0xc000
	ds_read_b128 v[166:169], v236
	ds_read_b128 v[170:173], v236 offset:1024
	ds_read_b128 v[174:177], v236 offset:2048
	ds_read_b128 v[178:181], v236 offset:3072
	ds_read_b128 v[194:197], v236 offset:4096
	ds_read_b128 v[198:201], v236 offset:5120
	ds_read_b128 v[202:205], v236 offset:6144
	ds_read_b128 v[206:209], v236 offset:7168
	global_load_lds_dwordx4 v[210:211], off
	v_lshl_add_u64 v[210:211], s[54:55], 0, v[190:191]
	s_add_i32 m0, s62, 0xe000
	s_nop 0
	global_load_lds_dwordx4 v[210:211], off
	s_waitcnt vmcnt(8)
	s_waitcnt lgkmcnt(0)
	s_barrier
	s_setprio 1
	s_waitcnt lgkmcnt(0)
	v_mfma_f32_16x16x32_bf16 v[138:141], v[126:129], v[166:169], v[138:141]
	v_mfma_f32_16x16x32_bf16 v[134:137], v[142:145], v[166:169], v[134:137]
	v_mfma_f32_16x16x32_bf16 v[114:117], v[126:129], v[174:177], v[114:117]
	v_mfma_f32_16x16x32_bf16 v[110:113], v[142:145], v[174:177], v[110:113]
	v_mfma_f32_16x16x32_bf16 v[92:95], v[126:129], v[194:197], v[92:95]
	v_mfma_f32_16x16x32_bf16 v[88:91], v[142:145], v[194:197], v[88:91]
	v_mfma_f32_16x16x32_bf16 v[76:79], v[126:129], v[202:205], v[76:79]
	v_mfma_f32_16x16x32_bf16 v[72:75], v[142:145], v[202:205], v[72:75]
	v_mfma_f32_16x16x32_bf16 v[138:141], v[130:133], v[170:173], v[138:141]
	v_mfma_f32_16x16x32_bf16 v[134:137], v[146:149], v[170:173], v[134:137]
	v_mfma_f32_16x16x32_bf16 v[114:117], v[130:133], v[178:181], v[114:117]
	v_mfma_f32_16x16x32_bf16 v[110:113], v[146:149], v[178:181], v[110:113]
	v_mfma_f32_16x16x32_bf16 v[92:95], v[130:133], v[198:201], v[92:95]
	v_mfma_f32_16x16x32_bf16 v[88:91], v[146:149], v[198:201], v[88:91]
	v_mfma_f32_16x16x32_bf16 v[76:79], v[130:133], v[206:209], v[76:79]
	v_mfma_f32_16x16x32_bf16 v[72:75], v[146:149], v[206:209], v[72:75]
	s_setprio 0
	s_setprio 1
	v_mfma_f32_16x16x32_bf16 v[122:125], v[150:153], v[166:169], v[122:125]
	v_mfma_f32_16x16x32_bf16 v[118:121], v[158:161], v[166:169], v[118:121]
	v_mfma_f32_16x16x32_bf16 v[106:109], v[150:153], v[174:177], v[106:109]
	v_mfma_f32_16x16x32_bf16 v[102:105], v[158:161], v[174:177], v[102:105]
	v_mfma_f32_16x16x32_bf16 v[84:87], v[150:153], v[194:197], v[84:87]
	v_mfma_f32_16x16x32_bf16 v[80:83], v[158:161], v[194:197], v[80:83]
	v_mfma_f32_16x16x32_bf16 v[68:71], v[150:153], v[202:205], v[68:71]
	v_mfma_f32_16x16x32_bf16 v[64:67], v[158:161], v[202:205], v[64:67]
	v_mfma_f32_16x16x32_bf16 v[122:125], v[154:157], v[170:173], v[122:125]
	v_mfma_f32_16x16x32_bf16 v[118:121], v[162:165], v[170:173], v[118:121]
	v_mfma_f32_16x16x32_bf16 v[106:109], v[154:157], v[178:181], v[106:109]
	v_mfma_f32_16x16x32_bf16 v[102:105], v[162:165], v[178:181], v[102:105]
	v_mfma_f32_16x16x32_bf16 v[84:87], v[154:157], v[198:201], v[84:87]
	v_mfma_f32_16x16x32_bf16 v[80:83], v[162:165], v[198:201], v[80:83]
	v_mfma_f32_16x16x32_bf16 v[68:71], v[154:157], v[206:209], v[68:71]
	v_mfma_f32_16x16x32_bf16 v[64:67], v[162:165], v[206:209], v[64:67]
	s_setprio 0
	s_barrier
	s_add_i32 s77, s77, s61
	v_lshl_add_u64 v[210:211], s[56:57], 0, v[96:97]
	s_mov_b32 m0, s77
	ds_read_b128 v[166:169], v236 offset:16384
	ds_read_b128 v[170:173], v236 offset:17408
	ds_read_b128 v[174:177], v236 offset:18432
	ds_read_b128 v[178:181], v236 offset:19456
	ds_read_b128 v[194:197], v236 offset:20480
	ds_read_b128 v[198:201], v236 offset:21504
	ds_read_b128 v[202:205], v236 offset:22528
	ds_read_b128 v[206:209], v236 offset:23552
	global_load_lds_dwordx4 v[210:211], off
	s_add_i32 m0, s77, 0x2000
	s_add_u32 s78, s56, 0x80000
	v_lshl_add_u64 v[212:213], s[56:57], 0, v[98:99]
	s_addc_u32 s79, s57, 0
	s_add_i32 s77, s80, s61
	global_load_lds_dwordx4 v[212:213], off
	v_lshl_add_u64 v[214:215], s[78:79], 0, v[96:97]
	s_mov_b32 m0, s77
	v_lshl_add_u64 v[216:217], s[58:59], 0, v[186:187]
	global_load_lds_dwordx4 v[214:215], off
	v_lshl_add_u64 v[214:215], s[78:79], 0, v[98:99]
	s_add_i32 m0, s77, 0x2000
	s_nop 0
	global_load_lds_dwordx4 v[214:215], off
	v_lshl_add_u64 v[214:215], s[58:59], 0, v[188:189]
	s_mov_b32 m0, s62
	s_nop 0
	global_load_lds_dwordx4 v[214:215], off
	s_mov_b32 m0, s63
	s_nop 0
	global_load_lds_dwordx4 v[216:217], off
	s_waitcnt vmcnt(8)
	s_waitcnt lgkmcnt(0)
	s_barrier
; #define PG8_STAGE(bufoff, gbase, voff) do { _Pragma("unroll") for (int _i = 0; _i < 2; ++_i) \
;         __builtin_amdgcn_global_load_lds((const unsigned*)((const char*)(gbase) + (voff)[_i]), (PG8_LAS unsigned*)(lds + (bufoff) + ldsw + _i * 8192), 16, 0, 0); } while (0)
; #define PG8_LDA(dst, b, h) do { _Pragma("unroll") for (int m = 0; m < 4; ++m) _Pragma("unroll") for (int k = 0; k < 2; ++k) dst[m][k] = *(const PG8_LAS bf16x8*)(lds + PG8_SA(b, h) + aoff + m * 2048 + k * 1024); } while (0)
; #define PG8_LDB(dst, b, h) do { _Pragma("unroll") for (int n = 0; n < 2; ++n) _Pragma("unroll") for (int k = 0; k < 2; ++k) dst[n][k] = *(const PG8_LAS bf16x8*)(lds + PG8_SB(b, h) + boff + n * 2048 + k * 1024); } while (0)
; #define PG8_MMA(ai, bj, At, Bt) do { __builtin_amdgcn_s_setprio(1); _Pragma("unroll") for (int m = 0; m < 4; ++m) _Pragma("unroll") for (int n = 0; n < 2; ++n) _Pragma("unroll") for (int k = 0; k < 2; ++k) \
;         acc[ai][bj][m][n] = __builtin_amdgcn_mfma_f32_16x16x32_bf16(Bt[n][k], At[m][k], acc[ai][bj][m][n], 0, 0, 0); __builtin_amdgcn_s_setprio(0); } while (0)
; #define PG8_WAIT_V(n) asm volatile("s_waitcnt vmcnt(" #n ")" ::: "memory")
; #define PG8_WAIT_L(n) asm volatile("s_waitcnt lgkmcnt(" #n ")" ::: "memory")
; #define PG8_BAR __builtin_amdgcn_s_barrier()
; #define PG8_SCHED __builtin_amdgcn_sched_barrier(0)
; template <class Epi, class Sched, bool ALIGN_EPI = false, bool SP2 = false>
; __device__ __forceinline__ void gemm_phase(PG8_LAS unsigned char* lds, const Gemm g, const Sched& S, const Epi& E, const int tid) {
;     ...
;             PG8_WAIT_V(8); PG8_WAIT_L(0); PG8_BAR; PG8_MMA(1, 0, At, B0); PG8_MMA(1, 1, At, B1); PG8_BAR; PG8_SCHED;
;             PG8_LDB(B0, 1, 0); PG8_LDB(B1, 1, 1); PG8_SCHED; PG8_LDA(At, 1, 0); PG8_STAGE(PG8_SA(0, 1), a2 + hstep, voffA);
;             PG8_WAIT_V(8); PG8_WAIT_L(0); PG8_BAR; PG8_MMA(0, 0, At, B0); PG8_MMA(0, 1, At, B1); PG8_BAR; PG8_SCHED;
	s_setprio 1
	s_waitcnt lgkmcnt(0)
	v_mfma_f32_16x16x32_bf16 v[60:63], v[126:129], v[166:169], v[60:63]
	v_mfma_f32_16x16x32_bf16 v[56:59], v[142:145], v[166:169], v[56:59]
	v_mfma_f32_16x16x32_bf16 v[44:47], v[126:129], v[174:177], v[44:47]
	v_mfma_f32_16x16x32_bf16 v[40:43], v[142:145], v[174:177], v[40:43]
	v_mfma_f32_16x16x32_bf16 v[28:31], v[126:129], v[194:197], v[28:31]
	v_mfma_f32_16x16x32_bf16 v[24:27], v[142:145], v[194:197], v[24:27]
	v_mfma_f32_16x16x32_bf16 v[12:15], v[126:129], v[202:205], v[12:15]
	v_mfma_f32_16x16x32_bf16 v[8:11], v[142:145], v[202:205], v[8:11]
	v_mfma_f32_16x16x32_bf16 v[60:63], v[130:133], v[170:173], v[60:63]
	v_mfma_f32_16x16x32_bf16 v[56:59], v[146:149], v[170:173], v[56:59]
	v_mfma_f32_16x16x32_bf16 v[44:47], v[130:133], v[178:181], v[44:47]
	v_mfma_f32_16x16x32_bf16 v[40:43], v[146:149], v[178:181], v[40:43]
	v_mfma_f32_16x16x32_bf16 v[28:31], v[130:133], v[198:201], v[28:31]
	v_mfma_f32_16x16x32_bf16 v[24:27], v[146:149], v[198:201], v[24:27]
	v_mfma_f32_16x16x32_bf16 v[12:15], v[130:133], v[206:209], v[12:15]
	v_mfma_f32_16x16x32_bf16 v[8:11], v[146:149], v[206:209], v[8:11]
	s_setprio 0
	s_setprio 1
	v_mfma_f32_16x16x32_bf16 v[52:55], v[150:153], v[166:169], v[52:55]
	v_mfma_f32_16x16x32_bf16 v[48:51], v[158:161], v[166:169], v[48:51]
	v_mfma_f32_16x16x32_bf16 v[36:39], v[150:153], v[174:177], v[36:39]
	v_mfma_f32_16x16x32_bf16 v[32:35], v[158:161], v[174:177], v[32:35]
	v_mfma_f32_16x16x32_bf16 v[20:23], v[150:153], v[194:197], v[20:23]
	v_mfma_f32_16x16x32_bf16 v[16:19], v[158:161], v[194:197], v[16:19]
	v_mfma_f32_16x16x32_bf16 v[4:7], v[150:153], v[202:205], v[4:7]
	v_mfma_f32_16x16x32_bf16 v[0:3], v[158:161], v[202:205], v[0:3]
	v_mfma_f32_16x16x32_bf16 v[52:55], v[154:157], v[170:173], v[52:55]
	v_mfma_f32_16x16x32_bf16 v[48:51], v[162:165], v[170:173], v[48:51]
	v_mfma_f32_16x16x32_bf16 v[36:39], v[154:157], v[178:181], v[36:39]
	v_mfma_f32_16x16x32_bf16 v[32:35], v[162:165], v[178:181], v[32:35]
	v_mfma_f32_16x16x32_bf16 v[20:23], v[154:157], v[198:201], v[20:23]
	v_mfma_f32_16x16x32_bf16 v[16:19], v[162:165], v[198:201], v[16:19]
	v_mfma_f32_16x16x32_bf16 v[4:7], v[154:157], v[206:209], v[4:7]
	v_mfma_f32_16x16x32_bf16 v[0:3], v[162:165], v[206:209], v[0:3]
	s_setprio 0
	s_barrier
	s_add_i32 s77, 0, 0x18000
	s_add_i32 s78, 0, 0x1c000
	v_add_u32_e32 v146, s77, v233
	v_add_u32_e32 v162, s78, v233
	ds_read_b128 v[126:129], v146
	ds_read_b128 v[130:133], v146 offset:1024
	ds_read_b128 v[142:145], v146 offset:2048
	ds_read_b128 v[146:149], v146 offset:3072
	ds_read_b128 v[150:153], v162
	ds_read_b128 v[154:157], v162 offset:1024
	ds_read_b128 v[158:161], v162 offset:2048
	ds_read_b128 v[162:165], v162 offset:3072
	s_add_u32 s58, s58, 0x80000
	s_addc_u32 s59, s59, 0
	s_mov_b32 m0, s64
	v_lshl_add_u64 v[218:219], s[58:59], 0, v[188:189]
	ds_read_b128 v[166:169], v236 offset:32768
	ds_read_b128 v[170:173], v236 offset:33792
	ds_read_b128 v[174:177], v236 offset:34816
	ds_read_b128 v[178:181], v236 offset:35840
	ds_read_b128 v[194:197], v236 offset:36864
	ds_read_b128 v[198:201], v236 offset:37888
	ds_read_b128 v[202:205], v236 offset:38912
	ds_read_b128 v[206:209], v236 offset:39936
	global_load_lds_dwordx4 v[218:219], off
	v_lshl_add_u64 v[218:219], s[58:59], 0, v[186:187]
	s_mov_b32 m0, s65
	s_nop 0
	global_load_lds_dwordx4 v[218:219], off
	s_waitcnt vmcnt(8)
	s_waitcnt lgkmcnt(0)
	s_barrier
	s_setprio 1
	s_waitcnt lgkmcnt(0)
	v_mfma_f32_16x16x32_bf16 v[138:141], v[126:129], v[166:169], v[138:141]
	v_mfma_f32_16x16x32_bf16 v[134:137], v[142:145], v[166:169], v[134:137]
	v_mfma_f32_16x16x32_bf16 v[114:117], v[126:129], v[174:177], v[114:117]
	v_mfma_f32_16x16x32_bf16 v[110:113], v[142:145], v[174:177], v[110:113]
	v_mfma_f32_16x16x32_bf16 v[92:95], v[126:129], v[194:197], v[92:95]
	v_mfma_f32_16x16x32_bf16 v[88:91], v[142:145], v[194:197], v[88:91]
	v_mfma_f32_16x16x32_bf16 v[76:79], v[126:129], v[202:205], v[76:79]
	v_mfma_f32_16x16x32_bf16 v[72:75], v[142:145], v[202:205], v[72:75]
	v_mfma_f32_16x16x32_bf16 v[138:141], v[130:133], v[170:173], v[138:141]
	v_mfma_f32_16x16x32_bf16 v[134:137], v[146:149], v[170:173], v[134:137]
	v_mfma_f32_16x16x32_bf16 v[114:117], v[130:133], v[178:181], v[114:117]
	v_mfma_f32_16x16x32_bf16 v[110:113], v[146:149], v[178:181], v[110:113]
	v_mfma_f32_16x16x32_bf16 v[92:95], v[130:133], v[198:201], v[92:95]
	v_mfma_f32_16x16x32_bf16 v[88:91], v[146:149], v[198:201], v[88:91]
	v_mfma_f32_16x16x32_bf16 v[76:79], v[130:133], v[206:209], v[76:79]
	v_mfma_f32_16x16x32_bf16 v[72:75], v[146:149], v[206:209], v[72:75]
	s_setprio 0
	s_setprio 1
	v_mfma_f32_16x16x32_bf16 v[122:125], v[150:153], v[166:169], v[122:125]
	v_mfma_f32_16x16x32_bf16 v[118:121], v[158:161], v[166:169], v[118:121]
	v_mfma_f32_16x16x32_bf16 v[106:109], v[150:153], v[174:177], v[106:109]
	v_mfma_f32_16x16x32_bf16 v[102:105], v[158:161], v[174:177], v[102:105]
	v_mfma_f32_16x16x32_bf16 v[84:87], v[150:153], v[194:197], v[84:87]
	v_mfma_f32_16x16x32_bf16 v[80:83], v[158:161], v[194:197], v[80:83]
	v_mfma_f32_16x16x32_bf16 v[68:71], v[150:153], v[202:205], v[68:71]
	v_mfma_f32_16x16x32_bf16 v[64:67], v[158:161], v[202:205], v[64:67]
	v_mfma_f32_16x16x32_bf16 v[122:125], v[154:157], v[170:173], v[122:125]
	v_mfma_f32_16x16x32_bf16 v[118:121], v[162:165], v[170:173], v[118:121]
	v_mfma_f32_16x16x32_bf16 v[106:109], v[154:157], v[178:181], v[106:109]
	v_mfma_f32_16x16x32_bf16 v[102:105], v[162:165], v[178:181], v[102:105]
	v_mfma_f32_16x16x32_bf16 v[84:87], v[154:157], v[198:201], v[84:87]
	v_mfma_f32_16x16x32_bf16 v[80:83], v[162:165], v[198:201], v[80:83]
	v_mfma_f32_16x16x32_bf16 v[68:71], v[154:157], v[206:209], v[68:71]
	v_mfma_f32_16x16x32_bf16 v[64:67], v[162:165], v[206:209], v[64:67]
	s_setprio 0
	s_barrier
; #define PG8_GAS __attribute__((address_space(1)))
; #define PG8_STAGE(bufoff, gbase, voff) do { _Pragma("unroll") for (int _i = 0; _i < 2; ++_i) \
;         __builtin_amdgcn_global_load_lds((const unsigned*)((const char*)(gbase) + (voff)[_i]), (PG8_LAS unsigned*)(lds + (bufoff) + ldsw + _i * 8192), 16, 0, 0); } while (0)
; #define PG8_LDA(dst, b, h) do { _Pragma("unroll") for (int m = 0; m < 4; ++m) _Pragma("unroll") for (int k = 0; k < 2; ++k) dst[m][k] = *(const PG8_LAS bf16x8*)(lds + PG8_SA(b, h) + aoff + m * 2048 + k * 1024); } while (0)
; #define PG8_MMA(ai, bj, At, Bt) do { __builtin_amdgcn_s_setprio(1); _Pragma("unroll") for (int m = 0; m < 4; ++m) _Pragma("unroll") for (int n = 0; n < 2; ++n) _Pragma("unroll") for (int k = 0; k < 2; ++k) \
;         acc[ai][bj][m][n] = __builtin_amdgcn_mfma_f32_16x16x32_bf16(Bt[n][k], At[m][k], acc[ai][bj][m][n], 0, 0, 0); __builtin_amdgcn_s_setprio(0); } while (0)
; #define PG8_WAIT_V(n) asm volatile("s_waitcnt vmcnt(" #n ")" ::: "memory")
; #define PG8_WAIT_L(n) asm volatile("s_waitcnt lgkmcnt(" #n ")" ::: "memory")
; #define PG8_BAR __builtin_amdgcn_s_barrier()
;     __device__ __forceinline__ void operator()(const f32x4 (&acc)[2][2][4][2], const Unit& u, int wr, int wc, int fr, int fq) const {
;         const int row0 = u.pm * BM + wr * 64 + fr, col0 = u.pn * BM + wc * 32 + 8 * fq, lcol = u.pn * BM + (wc * 4 + fq) * 16;
; #pragma unroll
;         for (int ai = 0; ai < 2; ++ai) {
;             u32x4 L4[4], H4[4][2];
; #pragma unroll
;             for (int m = 0; m < 4; ++m) {
;                 const int row = row0 + ai * HALF + m * 16; const size_t off = (size_t)row * 2048 + col0, loff = (size_t)row * 2048 + lcol;
;                 L4[m] = *(const PG8_GAS u32x4*)(lin + loff); H4[m][0] = *(const PG8_GAS u32x4*)(hin + off); H4[m][1] = *(const PG8_GAS u32x4*)(hin + off + HALF);
;             }
; template <class Epi, class Sched, bool ALIGN_EPI = false, bool SP2 = false>
; __device__ __forceinline__ void gemm_phase(PG8_LAS unsigned char* lds, const Gemm g, const Sched& S, const Epi& E, const int tid) {
;     ...
;             PG8_LDA(At, 1, 1); PG8_STAGE(PG8_SB(1, 0), b3, voffB); PG8_STAGE(PG8_SB(1, 1), b3 + hstep, voffB); PG8_STAGE(PG8_SA(1, 0), a3, voffA);
;             PG8_WAIT_V(8); PG8_WAIT_L(0); PG8_BAR; PG8_MMA(1, 0, At, B0); PG8_MMA(1, 1, At, B1); PG8_BAR; PG8_SCHED;
	s_add_i32 s58, s77, s61
	v_lshl_add_u64 v[210:211], v[210:211], 0, s[28:29]
	s_mov_b32 m0, s58
	ds_read_b128 v[166:169], v236 offset:49152
	ds_read_b128 v[170:173], v236 offset:50176
	ds_read_b128 v[174:177], v236 offset:51200
	ds_read_b128 v[178:181], v236 offset:52224
	ds_read_b128 v[194:197], v236 offset:53248
	ds_read_b128 v[198:201], v236 offset:54272
	ds_read_b128 v[202:205], v236 offset:55296
	ds_read_b128 v[206:209], v236 offset:56320
	global_load_lds_dwordx4 v[210:211], off
	s_add_i32 m0, s58, 0x2000
	s_add_u32 s56, s56, 0x80080
	v_lshl_add_u64 v[210:211], v[212:213], 0, s[28:29]
	s_addc_u32 s57, s57, 0
	s_add_i32 s58, s78, s61
	global_load_lds_dwordx4 v[210:211], off
	v_lshl_add_u64 v[210:211], s[56:57], 0, v[96:97]
	s_mov_b32 m0, s58
	s_nop 0
	global_load_lds_dwordx4 v[210:211], off
	v_lshl_add_u64 v[210:211], s[56:57], 0, v[98:99]
	s_add_i32 m0, s58, 0x2000
	s_nop 0
	global_load_lds_dwordx4 v[210:211], off
	v_lshl_add_u64 v[210:211], v[214:215], 0, s[28:29]
	s_mov_b32 m0, s66
	s_nop 0
	global_load_lds_dwordx4 v[210:211], off
	v_lshl_add_u64 v[210:211], v[216:217], 0, s[28:29]
	s_mov_b32 m0, s67
	s_nop 0
	global_load_lds_dwordx4 v[210:211], off
	s_waitcnt vmcnt(8)
	s_waitcnt lgkmcnt(0)
	s_barrier
	s_setprio 1
	s_waitcnt lgkmcnt(0)
	v_mfma_f32_16x16x32_bf16 v[60:63], v[126:129], v[166:169], v[60:63]
	v_mfma_f32_16x16x32_bf16 v[56:59], v[142:145], v[166:169], v[56:59]
	v_mfma_f32_16x16x32_bf16 v[44:47], v[126:129], v[174:177], v[44:47]
	v_mfma_f32_16x16x32_bf16 v[40:43], v[142:145], v[174:177], v[40:43]
	v_mfma_f32_16x16x32_bf16 v[28:31], v[126:129], v[194:197], v[28:31]
	v_mfma_f32_16x16x32_bf16 v[24:27], v[142:145], v[194:197], v[24:27]
	v_mfma_f32_16x16x32_bf16 v[12:15], v[126:129], v[202:205], v[12:15]
	v_mfma_f32_16x16x32_bf16 v[8:11], v[142:145], v[202:205], v[8:11]
	v_mfma_f32_16x16x32_bf16 v[60:63], v[130:133], v[170:173], v[60:63]
	v_mfma_f32_16x16x32_bf16 v[56:59], v[146:149], v[170:173], v[56:59]
	v_mfma_f32_16x16x32_bf16 v[44:47], v[130:133], v[178:181], v[44:47]
	v_mfma_f32_16x16x32_bf16 v[40:43], v[146:149], v[178:181], v[40:43]
	v_mfma_f32_16x16x32_bf16 v[28:31], v[130:133], v[198:201], v[28:31]
	v_mfma_f32_16x16x32_bf16 v[24:27], v[146:149], v[198:201], v[24:27]
	v_mfma_f32_16x16x32_bf16 v[12:15], v[130:133], v[206:209], v[12:15]
	v_mfma_f32_16x16x32_bf16 v[8:11], v[146:149], v[206:209], v[8:11]
	s_setprio 0
	s_setprio 1
	v_mfma_f32_16x16x32_bf16 v[52:55], v[150:153], v[166:169], v[52:55]
	v_mfma_f32_16x16x32_bf16 v[48:51], v[158:161], v[166:169], v[48:51]
	v_mfma_f32_16x16x32_bf16 v[36:39], v[150:153], v[174:177], v[36:39]
	v_mfma_f32_16x16x32_bf16 v[32:35], v[158:161], v[174:177], v[32:35]
	v_mfma_f32_16x16x32_bf16 v[20:23], v[150:153], v[194:197], v[20:23]
	v_mfma_f32_16x16x32_bf16 v[16:19], v[158:161], v[194:197], v[16:19]
	v_mfma_f32_16x16x32_bf16 v[4:7], v[150:153], v[202:205], v[4:7]
	v_mfma_f32_16x16x32_bf16 v[0:3], v[158:161], v[202:205], v[0:3]
	v_mfma_f32_16x16x32_bf16 v[52:55], v[154:157], v[170:173], v[52:55]
	v_mfma_f32_16x16x32_bf16 v[48:51], v[162:165], v[170:173], v[48:51]
	v_mfma_f32_16x16x32_bf16 v[36:39], v[154:157], v[178:181], v[36:39]
	v_mfma_f32_16x16x32_bf16 v[32:35], v[162:165], v[178:181], v[32:35]
	v_mfma_f32_16x16x32_bf16 v[20:23], v[154:157], v[198:201], v[20:23]
	v_mfma_f32_16x16x32_bf16 v[16:19], v[162:165], v[198:201], v[16:19]
	v_mfma_f32_16x16x32_bf16 v[4:7], v[154:157], v[206:209], v[4:7]
	v_mfma_f32_16x16x32_bf16 v[0:3], v[162:165], v[206:209], v[0:3]
	s_setprio 0
	s_barrier
	s_add_i32 s76, s76, 2
	s_add_u32 s73, s73, 0x100
	s_addc_u32 s75, s75, 0
	s_add_u32 s54, s54, 0x100
	s_addc_u32 s55, s55, 0
	s_cmp_gt_u32 s76, 29
	s_cbranch_scc0 .LBB0_1199
	v_and_b32_e32 v127, 64, v228
	v_xor_b32_e32 v126, 16, v228
	v_add_u32_e32 v127, 64, v127
	v_cmp_lt_i32_e32 vcc, v126, v127
	s_lshl_b32 s47, s69, 8
	v_lshl_add_u32 v198, s70, 8, v101
	v_cndmask_b32_e32 v126, v228, v126, vcc
	v_or_b32_e32 v194, s47, v235
	v_lshlrev_b32_e32 v238, 2, v126
	v_xor_b32_e32 v126, 32, v228
	v_or_b32_e32 v196, s47, v234
	v_ashrrev_i32_e32 v195, 31, v194
	v_cmp_lt_i32_e32 vcc, v126, v127
	v_ashrrev_i32_e32 v199, 31, v198
	v_ashrrev_i32_e32 v197, 31, v196
	v_cndmask_b32_e32 v126, v228, v126, vcc
	v_lshl_add_u64 v[202:203], s[34:35], 0, v[194:195]
	v_lshlrev_b64 v[216:217], 11, v[198:199]
	v_lshlrev_b32_e32 v237, 2, v126
	v_lshlrev_b64 v[218:219], 1, v[196:197]
	v_lshl_add_u64 v[126:127], v[202:203], 0, v[216:217]
	v_lshl_add_u64 v[200:201], s[30:31], 0, v[218:219]
	global_load_dwordx4 v[170:173], v[126:127], off
	v_lshlrev_b64 v[220:221], 12, v[198:199]
	v_lshl_add_u64 v[126:127], v[200:201], 0, v[220:221]
	global_load_dwordx4 v[178:181], v[126:127], off
	global_load_dwordx4 v[174:177], v[126:127], off offset:256
	v_or_b32_e32 v212, 16, v198
	v_ashrrev_i32_e32 v213, 31, v212
	v_lshlrev_b64 v[214:215], 11, v[212:213]
	v_lshl_add_u64 v[126:127], v[202:203], 0, v[214:215]
	v_or_b32_e32 v208, 32, v198
	global_load_dwordx4 v[158:161], v[126:127], off
	v_lshlrev_b64 v[126:127], 12, v[212:213]
	v_ashrrev_i32_e32 v209, 31, v208
	v_lshl_add_u64 v[126:127], v[200:201], 0, v[126:127]
	v_lshlrev_b64 v[210:211], 11, v[208:209]
	global_load_dwordx4 v[166:169], v[126:127], off
	global_load_dwordx4 v[162:165], v[126:127], off offset:256
	v_lshl_add_u64 v[126:127], v[202:203], 0, v[210:211]
	v_or_b32_e32 v204, 48, v198
	global_load_dwordx4 v[146:149], v[126:127], off
	v_lshlrev_b64 v[126:127], 12, v[208:209]
	v_ashrrev_i32_e32 v205, 31, v204
	v_lshl_add_u64 v[126:127], v[200:201], 0, v[126:127]
	v_lshlrev_b64 v[206:207], 11, v[204:205]
	v_lshlrev_b64 v[130:131], 12, v[204:205]
	global_load_dwordx4 v[154:157], v[126:127], off
	global_load_dwordx4 v[150:153], v[126:127], off offset:256
	v_lshl_add_u64 v[126:127], v[202:203], 0, v[206:207]
	v_lshl_add_u64 v[130:131], v[200:201], 0, v[130:131]
	global_load_dwordx4 v[126:129], v[126:127], off
	s_nop 0
	global_load_dwordx4 v[142:145], v[130:131], off
	s_nop 0
	global_load_dwordx4 v[130:133], v[130:131], off offset:256
	v_mov_b32_e32 v225, v134
	v_mov_b32_e32 v243, v136
	v_mov_b32_e32 v242, v140
	s_waitcnt vmcnt(0)
; #define PG8_GAS __attribute__((address_space(1)))
; __device__ __forceinline__ float e_x24(unsigned h16, unsigned l8) { return __uint_as_float(((h16 - (l8 >> 7)) << 16) | (l8 << 8)); }
;     __device__ __forceinline__ void operator()(const f32x4 (&acc)[2][2][4][2], const Unit& u, int wr, int wc, int fr, int fq) const {
;     ...
;             for (int m = 0; m < 4; ++m) {
;                 const int row = row0 + ai * HALF + m * 16; const size_t off = (size_t)row * 2048 + col0, loff = (size_t)row * 2048 + lcol; float ss = 0.f;
;                 const u32x4 l4 = L4[m];
;                 u32x4 lo4;
; #pragma unroll
;                 for (int bj = 0; bj < 2; ++bj) {
;                     const u32x4 h4 = H4[m][bj];
;                     u32x4 ho;
; #pragma unroll
;                     for (int j = 0; j < 4; ++j) {
;                         const unsigned lw = l4[2 * bj + (j >> 1)], lb0 = (lw >> (16 * (j & 1))) & 0xffu, lb1 = (lw >> (16 * (j & 1) + 8)) & 0xffu;
;                         const float x0 = e_x24(h4[j] & 0xffffu, lb0) + acc[ai][bj][m][j >> 1][2 * (j & 1)] * scale, x1 = e_x24(h4[j] >> 16, lb1) + acc[ai][bj][m][j >> 1][2 * (j & 1) + 1] * scale;
;                         const unsigned b0 = __float_as_uint(x0), b1 = __float_as_uint(x1);
;                         ho[j] = ((b0 + 0x8000u) >> 16) | ((b1 + 0x8000u) & 0xffff0000u);
;                         const unsigned nb = ((b0 >> 8) & 0xffu) | (b1 & 0xff00u);
;                         if ((j & 1) == 0) lo4[2 * bj + (j >> 1)] = nb; else lo4[2 * bj + (j >> 1)] |= nb << 16;
;                         ss += x0 * x0 + x1 * x1;
;                     }
;                     *(PG8_GAS u32x4*)(hout + off + bj * HALF) = ho;
;                 }
;                 *(PG8_GAS u32x4*)(lout + loff) = lo4;
	v_lshrrev_b32_sdwa v182, v229, v171 dst_sel:DWORD dst_unused:UNUSED_PAD src0_sel:DWORD src1_sel:BYTE_0
	v_lshrrev_b32_sdwa v183, v229, v170 dst_sel:DWORD dst_unused:UNUSED_PAD src0_sel:DWORD src1_sel:BYTE_0
	v_sub_u32_sdwa v183, v178, v183 dst_sel:WORD_1 dst_unused:UNUSED_PAD src0_sel:DWORD src1_sel:DWORD
	v_sub_u32_sdwa v182, v180, v182 dst_sel:WORD_1 dst_unused:UNUSED_PAD src0_sel:DWORD src1_sel:DWORD
	v_lshlrev_b32_sdwa v222, v230, v171 dst_sel:DWORD dst_unused:UNUSED_PAD src0_sel:DWORD src1_sel:BYTE_0
	v_lshlrev_b32_sdwa v224, v230, v170 dst_sel:DWORD dst_unused:UNUSED_PAD src0_sel:DWORD src1_sel:BYTE_0
	v_or_b32_e32 v223, v182, v222
	v_or_b32_e32 v222, v183, v224
	v_mov_b32_e32 v224, v138
	v_pk_add_f32 v[222:223], v[224:225], v[222:223]
	v_lshlrev_b32_e32 v182, 1, v170
	v_add_u32_e32 v134, 0x8000, v222
	v_lshrrev_b32_e32 v138, 16, v134
	v_lshlrev_b32_e32 v134, 1, v171
	v_and_b32_e32 v134, 0x10000, v134
	v_and_b32_e32 v182, 0x10000, v182
	v_sub_u32_e32 v134, v180, v134
	v_sub_u32_e32 v178, v178, v182
	v_and_b32_e32 v134, 0xffff0000, v134
	v_and_b32_e32 v178, 0xffff0000, v178
	v_and_b32_e32 v180, 0xff00, v171
	v_and_b32_e32 v182, 0xff00, v170
	v_or_b32_e32 v225, v134, v180
	v_or_b32_e32 v224, v178, v182
	v_mov_b32_e32 v134, v139
	v_pk_add_f32 v[224:225], v[134:135], v[224:225]
	v_and_b32_sdwa v135, v171, s93 dst_sel:DWORD dst_unused:UNUSED_PAD src0_sel:WORD_1 src1_sel:DWORD
	v_and_b32_sdwa v178, v170, s93 dst_sel:DWORD dst_unused:UNUSED_PAD src0_sel:WORD_1 src1_sel:DWORD
	v_lshlrev_b32_sdwa v182, v231, v170 dst_sel:DWORD dst_unused:UNUSED_PAD src0_sel:DWORD src1_sel:BYTE_3
	v_lshlrev_b32_sdwa v136, v231, v171 dst_sel:DWORD dst_unused:UNUSED_PAD src0_sel:DWORD src1_sel:BYTE_3
	v_lshrrev_b32_e32 v180, 7, v178
	v_lshrrev_b32_e32 v183, 7, v135
	v_and_b32_e32 v136, 0x10000, v136
	v_and_b32_e32 v140, 0x10000, v182
	v_sub_u32_sdwa v180, v179, v180 dst_sel:WORD_1 dst_unused:UNUSED_PAD src0_sel:DWORD src1_sel:DWORD
	v_sub_u32_sdwa v183, v181, v183 dst_sel:WORD_1 dst_unused:UNUSED_PAD src0_sel:DWORD src1_sel:DWORD
	v_lshlrev_b32_e32 v135, 8, v135
	v_lshlrev_b32_e32 v178, 8, v178
	v_sub_u32_e32 v136, v181, v136
	v_sub_u32_e32 v140, v179, v140
	v_or_b32_e32 v241, v183, v135
	v_or_b32_e32 v240, v180, v178
	v_and_b32_e32 v136, 0xffff0000, v136
	v_and_b32_e32 v140, 0xffff0000, v140
	v_lshlrev_b32_sdwa v171, v230, v171 dst_sel:DWORD dst_unused:UNUSED_PAD src0_sel:DWORD src1_sel:BYTE_3
	v_lshlrev_b32_sdwa v170, v230, v170 dst_sel:DWORD dst_unused:UNUSED_PAD src0_sel:DWORD src1_sel:BYTE_3
	v_pk_add_f32 v[240:241], v[242:243], v[240:241]
	v_or_b32_e32 v171, v136, v171
	v_or_b32_e32 v170, v140, v170
	v_mov_b32_e32 v136, v141
	v_add_u32_e32 v135, 0x8000, v240
	v_pk_add_f32 v[140:141], v[136:137], v[170:171]
	v_lshrrev_b32_e32 v135, 16, v135
	v_add_u32_e32 v136, 0x8000, v140
	v_and_or_b32 v135, v136, s90, v135
	v_pk_mul_f32 v[136:137], v[140:141], v[140:141]
	v_add_u32_e32 v178, 0x8000, v141
	v_pk_fma_f32 v[170:171], v[240:241], v[240:241], v[136:137]
	v_add_u32_e32 v136, 0x8000, v223
	v_lshrrev_b32_e32 v136, 16, v136
	v_add_u32_e32 v137, 0x8000, v225
	v_and_or_b32 v136, v137, s90, v136
	v_add_u32_e32 v137, 0x8000, v241
	v_lshrrev_b32_e32 v137, 16, v137
	v_add_u32_e32 v134, 0x8000, v224
	v_and_or_b32 v137, v178, s90, v137
	v_lshl_add_u64 v[178:179], s[30:31], 0, v[220:221]
	v_and_or_b32 v134, v134, s90, v138
	v_lshl_add_u64 v[178:179], v[178:179], 0, v[218:219]
	global_store_dwordx4 v[178:179], v[134:137], off nt
	v_lshlrev_b32_sdwa v182, v231, v172 dst_sel:DWORD dst_unused:UNUSED_PAD src0_sel:DWORD src1_sel:BYTE_3
	v_mov_b32_e32 v219, v120
	v_lshrrev_b32_sdwa v134, v229, v173 dst_sel:DWORD dst_unused:UNUSED_PAD src0_sel:DWORD src1_sel:BYTE_0
	v_lshrrev_b32_sdwa v135, v229, v172 dst_sel:DWORD dst_unused:UNUSED_PAD src0_sel:DWORD src1_sel:BYTE_0
	v_sub_u32_sdwa v136, v174, v135 dst_sel:WORD_1 dst_unused:UNUSED_PAD src0_sel:DWORD src1_sel:DWORD
	v_sub_u32_sdwa v134, v176, v134 dst_sel:WORD_1 dst_unused:UNUSED_PAD src0_sel:DWORD src1_sel:DWORD
	v_lshlrev_b32_sdwa v135, v230, v173 dst_sel:DWORD dst_unused:UNUSED_PAD src0_sel:DWORD src1_sel:BYTE_0
	v_lshlrev_b32_sdwa v137, v230, v172 dst_sel:DWORD dst_unused:UNUSED_PAD src0_sel:DWORD src1_sel:BYTE_0
	v_or_b32_e32 v135, v134, v135
	v_or_b32_e32 v134, v136, v137
	v_mov_b32_e32 v136, v122
	v_mov_b32_e32 v137, v118
	v_pk_add_f32 v[134:135], v[136:137], v[134:135]
	v_lshlrev_b32_e32 v122, 1, v172
	v_add_u32_e32 v118, 0x8000, v134
	v_lshrrev_b32_e32 v180, 16, v118
	v_lshlrev_b32_e32 v118, 1, v173
	v_and_b32_e32 v118, 0x10000, v118
	v_and_b32_e32 v122, 0x10000, v122
	v_sub_u32_e32 v118, v176, v118
	v_sub_u32_e32 v122, v174, v122
	v_and_b32_e32 v118, 0xffff0000, v118
	v_and_b32_e32 v122, 0xffff0000, v122
	v_and_b32_e32 v136, 0xff00, v173
	v_and_b32_e32 v174, 0xff00, v172
	v_or_b32_e32 v137, v118, v136
	v_or_b32_e32 v136, v122, v174
	v_mov_b32_e32 v118, v123
	v_pk_add_f32 v[122:123], v[118:119], v[136:137]
	v_and_b32_sdwa v119, v173, s93 dst_sel:DWORD dst_unused:UNUSED_PAD src0_sel:WORD_1 src1_sel:DWORD
	v_add_u32_e32 v118, 0x8000, v122
	v_and_b32_sdwa v174, v172, s93 dst_sel:DWORD dst_unused:UNUSED_PAD src0_sel:WORD_1 src1_sel:DWORD
	v_lshlrev_b32_sdwa v120, v231, v173 dst_sel:DWORD dst_unused:UNUSED_PAD src0_sel:DWORD src1_sel:BYTE_3
	v_and_or_b32 v118, v118, s90, v180
	v_lshrrev_b32_e32 v176, 7, v174
	v_lshrrev_b32_e32 v180, 7, v119
	v_mov_b32_e32 v218, v124
	v_and_b32_e32 v120, 0x10000, v120
	v_and_b32_e32 v124, 0x10000, v182
	v_sub_u32_sdwa v176, v175, v176 dst_sel:WORD_1 dst_unused:UNUSED_PAD src0_sel:DWORD src1_sel:DWORD
	v_sub_u32_sdwa v180, v177, v180 dst_sel:WORD_1 dst_unused:UNUSED_PAD src0_sel:DWORD src1_sel:DWORD
; #define PG8_GAS __attribute__((address_space(1)))
; __device__ __forceinline__ float e_x24(unsigned h16, unsigned l8) { return __uint_as_float(((h16 - (l8 >> 7)) << 16) | (l8 << 8)); }
;     __device__ __forceinline__ void operator()(const f32x4 (&acc)[2][2][4][2], const Unit& u, int wr, int wc, int fr, int fq) const {
;     ...
;                 const int row = row0 + ai * HALF + m * 16; const size_t off = (size_t)row * 2048 + col0, loff = (size_t)row * 2048 + lcol; float ss = 0.f;
;                 const u32x4 l4 = L4[m];
;                 u32x4 lo4;
; #pragma unroll
;                 for (int bj = 0; bj < 2; ++bj) {
;                     const u32x4 h4 = H4[m][bj];
;                     u32x4 ho;
; #pragma unroll
;                     for (int j = 0; j < 4; ++j) {
;                         const unsigned lw = l4[2 * bj + (j >> 1)], lb0 = (lw >> (16 * (j & 1))) & 0xffu, lb1 = (lw >> (16 * (j & 1) + 8)) & 0xffu;
;                         const float x0 = e_x24(h4[j] & 0xffffu, lb0) + acc[ai][bj][m][j >> 1][2 * (j & 1)] * scale, x1 = e_x24(h4[j] >> 16, lb1) + acc[ai][bj][m][j >> 1][2 * (j & 1) + 1] * scale;
;                         const unsigned b0 = __float_as_uint(x0), b1 = __float_as_uint(x1);
;                         ho[j] = ((b0 + 0x8000u) >> 16) | ((b1 + 0x8000u) & 0xffff0000u);
;                         const unsigned nb = ((b0 >> 8) & 0xffu) | (b1 & 0xff00u);
;                         if ((j & 1) == 0) lo4[2 * bj + (j >> 1)] = nb; else lo4[2 * bj + (j >> 1)] |= nb << 16;
;                         ss += x0 * x0 + x1 * x1;
;                     }
;                     *(PG8_GAS u32x4*)(hout + off + bj * HALF) = ho;
;                 }
;                 *(PG8_GAS u32x4*)(lout + loff) = lo4;
;                 ss += __shfl_xor(ss, 16); ss += __shfl_xor(ss, 32);
;                 if (fq == 0) __hip_atomic_fetch_add((PG8_GAS unsigned long long*)(rowsq_out + row), (unsigned long long)(ss * 16777216.0f + 0.5f), __ATOMIC_RELAXED, __HIP_MEMORY_SCOPE_AGENT);
	v_lshlrev_b32_e32 v119, 8, v119
	v_lshlrev_b32_e32 v174, 8, v174
	v_sub_u32_e32 v120, v177, v120
	v_sub_u32_e32 v124, v175, v124
	v_or_b32_e32 v181, v180, v119
	v_or_b32_e32 v180, v176, v174
	v_and_b32_e32 v120, 0xffff0000, v120
	v_and_b32_e32 v124, 0xffff0000, v124
	v_lshlrev_b32_sdwa v173, v230, v173 dst_sel:DWORD dst_unused:UNUSED_PAD src0_sel:DWORD src1_sel:BYTE_3
	v_lshlrev_b32_sdwa v172, v230, v172 dst_sel:DWORD dst_unused:UNUSED_PAD src0_sel:DWORD src1_sel:BYTE_3
	v_pk_add_f32 v[180:181], v[218:219], v[180:181]
	v_or_b32_e32 v173, v120, v173
	v_or_b32_e32 v172, v124, v172
	v_mov_b32_e32 v120, v125
	v_add_u32_e32 v119, 0x8000, v180
	v_pk_add_f32 v[124:125], v[120:121], v[172:173]
	v_lshrrev_b32_e32 v119, 16, v119
	v_add_u32_e32 v120, 0x8000, v124
	v_pk_mul_f32 v[138:139], v[224:225], v[224:225]
	v_pk_mul_f32 v[136:137], v[122:123], v[122:123]
	v_and_or_b32 v119, v120, s90, v119
	v_pk_mul_f32 v[120:121], v[124:125], v[124:125]
	v_pk_fma_f32 v[138:139], v[222:223], v[222:223], v[138:139]
	v_pk_fma_f32 v[136:137], v[134:135], v[134:135], v[136:137]
	v_pk_fma_f32 v[172:173], v[180:181], v[180:181], v[120:121]
	v_add_u32_e32 v120, 0x8000, v135
	v_lshrrev_b32_e32 v134, 8, v134
	v_lshrrev_b32_e32 v120, 16, v120
	v_add_u32_e32 v121, 0x8000, v123
	v_perm_b32 v122, v122, v134, s94
	v_add_f32_e32 v134, v138, v170
	v_and_or_b32 v120, v121, s90, v120
	v_add_u32_e32 v121, 0x8000, v181
	v_add_f32_e32 v134, v139, v134
	v_lshrrev_b32_e32 v121, 16, v121
	v_add_u32_e32 v174, 0x8000, v125
	v_add_f32_e32 v134, v171, v134
	v_and_or_b32 v121, v174, s90, v121
	v_lshrrev_b32_e32 v174, 8, v181
	v_lshrrev_b32_e32 v175, 8, v180
	v_add_f32_e32 v134, v136, v134
	v_lshrrev_b32_e32 v176, 8, v241
	v_lshrrev_b32_e32 v177, 8, v240
	v_perm_b32 v124, v124, v175, s94
	v_perm_b32 v125, v125, v174, s94
	v_lshrrev_b32_e32 v135, 8, v135
	v_lshrrev_b32_e32 v174, 8, v223
	v_lshrrev_b32_e32 v175, 8, v222
	v_add_f32_e32 v134, v172, v134
	v_perm_b32 v140, v140, v177, s94
	v_perm_b32 v141, v141, v176, s94
	v_perm_b32 v175, v224, v175, s94
	v_perm_b32 v174, v225, v174, s94
	v_perm_b32 v123, v123, v135, s94
	v_add_f32_e32 v134, v137, v134
	global_store_dwordx4 v[178:179], v[118:121], off offset:256 nt
	v_lshl_or_b32 v125, v125, 16, v123
	v_lshl_or_b32 v124, v124, 16, v122
	v_lshl_add_u64 v[118:119], s[34:35], 0, v[216:217]
	v_lshl_or_b32 v123, v141, 16, v174
	v_lshl_or_b32 v122, v140, 16, v175
	v_add_f32_e32 v134, v173, v134
	v_lshl_add_u64 v[118:119], v[118:119], 0, v[194:195]
	global_store_dwordx4 v[118:119], v[122:125], off nt
	ds_bpermute_b32 v118, v238, v134
	s_waitcnt lgkmcnt(0)
	v_add_f32_e32 v118, v134, v118
	ds_bpermute_b32 v119, v237, v118
	s_and_saveexec_b64 s[54:55], s[40:41]
	s_mov_b32 s80, 0x4b800000
	s_cbranch_execz .LBB0_1202
	s_waitcnt lgkmcnt(0)
	v_add_f32_e32 v118, v118, v119
	v_fma_f32 v118, v118, s80, 0.5
	v_trunc_f32_e32 v118, v118
	v_mul_f32_e32 v119, 0x2f800000, v118
	v_floor_f32_e32 v119, v119
	v_fmac_f32_e32 v118, 0xcf800000, v119
	v_cvt_u32_f32_e32 v118, v118
	v_cvt_u32_f32_e32 v119, v119
	v_lshl_add_u64 v[120:121], v[198:199], 3, s[44:45]
	global_atomic_add_x2 v[120:121], v[118:119], off
.LBB0_1202:
	s_or_b64 exec, exec, s[54:55]
	v_lshrrev_b32_sdwa v118, v229, v159 dst_sel:DWORD dst_unused:UNUSED_PAD src0_sel:DWORD src1_sel:BYTE_0
	s_waitcnt lgkmcnt(0)
	v_lshrrev_b32_sdwa v119, v229, v158 dst_sel:DWORD dst_unused:UNUSED_PAD src0_sel:DWORD src1_sel:BYTE_0
	v_sub_u32_sdwa v120, v166, v119 dst_sel:WORD_1 dst_unused:UNUSED_PAD src0_sel:DWORD src1_sel:DWORD
	v_sub_u32_sdwa v118, v168, v118 dst_sel:WORD_1 dst_unused:UNUSED_PAD src0_sel:DWORD src1_sel:DWORD
	v_lshlrev_b32_sdwa v119, v230, v159 dst_sel:DWORD dst_unused:UNUSED_PAD src0_sel:DWORD src1_sel:BYTE_0
	v_lshlrev_b32_sdwa v121, v230, v158 dst_sel:DWORD dst_unused:UNUSED_PAD src0_sel:DWORD src1_sel:BYTE_0
	v_or_b32_e32 v119, v118, v119
	v_or_b32_e32 v118, v120, v121
	v_mov_b32_e32 v120, v114
	v_mov_b32_e32 v121, v110
	v_pk_add_f32 v[118:119], v[120:121], v[118:119]
	v_lshlrev_b32_e32 v122, 1, v159
	v_lshlrev_b32_e32 v123, 1, v158
	v_add_u32_e32 v110, 0x8000, v118
	v_lshrrev_b32_e32 v136, 16, v110
	v_and_b32_e32 v110, 0x10000, v122
	v_and_b32_e32 v114, 0x10000, v123
	v_sub_u32_e32 v110, v168, v110
	v_sub_u32_e32 v114, v166, v114
	v_and_b32_e32 v124, 0xff00, v159
	v_and_b32_e32 v125, 0xff00, v158
	v_and_b32_e32 v110, 0xffff0000, v110
	v_and_b32_e32 v114, 0xffff0000, v114
	v_or_b32_e32 v121, v110, v124
	v_or_b32_e32 v120, v114, v125
	v_mov_b32_e32 v110, v115
	v_and_b32_sdwa v122, v158, s93 dst_sel:DWORD dst_unused:UNUSED_PAD src0_sel:WORD_1 src1_sel:DWORD
	v_pk_add_f32 v[114:115], v[110:111], v[120:121]
	v_and_b32_sdwa v111, v159, s93 dst_sel:DWORD dst_unused:UNUSED_PAD src0_sel:WORD_1 src1_sel:DWORD
	v_lshrrev_b32_e32 v123, 7, v122
	v_lshlrev_b32_sdwa v134, v231, v158 dst_sel:DWORD dst_unused:UNUSED_PAD src0_sel:DWORD src1_sel:BYTE_3
	v_lshlrev_b32_sdwa v135, v231, v159 dst_sel:DWORD dst_unused:UNUSED_PAD src0_sel:DWORD src1_sel:BYTE_3
	v_lshrrev_b32_e32 v124, 7, v111
	v_sub_u32_sdwa v125, v167, v123 dst_sel:WORD_1 dst_unused:UNUSED_PAD src0_sel:DWORD src1_sel:DWORD
	v_lshlrev_b32_e32 v122, 8, v122
	v_sub_u32_sdwa v123, v169, v124 dst_sel:WORD_1 dst_unused:UNUSED_PAD src0_sel:DWORD src1_sel:DWORD
	v_lshlrev_b32_e32 v111, 8, v111
	v_or_b32_e32 v122, v125, v122
	v_mov_b32_e32 v124, v116
	v_mov_b32_e32 v125, v112
	v_and_b32_e32 v112, 0x10000, v135
	v_and_b32_e32 v116, 0x10000, v134
	v_or_b32_e32 v123, v123, v111
	v_sub_u32_e32 v112, v169, v112
	v_sub_u32_e32 v116, v167, v116
	v_pk_add_f32 v[122:123], v[124:125], v[122:123]
	v_and_b32_e32 v112, 0xffff0000, v112
	v_and_b32_e32 v116, 0xffff0000, v116
; #define PG8_GAS __attribute__((address_space(1)))
; __device__ __forceinline__ float e_x24(unsigned h16, unsigned l8) { return __uint_as_float(((h16 - (l8 >> 7)) << 16) | (l8 << 8)); }
;     __device__ __forceinline__ void operator()(const f32x4 (&acc)[2][2][4][2], const Unit& u, int wr, int wc, int fr, int fq) const {
;     ...
;             for (int m = 0; m < 4; ++m) {
;                 const int row = row0 + ai * HALF + m * 16; const size_t off = (size_t)row * 2048 + col0, loff = (size_t)row * 2048 + lcol; float ss = 0.f;
;                 const u32x4 l4 = L4[m];
;                 u32x4 lo4;
; #pragma unroll
;                 for (int bj = 0; bj < 2; ++bj) {
;                     const u32x4 h4 = H4[m][bj];
;                     u32x4 ho;
; #pragma unroll
;                     for (int j = 0; j < 4; ++j) {
;                         const unsigned lw = l4[2 * bj + (j >> 1)], lb0 = (lw >> (16 * (j & 1))) & 0xffu, lb1 = (lw >> (16 * (j & 1) + 8)) & 0xffu;
;                         const float x0 = e_x24(h4[j] & 0xffffu, lb0) + acc[ai][bj][m][j >> 1][2 * (j & 1)] * scale, x1 = e_x24(h4[j] >> 16, lb1) + acc[ai][bj][m][j >> 1][2 * (j & 1) + 1] * scale;
;                         const unsigned b0 = __float_as_uint(x0), b1 = __float_as_uint(x1);
;                         ho[j] = ((b0 + 0x8000u) >> 16) | ((b1 + 0x8000u) & 0xffff0000u);
;                         const unsigned nb = ((b0 >> 8) & 0xffu) | (b1 & 0xff00u);
;                         if ((j & 1) == 0) lo4[2 * bj + (j >> 1)] = nb; else lo4[2 * bj + (j >> 1)] |= nb << 16;
;                         ss += x0 * x0 + x1 * x1;
;                     }
;                     *(PG8_GAS u32x4*)(hout + off + bj * HALF) = ho;
;                 }
;                 *(PG8_GAS u32x4*)(lout + loff) = lo4;
;                 ss += __shfl_xor(ss, 16); ss += __shfl_xor(ss, 32);
;                 if (fq == 0) __hip_atomic_fetch_add((PG8_GAS unsigned long long*)(rowsq_out + row), (unsigned long long)(ss * 16777216.0f + 0.5f), __ATOMIC_RELAXED, __HIP_MEMORY_SCOPE_AGENT);
	v_lshlrev_b32_sdwa v124, v230, v159 dst_sel:DWORD dst_unused:UNUSED_PAD src0_sel:DWORD src1_sel:BYTE_3
	v_lshlrev_b32_sdwa v134, v230, v158 dst_sel:DWORD dst_unused:UNUSED_PAD src0_sel:DWORD src1_sel:BYTE_3
	v_or_b32_e32 v125, v112, v124
	v_or_b32_e32 v124, v116, v134
	v_mov_b32_e32 v112, v117
	v_add_u32_e32 v111, 0x8000, v122
	v_pk_add_f32 v[116:117], v[112:113], v[124:125]
	v_lshrrev_b32_e32 v111, 16, v111
	v_add_u32_e32 v112, 0x8000, v116
	v_and_or_b32 v111, v112, s90, v111
	v_pk_mul_f32 v[112:113], v[116:117], v[116:117]
	v_add_u32_e32 v134, 0x8000, v117
	v_pk_fma_f32 v[124:125], v[122:123], v[122:123], v[112:113]
	v_add_u32_e32 v112, 0x8000, v119
	v_lshrrev_b32_e32 v112, 16, v112
	v_add_u32_e32 v113, 0x8000, v115
	v_and_or_b32 v112, v113, s90, v112
	v_add_u32_e32 v113, 0x8000, v123
	v_lshrrev_b32_e32 v113, 16, v113
	v_add_u32_e32 v110, 0x8000, v114
	v_and_or_b32 v113, v134, s90, v113
	v_lshl_add_u64 v[134:135], v[214:215], 1, s[30:31]
	v_and_or_b32 v110, v110, s90, v136
	v_lshl_add_u64 v[134:135], v[196:197], 1, v[134:135]
	global_store_dwordx4 v[134:135], v[110:113], off nt
	v_lshlrev_b32_e32 v136, 1, v161
	v_lshlrev_b32_e32 v137, 1, v160
	v_lshrrev_b32_sdwa v110, v229, v161 dst_sel:DWORD dst_unused:UNUSED_PAD src0_sel:DWORD src1_sel:BYTE_0
	v_lshrrev_b32_sdwa v111, v229, v160 dst_sel:DWORD dst_unused:UNUSED_PAD src0_sel:DWORD src1_sel:BYTE_0
	v_sub_u32_sdwa v112, v162, v111 dst_sel:WORD_1 dst_unused:UNUSED_PAD src0_sel:DWORD src1_sel:DWORD
	v_sub_u32_sdwa v110, v164, v110 dst_sel:WORD_1 dst_unused:UNUSED_PAD src0_sel:DWORD src1_sel:DWORD
	v_lshlrev_b32_sdwa v111, v230, v161 dst_sel:DWORD dst_unused:UNUSED_PAD src0_sel:DWORD src1_sel:BYTE_0
	v_lshlrev_b32_sdwa v113, v230, v160 dst_sel:DWORD dst_unused:UNUSED_PAD src0_sel:DWORD src1_sel:BYTE_0
	v_or_b32_e32 v111, v110, v111
	v_or_b32_e32 v110, v112, v113
	v_mov_b32_e32 v112, v106
	v_mov_b32_e32 v113, v102
	v_pk_add_f32 v[110:111], v[112:113], v[110:111]
	v_and_b32_e32 v112, 0x10000, v137
	v_add_u32_e32 v102, 0x8000, v110
	v_lshrrev_b32_e32 v106, 16, v102
	v_and_b32_e32 v102, 0x10000, v136
	v_sub_u32_e32 v102, v164, v102
	v_sub_u32_e32 v112, v162, v112
	v_and_b32_e32 v138, 0xff00, v161
	v_and_b32_e32 v139, 0xff00, v160
	v_and_b32_e32 v102, 0xffff0000, v102
	v_and_b32_e32 v112, 0xffff0000, v112
	v_or_b32_e32 v113, v102, v138
	v_or_b32_e32 v112, v112, v139
	v_mov_b32_e32 v102, v107
	v_pk_add_f32 v[102:103], v[102:103], v[112:113]
	v_and_b32_sdwa v136, v160, s93 dst_sel:DWORD dst_unused:UNUSED_PAD src0_sel:WORD_1 src1_sel:DWORD
	v_add_u32_e32 v107, 0x8000, v102
	v_and_or_b32 v106, v107, s90, v106
	v_and_b32_sdwa v107, v161, s93 dst_sel:DWORD dst_unused:UNUSED_PAD src0_sel:WORD_1 src1_sel:DWORD
	v_lshrrev_b32_e32 v137, 7, v136
	v_lshrrev_b32_e32 v138, 7, v107
	v_sub_u32_sdwa v139, v163, v137 dst_sel:WORD_1 dst_unused:UNUSED_PAD src0_sel:DWORD src1_sel:DWORD
	v_sub_u32_sdwa v137, v165, v138 dst_sel:WORD_1 dst_unused:UNUSED_PAD src0_sel:DWORD src1_sel:DWORD
	v_lshlrev_b32_e32 v107, 8, v107
	v_lshlrev_b32_e32 v136, 8, v136
	v_or_b32_e32 v137, v137, v107
	v_or_b32_e32 v136, v139, v136
	v_mov_b32_e32 v138, v108
	v_mov_b32_e32 v139, v104
	v_pk_add_f32 v[136:137], v[138:139], v[136:137]
	v_lshlrev_b32_sdwa v140, v231, v160 dst_sel:DWORD dst_unused:UNUSED_PAD src0_sel:DWORD src1_sel:BYTE_3
	v_lshlrev_b32_sdwa v141, v231, v161 dst_sel:DWORD dst_unused:UNUSED_PAD src0_sel:DWORD src1_sel:BYTE_3
	v_add_u32_e32 v104, 0x8000, v136
	v_lshrrev_b32_e32 v107, 16, v104
	v_and_b32_e32 v104, 0x10000, v141
	v_and_b32_e32 v108, 0x10000, v140
	v_sub_u32_e32 v104, v165, v104
	v_sub_u32_e32 v108, v163, v108
	v_pk_mul_f32 v[120:121], v[114:115], v[114:115]
	v_pk_mul_f32 v[112:113], v[102:103], v[102:103]
	v_and_b32_e32 v104, 0xffff0000, v104
	v_and_b32_e32 v108, 0xffff0000, v108
	v_lshlrev_b32_sdwa v138, v230, v161 dst_sel:DWORD dst_unused:UNUSED_PAD src0_sel:DWORD src1_sel:BYTE_3
	v_lshlrev_b32_sdwa v140, v230, v160 dst_sel:DWORD dst_unused:UNUSED_PAD src0_sel:DWORD src1_sel:BYTE_3
	v_pk_fma_f32 v[120:121], v[118:119], v[118:119], v[120:121]
	v_pk_fma_f32 v[112:113], v[110:111], v[110:111], v[112:113]
	v_or_b32_e32 v139, v104, v138
	v_or_b32_e32 v138, v108, v140
	v_mov_b32_e32 v104, v109
	v_lshrrev_b32_e32 v110, 8, v110
	v_pk_add_f32 v[104:105], v[104:105], v[138:139]
	v_perm_b32 v102, v102, v110, s94
	v_add_f32_e32 v110, v120, v124
	v_add_u32_e32 v108, 0x8000, v104
	v_add_f32_e32 v110, v121, v110
	v_and_or_b32 v107, v108, s90, v107
	v_pk_mul_f32 v[108:109], v[104:105], v[104:105]
	v_add_f32_e32 v110, v125, v110
	v_pk_fma_f32 v[138:139], v[136:137], v[136:137], v[108:109]
	v_add_f32_e32 v110, v112, v110
	v_add_f32_e32 v110, v138, v110
	v_lshrrev_b32_e32 v118, 8, v118
	v_add_f32_e32 v110, v113, v110
	v_lshrrev_b32_e32 v119, 8, v119
	v_perm_b32 v114, v114, v118, s94
	v_add_f32_e32 v118, v139, v110
	v_perm_b32 v115, v115, v119, s94
	ds_bpermute_b32 v119, v238, v118
	v_add_u32_e32 v108, 0x8000, v111
	v_lshrrev_b32_e32 v108, 16, v108
	v_add_u32_e32 v109, 0x8000, v103
	v_lshrrev_b32_e32 v136, 8, v136
	v_and_or_b32 v108, v109, s90, v108
	v_add_u32_e32 v109, 0x8000, v137
	v_lshrrev_b32_e32 v137, 8, v137
	v_perm_b32 v104, v104, v136, s94
	v_lshrrev_b32_e32 v111, 8, v111
	v_add_u32_e32 v140, 0x8000, v105
	v_perm_b32 v105, v105, v137, s94
	v_perm_b32 v103, v103, v111, s94
	v_lshl_or_b32 v112, v104, 16, v102
	s_waitcnt lgkmcnt(0)
	v_add_f32_e32 v102, v118, v119
	v_lshl_or_b32 v113, v105, 16, v103
	ds_bpermute_b32 v103, v237, v102
	v_lshrrev_b32_e32 v123, 8, v123
	v_lshrrev_b32_e32 v122, 8, v122
	v_lshrrev_b32_e32 v109, 16, v109
	v_perm_b32 v116, v116, v122, s94
	v_perm_b32 v117, v117, v123, s94
	v_lshl_add_u64 v[104:105], s[34:35], 0, v[214:215]
	v_and_or_b32 v109, v140, s90, v109
	v_lshl_or_b32 v111, v117, 16, v115
	v_lshl_or_b32 v110, v116, 16, v114
	v_lshl_add_u64 v[104:105], v[104:105], 0, v[194:195]
	global_store_dwordx4 v[134:135], v[106:109], off offset:256 nt
	global_store_dwordx4 v[104:105], v[110:113], off nt
	s_and_saveexec_b64 s[54:55], s[40:41]
	s_cbranch_execz .LBB0_1204
	s_waitcnt lgkmcnt(0)
	v_add_f32_e32 v102, v102, v103
	v_fma_f32 v102, v102, s80, 0.5
	v_trunc_f32_e32 v102, v102
	v_mul_f32_e32 v103, 0x2f800000, v102
	v_floor_f32_e32 v103, v103
	v_fmac_f32_e32 v102, 0xcf800000, v103
	v_cvt_u32_f32_e32 v102, v102
	v_cvt_u32_f32_e32 v103, v103
	v_lshl_add_u64 v[104:105], v[212:213], 3, s[44:45]
	global_atomic_add_x2 v[104:105], v[102:103], off
; #define PG8_GAS __attribute__((address_space(1)))
; __device__ __forceinline__ float e_x24(unsigned h16, unsigned l8) { return __uint_as_float(((h16 - (l8 >> 7)) << 16) | (l8 << 8)); }
;     __device__ __forceinline__ void operator()(const f32x4 (&acc)[2][2][4][2], const Unit& u, int wr, int wc, int fr, int fq) const {
;     ...
;             for (int m = 0; m < 4; ++m) {
;                 const int row = row0 + ai * HALF + m * 16; const size_t off = (size_t)row * 2048 + col0, loff = (size_t)row * 2048 + lcol; float ss = 0.f;
;                 const u32x4 l4 = L4[m];
;                 u32x4 lo4;
; #pragma unroll
;                 for (int bj = 0; bj < 2; ++bj) {
;                     const u32x4 h4 = H4[m][bj];
;                     u32x4 ho;
; #pragma unroll
;                     for (int j = 0; j < 4; ++j) {
;                         const unsigned lw = l4[2 * bj + (j >> 1)], lb0 = (lw >> (16 * (j & 1))) & 0xffu, lb1 = (lw >> (16 * (j & 1) + 8)) & 0xffu;
;                         const float x0 = e_x24(h4[j] & 0xffffu, lb0) + acc[ai][bj][m][j >> 1][2 * (j & 1)] * scale, x1 = e_x24(h4[j] >> 16, lb1) + acc[ai][bj][m][j >> 1][2 * (j & 1) + 1] * scale;
;                         const unsigned b0 = __float_as_uint(x0), b1 = __float_as_uint(x1);
;                         ho[j] = ((b0 + 0x8000u) >> 16) | ((b1 + 0x8000u) & 0xffff0000u);
;                         const unsigned nb = ((b0 >> 8) & 0xffu) | (b1 & 0xff00u);
;                         if ((j & 1) == 0) lo4[2 * bj + (j >> 1)] = nb; else lo4[2 * bj + (j >> 1)] |= nb << 16;
;                         ss += x0 * x0 + x1 * x1;
;                     }
;                     *(PG8_GAS u32x4*)(hout + off + bj * HALF) = ho;
;                 }
;                 *(PG8_GAS u32x4*)(lout + loff) = lo4;
;                 ss += __shfl_xor(ss, 16); ss += __shfl_xor(ss, 32);
;                 if (fq == 0) __hip_atomic_fetch_add((PG8_GAS unsigned long long*)(rowsq_out + row), (unsigned long long)(ss * 16777216.0f + 0.5f), __ATOMIC_RELAXED, __HIP_MEMORY_SCOPE_AGENT);
.LBB0_1204:
	s_or_b64 exec, exec, s[54:55]
	v_lshrrev_b32_sdwa v102, v229, v147 dst_sel:DWORD dst_unused:UNUSED_PAD src0_sel:DWORD src1_sel:BYTE_0
	s_waitcnt lgkmcnt(0)
	v_lshrrev_b32_sdwa v103, v229, v146 dst_sel:DWORD dst_unused:UNUSED_PAD src0_sel:DWORD src1_sel:BYTE_0
	v_sub_u32_sdwa v104, v154, v103 dst_sel:WORD_1 dst_unused:UNUSED_PAD src0_sel:DWORD src1_sel:DWORD
	v_sub_u32_sdwa v102, v156, v102 dst_sel:WORD_1 dst_unused:UNUSED_PAD src0_sel:DWORD src1_sel:DWORD
	v_lshlrev_b32_sdwa v103, v230, v147 dst_sel:DWORD dst_unused:UNUSED_PAD src0_sel:DWORD src1_sel:BYTE_0
	v_lshlrev_b32_sdwa v105, v230, v146 dst_sel:DWORD dst_unused:UNUSED_PAD src0_sel:DWORD src1_sel:BYTE_0
	v_or_b32_e32 v103, v102, v103
	v_or_b32_e32 v102, v104, v105
	v_mov_b32_e32 v104, v92
	v_mov_b32_e32 v105, v88
	v_pk_add_f32 v[102:103], v[104:105], v[102:103]
	v_lshlrev_b32_e32 v106, 1, v147
	v_lshlrev_b32_e32 v107, 1, v146
	v_add_u32_e32 v88, 0x8000, v102
	v_lshrrev_b32_e32 v112, 16, v88
	v_and_b32_e32 v88, 0x10000, v106
	v_and_b32_e32 v92, 0x10000, v107
	v_sub_u32_e32 v88, v156, v88
	v_sub_u32_e32 v92, v154, v92
	v_and_b32_e32 v108, 0xff00, v147
	v_and_b32_e32 v109, 0xff00, v146
	v_and_b32_e32 v88, 0xffff0000, v88
	v_and_b32_e32 v92, 0xffff0000, v92
	v_or_b32_e32 v105, v88, v108
	v_or_b32_e32 v104, v92, v109
	v_mov_b32_e32 v88, v93
	v_and_b32_sdwa v106, v146, s93 dst_sel:DWORD dst_unused:UNUSED_PAD src0_sel:WORD_1 src1_sel:DWORD
	v_pk_add_f32 v[92:93], v[88:89], v[104:105]
	v_and_b32_sdwa v89, v147, s93 dst_sel:DWORD dst_unused:UNUSED_PAD src0_sel:WORD_1 src1_sel:DWORD
	v_lshrrev_b32_e32 v107, 7, v106
	v_lshlrev_b32_sdwa v110, v231, v146 dst_sel:DWORD dst_unused:UNUSED_PAD src0_sel:DWORD src1_sel:BYTE_3
	v_lshlrev_b32_sdwa v111, v231, v147 dst_sel:DWORD dst_unused:UNUSED_PAD src0_sel:DWORD src1_sel:BYTE_3
	v_lshrrev_b32_e32 v108, 7, v89
	v_sub_u32_sdwa v109, v155, v107 dst_sel:WORD_1 dst_unused:UNUSED_PAD src0_sel:DWORD src1_sel:DWORD
	v_lshlrev_b32_e32 v106, 8, v106
	v_sub_u32_sdwa v107, v157, v108 dst_sel:WORD_1 dst_unused:UNUSED_PAD src0_sel:DWORD src1_sel:DWORD
	v_lshlrev_b32_e32 v89, 8, v89
	v_or_b32_e32 v106, v109, v106
	v_mov_b32_e32 v108, v94
	v_mov_b32_e32 v109, v90
	v_and_b32_e32 v90, 0x10000, v111
	v_and_b32_e32 v94, 0x10000, v110
	v_or_b32_e32 v107, v107, v89
	v_sub_u32_e32 v90, v157, v90
	v_sub_u32_e32 v94, v155, v94
	v_pk_add_f32 v[106:107], v[108:109], v[106:107]
	v_and_b32_e32 v90, 0xffff0000, v90
	v_and_b32_e32 v94, 0xffff0000, v94
	v_lshlrev_b32_sdwa v108, v230, v147 dst_sel:DWORD dst_unused:UNUSED_PAD src0_sel:DWORD src1_sel:BYTE_3
	v_lshlrev_b32_sdwa v110, v230, v146 dst_sel:DWORD dst_unused:UNUSED_PAD src0_sel:DWORD src1_sel:BYTE_3
	v_or_b32_e32 v109, v90, v108
	v_or_b32_e32 v108, v94, v110
	v_mov_b32_e32 v90, v95
	v_add_u32_e32 v89, 0x8000, v106
	v_pk_add_f32 v[94:95], v[90:91], v[108:109]
	v_lshrrev_b32_e32 v89, 16, v89
	v_add_u32_e32 v90, 0x8000, v94
	v_and_or_b32 v89, v90, s90, v89
	v_pk_mul_f32 v[90:91], v[94:95], v[94:95]
	v_add_u32_e32 v110, 0x8000, v95
	v_pk_fma_f32 v[108:109], v[106:107], v[106:107], v[90:91]
	v_add_u32_e32 v90, 0x8000, v103
	v_lshrrev_b32_e32 v90, 16, v90
	v_add_u32_e32 v91, 0x8000, v93
	v_and_or_b32 v90, v91, s90, v90
	v_add_u32_e32 v91, 0x8000, v107
	v_lshrrev_b32_e32 v91, 16, v91
	v_add_u32_e32 v88, 0x8000, v92
	v_and_or_b32 v91, v110, s90, v91
	v_lshl_add_u64 v[110:111], v[210:211], 1, s[30:31]
	v_and_or_b32 v88, v88, s90, v112
	v_lshl_add_u64 v[110:111], v[196:197], 1, v[110:111]
	global_store_dwordx4 v[110:111], v[88:91], off nt
	v_lshlrev_b32_e32 v112, 1, v149
	v_lshlrev_b32_e32 v113, 1, v148
	v_lshrrev_b32_sdwa v88, v229, v149 dst_sel:DWORD dst_unused:UNUSED_PAD src0_sel:DWORD src1_sel:BYTE_0
	v_lshrrev_b32_sdwa v89, v229, v148 dst_sel:DWORD dst_unused:UNUSED_PAD src0_sel:DWORD src1_sel:BYTE_0
	v_sub_u32_sdwa v90, v150, v89 dst_sel:WORD_1 dst_unused:UNUSED_PAD src0_sel:DWORD src1_sel:DWORD
	v_sub_u32_sdwa v88, v152, v88 dst_sel:WORD_1 dst_unused:UNUSED_PAD src0_sel:DWORD src1_sel:DWORD
	v_lshlrev_b32_sdwa v89, v230, v149 dst_sel:DWORD dst_unused:UNUSED_PAD src0_sel:DWORD src1_sel:BYTE_0
	v_lshlrev_b32_sdwa v91, v230, v148 dst_sel:DWORD dst_unused:UNUSED_PAD src0_sel:DWORD src1_sel:BYTE_0
	v_or_b32_e32 v89, v88, v89
	v_or_b32_e32 v88, v90, v91
	v_mov_b32_e32 v90, v84
	v_mov_b32_e32 v91, v80
	v_pk_add_f32 v[88:89], v[90:91], v[88:89]
	v_and_b32_e32 v90, 0x10000, v113
	v_add_u32_e32 v80, 0x8000, v88
	v_lshrrev_b32_e32 v84, 16, v80
	v_and_b32_e32 v80, 0x10000, v112
	v_sub_u32_e32 v80, v152, v80
	v_sub_u32_e32 v90, v150, v90
	v_and_b32_e32 v114, 0xff00, v149
	v_and_b32_e32 v115, 0xff00, v148
	v_and_b32_e32 v80, 0xffff0000, v80
	v_and_b32_e32 v90, 0xffff0000, v90
	v_or_b32_e32 v91, v80, v114
	v_or_b32_e32 v90, v90, v115
	v_mov_b32_e32 v80, v85
	v_pk_add_f32 v[80:81], v[80:81], v[90:91]
	v_and_b32_sdwa v112, v148, s93 dst_sel:DWORD dst_unused:UNUSED_PAD src0_sel:WORD_1 src1_sel:DWORD
	v_add_u32_e32 v85, 0x8000, v80
	v_and_or_b32 v84, v85, s90, v84
	v_and_b32_sdwa v85, v149, s93 dst_sel:DWORD dst_unused:UNUSED_PAD src0_sel:WORD_1 src1_sel:DWORD
	v_lshrrev_b32_e32 v113, 7, v112
	v_lshrrev_b32_e32 v114, 7, v85
	v_sub_u32_sdwa v115, v151, v113 dst_sel:WORD_1 dst_unused:UNUSED_PAD src0_sel:DWORD src1_sel:DWORD
	v_sub_u32_sdwa v113, v153, v114 dst_sel:WORD_1 dst_unused:UNUSED_PAD src0_sel:DWORD src1_sel:DWORD
	v_lshlrev_b32_e32 v85, 8, v85
	v_lshlrev_b32_e32 v112, 8, v112
	v_or_b32_e32 v113, v113, v85
	v_or_b32_e32 v112, v115, v112
	v_mov_b32_e32 v114, v86
	v_mov_b32_e32 v115, v82
	v_pk_add_f32 v[112:113], v[114:115], v[112:113]
	v_lshlrev_b32_sdwa v116, v231, v148 dst_sel:DWORD dst_unused:UNUSED_PAD src0_sel:DWORD src1_sel:BYTE_3
; #define PG8_GAS __attribute__((address_space(1)))
; __device__ __forceinline__ float e_x24(unsigned h16, unsigned l8) { return __uint_as_float(((h16 - (l8 >> 7)) << 16) | (l8 << 8)); }
;     __device__ __forceinline__ void operator()(const f32x4 (&acc)[2][2][4][2], const Unit& u, int wr, int wc, int fr, int fq) const {
;     ...
;             for (int m = 0; m < 4; ++m) {
;                 const int row = row0 + ai * HALF + m * 16; const size_t off = (size_t)row * 2048 + col0, loff = (size_t)row * 2048 + lcol; float ss = 0.f;
;                 const u32x4 l4 = L4[m];
;                 u32x4 lo4;
; #pragma unroll
;                 for (int bj = 0; bj < 2; ++bj) {
;                     const u32x4 h4 = H4[m][bj];
;                     u32x4 ho;
; #pragma unroll
;                     for (int j = 0; j < 4; ++j) {
;                         const unsigned lw = l4[2 * bj + (j >> 1)], lb0 = (lw >> (16 * (j & 1))) & 0xffu, lb1 = (lw >> (16 * (j & 1) + 8)) & 0xffu;
;                         const float x0 = e_x24(h4[j] & 0xffffu, lb0) + acc[ai][bj][m][j >> 1][2 * (j & 1)] * scale, x1 = e_x24(h4[j] >> 16, lb1) + acc[ai][bj][m][j >> 1][2 * (j & 1) + 1] * scale;
;                         const unsigned b0 = __float_as_uint(x0), b1 = __float_as_uint(x1);
;                         ho[j] = ((b0 + 0x8000u) >> 16) | ((b1 + 0x8000u) & 0xffff0000u);
;                         const unsigned nb = ((b0 >> 8) & 0xffu) | (b1 & 0xff00u);
;                         if ((j & 1) == 0) lo4[2 * bj + (j >> 1)] = nb; else lo4[2 * bj + (j >> 1)] |= nb << 16;
;                         ss += x0 * x0 + x1 * x1;
;                     }
;                     *(PG8_GAS u32x4*)(hout + off + bj * HALF) = ho;
;                 }
;                 *(PG8_GAS u32x4*)(lout + loff) = lo4;
;                 ss += __shfl_xor(ss, 16); ss += __shfl_xor(ss, 32);
;                 if (fq == 0) __hip_atomic_fetch_add((PG8_GAS unsigned long long*)(rowsq_out + row), (unsigned long long)(ss * 16777216.0f + 0.5f), __ATOMIC_RELAXED, __HIP_MEMORY_SCOPE_AGENT);
	v_lshlrev_b32_sdwa v117, v231, v149 dst_sel:DWORD dst_unused:UNUSED_PAD src0_sel:DWORD src1_sel:BYTE_3
	v_add_u32_e32 v82, 0x8000, v112
	v_lshrrev_b32_e32 v85, 16, v82
	v_and_b32_e32 v82, 0x10000, v117
	v_and_b32_e32 v86, 0x10000, v116
	v_sub_u32_e32 v82, v153, v82
	v_sub_u32_e32 v86, v151, v86
	v_pk_mul_f32 v[104:105], v[92:93], v[92:93]
	v_pk_mul_f32 v[90:91], v[80:81], v[80:81]
	v_and_b32_e32 v82, 0xffff0000, v82
	v_and_b32_e32 v86, 0xffff0000, v86
	v_lshlrev_b32_sdwa v114, v230, v149 dst_sel:DWORD dst_unused:UNUSED_PAD src0_sel:DWORD src1_sel:BYTE_3
	v_lshlrev_b32_sdwa v116, v230, v148 dst_sel:DWORD dst_unused:UNUSED_PAD src0_sel:DWORD src1_sel:BYTE_3
	v_pk_fma_f32 v[104:105], v[102:103], v[102:103], v[104:105]
	v_pk_fma_f32 v[90:91], v[88:89], v[88:89], v[90:91]
	v_or_b32_e32 v115, v82, v114
	v_or_b32_e32 v114, v86, v116
	v_mov_b32_e32 v82, v87
	v_lshrrev_b32_e32 v88, 8, v88
	v_pk_add_f32 v[82:83], v[82:83], v[114:115]
	v_perm_b32 v80, v80, v88, s94
	v_add_f32_e32 v88, v104, v108
	v_add_u32_e32 v86, 0x8000, v82
	v_add_f32_e32 v88, v105, v88
	v_and_or_b32 v85, v86, s90, v85
	v_pk_mul_f32 v[86:87], v[82:83], v[82:83]
	v_add_f32_e32 v88, v109, v88
	v_pk_fma_f32 v[114:115], v[112:113], v[112:113], v[86:87]
	v_add_f32_e32 v88, v90, v88
	v_add_f32_e32 v88, v114, v88
	v_lshrrev_b32_e32 v102, 8, v102
	v_add_f32_e32 v88, v91, v88
	v_lshrrev_b32_e32 v103, 8, v103
	v_perm_b32 v92, v92, v102, s94
	v_add_f32_e32 v102, v115, v88
	v_perm_b32 v93, v93, v103, s94
	ds_bpermute_b32 v103, v238, v102
	v_add_u32_e32 v86, 0x8000, v89
	v_lshrrev_b32_e32 v86, 16, v86
	v_add_u32_e32 v87, 0x8000, v81
	v_lshrrev_b32_e32 v112, 8, v112
	v_and_or_b32 v86, v87, s90, v86
	v_add_u32_e32 v87, 0x8000, v113
	v_lshrrev_b32_e32 v113, 8, v113
	v_perm_b32 v82, v82, v112, s94
	v_lshrrev_b32_e32 v89, 8, v89
	v_add_u32_e32 v116, 0x8000, v83
	v_perm_b32 v83, v83, v113, s94
	v_perm_b32 v81, v81, v89, s94
	v_lshl_or_b32 v90, v82, 16, v80
	s_waitcnt lgkmcnt(0)
	v_add_f32_e32 v80, v102, v103
	v_lshl_or_b32 v91, v83, 16, v81
	ds_bpermute_b32 v81, v237, v80
	v_lshrrev_b32_e32 v107, 8, v107
	v_lshrrev_b32_e32 v106, 8, v106
	v_lshrrev_b32_e32 v87, 16, v87
	v_perm_b32 v94, v94, v106, s94
	v_perm_b32 v95, v95, v107, s94
	v_lshl_add_u64 v[82:83], s[34:35], 0, v[210:211]
	v_and_or_b32 v87, v116, s90, v87
	v_lshl_or_b32 v89, v95, 16, v93
	v_lshl_or_b32 v88, v94, 16, v92
	v_lshl_add_u64 v[82:83], v[82:83], 0, v[194:195]
	global_store_dwordx4 v[110:111], v[84:87], off offset:256 nt
	global_store_dwordx4 v[82:83], v[88:91], off nt
	s_and_saveexec_b64 s[54:55], s[40:41]
	s_cbranch_execz .LBB0_1206
	s_waitcnt lgkmcnt(0)
	v_add_f32_e32 v80, v80, v81
	v_fma_f32 v80, v80, s80, 0.5
	v_trunc_f32_e32 v80, v80
	v_mul_f32_e32 v81, 0x2f800000, v80
	v_floor_f32_e32 v81, v81
	v_fmac_f32_e32 v80, 0xcf800000, v81
	v_cvt_u32_f32_e32 v80, v80
	v_cvt_u32_f32_e32 v81, v81
	v_lshl_add_u64 v[82:83], v[208:209], 3, s[44:45]
	global_atomic_add_x2 v[82:83], v[80:81], off
.LBB0_1206:
	s_or_b64 exec, exec, s[54:55]
	v_lshrrev_b32_sdwa v80, v229, v127 dst_sel:DWORD dst_unused:UNUSED_PAD src0_sel:DWORD src1_sel:BYTE_0
	s_waitcnt lgkmcnt(0)
	v_lshrrev_b32_sdwa v81, v229, v126 dst_sel:DWORD dst_unused:UNUSED_PAD src0_sel:DWORD src1_sel:BYTE_0
	v_sub_u32_sdwa v82, v142, v81 dst_sel:WORD_1 dst_unused:UNUSED_PAD src0_sel:DWORD src1_sel:DWORD
	v_sub_u32_sdwa v80, v144, v80 dst_sel:WORD_1 dst_unused:UNUSED_PAD src0_sel:DWORD src1_sel:DWORD
	v_lshlrev_b32_sdwa v81, v230, v127 dst_sel:DWORD dst_unused:UNUSED_PAD src0_sel:DWORD src1_sel:BYTE_0
	v_lshlrev_b32_sdwa v83, v230, v126 dst_sel:DWORD dst_unused:UNUSED_PAD src0_sel:DWORD src1_sel:BYTE_0
	v_or_b32_e32 v81, v80, v81
	v_or_b32_e32 v80, v82, v83
	v_mov_b32_e32 v82, v76
	v_mov_b32_e32 v83, v72
	v_pk_add_f32 v[80:81], v[82:83], v[80:81]
	v_lshlrev_b32_e32 v84, 1, v127
	v_lshlrev_b32_e32 v85, 1, v126
	v_add_u32_e32 v72, 0x8000, v80
	v_lshrrev_b32_e32 v90, 16, v72
	v_and_b32_e32 v72, 0x10000, v84
	v_and_b32_e32 v76, 0x10000, v85
	v_sub_u32_e32 v72, v144, v72
	v_sub_u32_e32 v76, v142, v76
	v_and_b32_e32 v86, 0xff00, v127
	v_and_b32_e32 v87, 0xff00, v126
	v_and_b32_e32 v72, 0xffff0000, v72
	v_and_b32_e32 v76, 0xffff0000, v76
	v_or_b32_e32 v83, v72, v86
	v_or_b32_e32 v82, v76, v87
	v_mov_b32_e32 v72, v77
	v_and_b32_sdwa v84, v126, s93 dst_sel:DWORD dst_unused:UNUSED_PAD src0_sel:WORD_1 src1_sel:DWORD
	v_pk_add_f32 v[76:77], v[72:73], v[82:83]
	v_and_b32_sdwa v73, v127, s93 dst_sel:DWORD dst_unused:UNUSED_PAD src0_sel:WORD_1 src1_sel:DWORD
	v_lshrrev_b32_e32 v85, 7, v84
	v_lshlrev_b32_sdwa v88, v231, v126 dst_sel:DWORD dst_unused:UNUSED_PAD src0_sel:DWORD src1_sel:BYTE_3
	v_lshlrev_b32_sdwa v89, v231, v127 dst_sel:DWORD dst_unused:UNUSED_PAD src0_sel:DWORD src1_sel:BYTE_3
	v_lshrrev_b32_e32 v86, 7, v73
	v_sub_u32_sdwa v87, v143, v85 dst_sel:WORD_1 dst_unused:UNUSED_PAD src0_sel:DWORD src1_sel:DWORD
	v_lshlrev_b32_e32 v84, 8, v84
	v_sub_u32_sdwa v85, v145, v86 dst_sel:WORD_1 dst_unused:UNUSED_PAD src0_sel:DWORD src1_sel:DWORD
	v_lshlrev_b32_e32 v73, 8, v73
	v_or_b32_e32 v84, v87, v84
	v_mov_b32_e32 v86, v78
	v_mov_b32_e32 v87, v74
	v_and_b32_e32 v74, 0x10000, v89
	v_and_b32_e32 v78, 0x10000, v88
	v_or_b32_e32 v85, v85, v73
	v_sub_u32_e32 v74, v145, v74
	v_sub_u32_e32 v78, v143, v78
	v_pk_add_f32 v[84:85], v[86:87], v[84:85]
	v_and_b32_e32 v74, 0xffff0000, v74
	v_and_b32_e32 v78, 0xffff0000, v78
	v_lshlrev_b32_sdwa v86, v230, v127 dst_sel:DWORD dst_unused:UNUSED_PAD src0_sel:DWORD src1_sel:BYTE_3
	v_lshlrev_b32_sdwa v88, v230, v126 dst_sel:DWORD dst_unused:UNUSED_PAD src0_sel:DWORD src1_sel:BYTE_3
	v_or_b32_e32 v87, v74, v86
	v_or_b32_e32 v86, v78, v88
	v_mov_b32_e32 v74, v79
; #define PG8_GAS __attribute__((address_space(1)))
; __device__ __forceinline__ float e_x24(unsigned h16, unsigned l8) { return __uint_as_float(((h16 - (l8 >> 7)) << 16) | (l8 << 8)); }
;     __device__ __forceinline__ void operator()(const f32x4 (&acc)[2][2][4][2], const Unit& u, int wr, int wc, int fr, int fq) const {
;     ...
;             for (int m = 0; m < 4; ++m) {
;                 const int row = row0 + ai * HALF + m * 16; const size_t off = (size_t)row * 2048 + col0, loff = (size_t)row * 2048 + lcol; float ss = 0.f;
;                 const u32x4 l4 = L4[m];
;                 u32x4 lo4;
; #pragma unroll
;                 for (int bj = 0; bj < 2; ++bj) {
;                     const u32x4 h4 = H4[m][bj];
;                     u32x4 ho;
; #pragma unroll
;                     for (int j = 0; j < 4; ++j) {
;                         const unsigned lw = l4[2 * bj + (j >> 1)], lb0 = (lw >> (16 * (j & 1))) & 0xffu, lb1 = (lw >> (16 * (j & 1) + 8)) & 0xffu;
;                         const float x0 = e_x24(h4[j] & 0xffffu, lb0) + acc[ai][bj][m][j >> 1][2 * (j & 1)] * scale, x1 = e_x24(h4[j] >> 16, lb1) + acc[ai][bj][m][j >> 1][2 * (j & 1) + 1] * scale;
;                         const unsigned b0 = __float_as_uint(x0), b1 = __float_as_uint(x1);
;                         ho[j] = ((b0 + 0x8000u) >> 16) | ((b1 + 0x8000u) & 0xffff0000u);
;                         const unsigned nb = ((b0 >> 8) & 0xffu) | (b1 & 0xff00u);
;                         if ((j & 1) == 0) lo4[2 * bj + (j >> 1)] = nb; else lo4[2 * bj + (j >> 1)] |= nb << 16;
;                         ss += x0 * x0 + x1 * x1;
;                     }
;                     *(PG8_GAS u32x4*)(hout + off + bj * HALF) = ho;
;                 }
;                 *(PG8_GAS u32x4*)(lout + loff) = lo4;
;                 ss += __shfl_xor(ss, 16); ss += __shfl_xor(ss, 32);
;                 if (fq == 0) __hip_atomic_fetch_add((PG8_GAS unsigned long long*)(rowsq_out + row), (unsigned long long)(ss * 16777216.0f + 0.5f), __ATOMIC_RELAXED, __HIP_MEMORY_SCOPE_AGENT);
	v_add_u32_e32 v73, 0x8000, v84
	v_pk_add_f32 v[78:79], v[74:75], v[86:87]
	v_lshrrev_b32_e32 v73, 16, v73
	v_add_u32_e32 v74, 0x8000, v78
	v_and_or_b32 v73, v74, s90, v73
	v_pk_mul_f32 v[74:75], v[78:79], v[78:79]
	v_add_u32_e32 v88, 0x8000, v79
	v_pk_fma_f32 v[86:87], v[84:85], v[84:85], v[74:75]
	v_add_u32_e32 v74, 0x8000, v81
	v_lshrrev_b32_e32 v74, 16, v74
	v_add_u32_e32 v75, 0x8000, v77
	v_and_or_b32 v74, v75, s90, v74
	v_add_u32_e32 v75, 0x8000, v85
	v_lshrrev_b32_e32 v75, 16, v75
	v_add_u32_e32 v72, 0x8000, v76
	v_and_or_b32 v75, v88, s90, v75
	v_lshl_add_u64 v[88:89], v[206:207], 1, s[30:31]
	v_and_or_b32 v72, v72, s90, v90
	v_lshl_add_u64 v[88:89], v[196:197], 1, v[88:89]
	global_store_dwordx4 v[88:89], v[72:75], off nt
	v_lshlrev_b32_e32 v90, 1, v129
	v_lshlrev_b32_e32 v91, 1, v128
	v_lshrrev_b32_sdwa v72, v229, v129 dst_sel:DWORD dst_unused:UNUSED_PAD src0_sel:DWORD src1_sel:BYTE_0
	v_lshrrev_b32_sdwa v73, v229, v128 dst_sel:DWORD dst_unused:UNUSED_PAD src0_sel:DWORD src1_sel:BYTE_0
	v_sub_u32_sdwa v74, v130, v73 dst_sel:WORD_1 dst_unused:UNUSED_PAD src0_sel:DWORD src1_sel:DWORD
	v_sub_u32_sdwa v72, v132, v72 dst_sel:WORD_1 dst_unused:UNUSED_PAD src0_sel:DWORD src1_sel:DWORD
	v_lshlrev_b32_sdwa v73, v230, v129 dst_sel:DWORD dst_unused:UNUSED_PAD src0_sel:DWORD src1_sel:BYTE_0
	v_lshlrev_b32_sdwa v75, v230, v128 dst_sel:DWORD dst_unused:UNUSED_PAD src0_sel:DWORD src1_sel:BYTE_0
	v_or_b32_e32 v73, v72, v73
	v_or_b32_e32 v72, v74, v75
	v_mov_b32_e32 v74, v68
	v_mov_b32_e32 v75, v64
	v_pk_add_f32 v[72:73], v[74:75], v[72:73]
	v_and_b32_e32 v74, 0x10000, v91
	v_add_u32_e32 v64, 0x8000, v72
	v_lshrrev_b32_e32 v68, 16, v64
	v_and_b32_e32 v64, 0x10000, v90
	v_sub_u32_e32 v64, v132, v64
	v_sub_u32_e32 v74, v130, v74
	v_and_b32_e32 v92, 0xff00, v129
	v_and_b32_e32 v93, 0xff00, v128
	v_and_b32_e32 v64, 0xffff0000, v64
	v_and_b32_e32 v74, 0xffff0000, v74
	v_or_b32_e32 v75, v64, v92
	v_or_b32_e32 v74, v74, v93
	v_mov_b32_e32 v64, v69
	v_pk_add_f32 v[64:65], v[64:65], v[74:75]
	v_and_b32_sdwa v90, v128, s93 dst_sel:DWORD dst_unused:UNUSED_PAD src0_sel:WORD_1 src1_sel:DWORD
	v_add_u32_e32 v69, 0x8000, v64
	v_and_or_b32 v68, v69, s90, v68
	v_and_b32_sdwa v69, v129, s93 dst_sel:DWORD dst_unused:UNUSED_PAD src0_sel:WORD_1 src1_sel:DWORD
	v_lshrrev_b32_e32 v91, 7, v90
	v_lshrrev_b32_e32 v92, 7, v69
	v_sub_u32_sdwa v93, v131, v91 dst_sel:WORD_1 dst_unused:UNUSED_PAD src0_sel:DWORD src1_sel:DWORD
	v_sub_u32_sdwa v91, v133, v92 dst_sel:WORD_1 dst_unused:UNUSED_PAD src0_sel:DWORD src1_sel:DWORD
	v_lshlrev_b32_e32 v69, 8, v69
	v_lshlrev_b32_e32 v90, 8, v90
	v_or_b32_e32 v91, v91, v69
	v_or_b32_e32 v90, v93, v90
	v_mov_b32_e32 v92, v70
	v_mov_b32_e32 v93, v66
	v_pk_add_f32 v[90:91], v[92:93], v[90:91]
	v_lshlrev_b32_sdwa v94, v231, v128 dst_sel:DWORD dst_unused:UNUSED_PAD src0_sel:DWORD src1_sel:BYTE_3
	v_lshlrev_b32_sdwa v95, v231, v129 dst_sel:DWORD dst_unused:UNUSED_PAD src0_sel:DWORD src1_sel:BYTE_3
	v_add_u32_e32 v66, 0x8000, v90
	v_lshrrev_b32_e32 v69, 16, v66
	v_and_b32_e32 v66, 0x10000, v95
	v_and_b32_e32 v70, 0x10000, v94
	v_sub_u32_e32 v66, v133, v66
	v_sub_u32_e32 v70, v131, v70
	v_pk_mul_f32 v[82:83], v[76:77], v[76:77]
	v_pk_mul_f32 v[74:75], v[64:65], v[64:65]
	v_and_b32_e32 v66, 0xffff0000, v66
	v_and_b32_e32 v70, 0xffff0000, v70
	v_lshlrev_b32_sdwa v92, v230, v129 dst_sel:DWORD dst_unused:UNUSED_PAD src0_sel:DWORD src1_sel:BYTE_3
	v_lshlrev_b32_sdwa v94, v230, v128 dst_sel:DWORD dst_unused:UNUSED_PAD src0_sel:DWORD src1_sel:BYTE_3
	v_pk_fma_f32 v[82:83], v[80:81], v[80:81], v[82:83]
	v_pk_fma_f32 v[74:75], v[72:73], v[72:73], v[74:75]
	v_or_b32_e32 v93, v66, v92
	v_or_b32_e32 v92, v70, v94
	v_mov_b32_e32 v66, v71
	v_lshrrev_b32_e32 v72, 8, v72
	v_pk_add_f32 v[66:67], v[66:67], v[92:93]
	v_perm_b32 v64, v64, v72, s94
	v_add_f32_e32 v72, v82, v86
	v_add_u32_e32 v70, 0x8000, v66
	v_add_f32_e32 v72, v83, v72
	v_and_or_b32 v69, v70, s90, v69
	v_pk_mul_f32 v[70:71], v[66:67], v[66:67]
	v_add_f32_e32 v72, v87, v72
	v_pk_fma_f32 v[92:93], v[90:91], v[90:91], v[70:71]
	v_add_f32_e32 v72, v74, v72
	v_add_f32_e32 v72, v92, v72
	v_lshrrev_b32_e32 v80, 8, v80
	v_add_f32_e32 v72, v75, v72
	v_lshrrev_b32_e32 v81, 8, v81
	v_perm_b32 v76, v76, v80, s94
	v_add_f32_e32 v80, v93, v72
	v_perm_b32 v77, v77, v81, s94
	ds_bpermute_b32 v81, v238, v80
	v_add_u32_e32 v70, 0x8000, v73
	v_lshrrev_b32_e32 v70, 16, v70
	v_add_u32_e32 v71, 0x8000, v65
	v_lshrrev_b32_e32 v90, 8, v90
	v_and_or_b32 v70, v71, s90, v70
	v_add_u32_e32 v71, 0x8000, v91
	v_lshrrev_b32_e32 v91, 8, v91
	v_perm_b32 v66, v66, v90, s94
	v_lshrrev_b32_e32 v73, 8, v73
	v_add_u32_e32 v94, 0x8000, v67
	v_perm_b32 v67, v67, v91, s94
	v_perm_b32 v65, v65, v73, s94
	v_lshl_or_b32 v74, v66, 16, v64
	s_waitcnt lgkmcnt(0)
	v_add_f32_e32 v64, v80, v81
	v_lshl_or_b32 v75, v67, 16, v65
	ds_bpermute_b32 v65, v237, v64
	v_lshrrev_b32_e32 v85, 8, v85
	v_lshrrev_b32_e32 v84, 8, v84
	v_lshrrev_b32_e32 v71, 16, v71
	v_perm_b32 v78, v78, v84, s94
	v_perm_b32 v79, v79, v85, s94
	v_lshl_add_u64 v[66:67], s[34:35], 0, v[206:207]
	v_and_or_b32 v71, v94, s90, v71
	v_lshl_or_b32 v73, v79, 16, v77
	v_lshl_or_b32 v72, v78, 16, v76
	v_lshl_add_u64 v[66:67], v[66:67], 0, v[194:195]
	global_store_dwordx4 v[88:89], v[68:71], off offset:256 nt
	global_store_dwordx4 v[66:67], v[72:75], off nt
	s_and_saveexec_b64 s[54:55], s[40:41]
	s_movk_i32 s78, 0x1fff
	s_cbranch_execz .LBB0_1208
	s_waitcnt lgkmcnt(0)
	v_add_f32_e32 v64, v64, v65
	v_fma_f32 v64, v64, s80, 0.5
	v_trunc_f32_e32 v64, v64
	v_mul_f32_e32 v65, 0x2f800000, v64
	v_floor_f32_e32 v65, v65
	v_fmac_f32_e32 v64, 0xcf800000, v65
	v_cvt_u32_f32_e32 v64, v64
	v_cvt_u32_f32_e32 v65, v65
	v_lshl_add_u64 v[66:67], v[204:205], 3, s[44:45]
	global_atomic_add_x2 v[66:67], v[64:65], off
; #define PG8_GAS __attribute__((address_space(1)))
; __device__ __forceinline__ float e_x24(unsigned h16, unsigned l8) { return __uint_as_float(((h16 - (l8 >> 7)) << 16) | (l8 << 8)); }
;     __device__ __forceinline__ void operator()(const f32x4 (&acc)[2][2][4][2], const Unit& u, int wr, int wc, int fr, int fq) const {
;     ...
;         for (int ai = 0; ai < 2; ++ai) {
;             u32x4 L4[4], H4[4][2];
; #pragma unroll
;             for (int m = 0; m < 4; ++m) {
;                 const int row = row0 + ai * HALF + m * 16; const size_t off = (size_t)row * 2048 + col0, loff = (size_t)row * 2048 + lcol;
;                 L4[m] = *(const PG8_GAS u32x4*)(lin + loff); H4[m][0] = *(const PG8_GAS u32x4*)(hin + off); H4[m][1] = *(const PG8_GAS u32x4*)(hin + off + HALF);
;             }
; #pragma unroll
;             for (int m = 0; m < 4; ++m) {
;                 const int row = row0 + ai * HALF + m * 16; const size_t off = (size_t)row * 2048 + col0, loff = (size_t)row * 2048 + lcol; float ss = 0.f;
;                 const u32x4 l4 = L4[m];
;                 u32x4 lo4;
; #pragma unroll
;                 for (int bj = 0; bj < 2; ++bj) {
;                     const u32x4 h4 = H4[m][bj];
;                     u32x4 ho;
; #pragma unroll
;                     for (int j = 0; j < 4; ++j) {
;                         const unsigned lw = l4[2 * bj + (j >> 1)], lb0 = (lw >> (16 * (j & 1))) & 0xffu, lb1 = (lw >> (16 * (j & 1) + 8)) & 0xffu;
;                         const float x0 = e_x24(h4[j] & 0xffffu, lb0) + acc[ai][bj][m][j >> 1][2 * (j & 1)] * scale, x1 = e_x24(h4[j] >> 16, lb1) + acc[ai][bj][m][j >> 1][2 * (j & 1) + 1] * scale;
;                         const unsigned b0 = __float_as_uint(x0), b1 = __float_as_uint(x1);
;                         ho[j] = ((b0 + 0x8000u) >> 16) | ((b1 + 0x8000u) & 0xffff0000u);
;                         const unsigned nb = ((b0 >> 8) & 0xffu) | (b1 & 0xff00u);
;                         if ((j & 1) == 0) lo4[2 * bj + (j >> 1)] = nb; else lo4[2 * bj + (j >> 1)] |= nb << 16;
;                         ss += x0 * x0 + x1 * x1;
;                     }
;                     *(PG8_GAS u32x4*)(hout + off + bj * HALF) = ho;
;                 }
;                 *(PG8_GAS u32x4*)(lout + loff) = lo4;
.LBB0_1208:
	s_or_b64 exec, exec, s[54:55]
	v_add_u32_e32 v130, 0x80, v198
	v_ashrrev_i32_e32 v131, 31, v130
	v_lshlrev_b64 v[132:133], 11, v[130:131]
	s_waitcnt lgkmcnt(0)
	v_lshl_add_u64 v[64:65], v[202:203], 0, v[132:133]
	global_load_dwordx4 v[106:109], v[64:65], off
	v_lshlrev_b64 v[134:135], 12, v[130:131]
	v_lshl_add_u64 v[64:65], v[200:201], 0, v[134:135]
	global_load_dwordx4 v[114:117], v[64:65], off
	global_load_dwordx4 v[110:113], v[64:65], off offset:256
	v_add_u32_e32 v126, 0x90, v198
	v_ashrrev_i32_e32 v127, 31, v126
	v_lshlrev_b64 v[128:129], 11, v[126:127]
	v_lshl_add_u64 v[64:65], v[202:203], 0, v[128:129]
	v_add_u32_e32 v122, 0xa0, v198
	global_load_dwordx4 v[88:91], v[64:65], off
	v_lshlrev_b64 v[64:65], 12, v[126:127]
	v_ashrrev_i32_e32 v123, 31, v122
	v_lshl_add_u64 v[64:65], v[200:201], 0, v[64:65]
	v_lshlrev_b64 v[124:125], 11, v[122:123]
	global_load_dwordx4 v[102:105], v[64:65], off
	global_load_dwordx4 v[92:95], v[64:65], off offset:256
	v_lshl_add_u64 v[64:65], v[202:203], 0, v[124:125]
	v_add_u32_e32 v118, 0xb0, v198
	global_load_dwordx4 v[76:79], v[64:65], off
	v_lshlrev_b64 v[64:65], 12, v[122:123]
	v_ashrrev_i32_e32 v119, 31, v118
	v_lshl_add_u64 v[64:65], v[200:201], 0, v[64:65]
	v_lshlrev_b64 v[120:121], 11, v[118:119]
	v_lshlrev_b64 v[68:69], 12, v[118:119]
	global_load_dwordx4 v[84:87], v[64:65], off
	global_load_dwordx4 v[80:83], v[64:65], off offset:256
	v_lshl_add_u64 v[64:65], v[202:203], 0, v[120:121]
	v_lshl_add_u64 v[68:69], v[200:201], 0, v[68:69]
	global_load_dwordx4 v[64:67], v[64:65], off
	s_nop 0
	global_load_dwordx4 v[72:75], v[68:69], off
	s_nop 0
	global_load_dwordx4 v[68:71], v[68:69], off offset:256
	v_mov_b32_e32 v143, v58
	v_mov_b32_e32 v142, v62
	s_waitcnt vmcnt(11)
	v_lshrrev_b32_sdwa v136, v229, v107 dst_sel:DWORD dst_unused:UNUSED_PAD src0_sel:DWORD src1_sel:BYTE_0
	v_lshrrev_b32_sdwa v137, v229, v106 dst_sel:DWORD dst_unused:UNUSED_PAD src0_sel:DWORD src1_sel:BYTE_0
	s_waitcnt vmcnt(10)
	v_sub_u32_sdwa v138, v114, v137 dst_sel:WORD_1 dst_unused:UNUSED_PAD src0_sel:DWORD src1_sel:DWORD
	v_sub_u32_sdwa v136, v116, v136 dst_sel:WORD_1 dst_unused:UNUSED_PAD src0_sel:DWORD src1_sel:DWORD
	v_lshlrev_b32_sdwa v137, v230, v107 dst_sel:DWORD dst_unused:UNUSED_PAD src0_sel:DWORD src1_sel:BYTE_0
	v_lshlrev_b32_sdwa v139, v230, v106 dst_sel:DWORD dst_unused:UNUSED_PAD src0_sel:DWORD src1_sel:BYTE_0
	v_or_b32_e32 v137, v136, v137
	v_or_b32_e32 v136, v138, v139
	v_mov_b32_e32 v138, v60
	v_mov_b32_e32 v139, v56
	v_pk_add_f32 v[136:137], v[138:139], v[136:137]
	v_lshlrev_b32_e32 v138, 1, v106
	v_add_u32_e32 v56, 0x8000, v136
	v_lshrrev_b32_e32 v60, 16, v56
	v_lshlrev_b32_e32 v56, 1, v107
	v_and_b32_e32 v56, 0x10000, v56
	v_and_b32_e32 v138, 0x10000, v138
	v_sub_u32_e32 v56, v116, v56
	v_sub_u32_e32 v114, v114, v138
	v_and_b32_e32 v56, 0xffff0000, v56
	v_and_b32_e32 v114, 0xffff0000, v114
	v_and_b32_e32 v116, 0xff00, v107
	v_and_b32_e32 v138, 0xff00, v106
	v_or_b32_e32 v139, v56, v116
	v_or_b32_e32 v138, v114, v138
	v_mov_b32_e32 v56, v61
	v_pk_add_f32 v[138:139], v[56:57], v[138:139]
	v_and_b32_sdwa v57, v107, s93 dst_sel:DWORD dst_unused:UNUSED_PAD src0_sel:WORD_1 src1_sel:DWORD
	v_and_b32_sdwa v114, v106, s93 dst_sel:DWORD dst_unused:UNUSED_PAD src0_sel:WORD_1 src1_sel:DWORD
	v_lshlrev_b32_sdwa v144, v231, v106 dst_sel:DWORD dst_unused:UNUSED_PAD src0_sel:DWORD src1_sel:BYTE_3
	v_lshlrev_b32_sdwa v58, v231, v107 dst_sel:DWORD dst_unused:UNUSED_PAD src0_sel:DWORD src1_sel:BYTE_3
	v_lshrrev_b32_e32 v116, 7, v114
	v_lshrrev_b32_e32 v140, 7, v57
	v_and_b32_e32 v58, 0x10000, v58
	v_and_b32_e32 v62, 0x10000, v144
	v_sub_u32_sdwa v116, v115, v116 dst_sel:WORD_1 dst_unused:UNUSED_PAD src0_sel:DWORD src1_sel:DWORD
	v_sub_u32_sdwa v140, v117, v140 dst_sel:WORD_1 dst_unused:UNUSED_PAD src0_sel:DWORD src1_sel:DWORD
	v_lshlrev_b32_e32 v57, 8, v57
	v_lshlrev_b32_e32 v114, 8, v114
	v_sub_u32_e32 v58, v117, v58
	v_sub_u32_e32 v62, v115, v62
	v_or_b32_e32 v141, v140, v57
	v_or_b32_e32 v140, v116, v114
	v_and_b32_e32 v58, 0xffff0000, v58
	v_and_b32_e32 v62, 0xffff0000, v62
	v_lshlrev_b32_sdwa v107, v230, v107 dst_sel:DWORD dst_unused:UNUSED_PAD src0_sel:DWORD src1_sel:BYTE_3
	v_lshlrev_b32_sdwa v106, v230, v106 dst_sel:DWORD dst_unused:UNUSED_PAD src0_sel:DWORD src1_sel:BYTE_3
	v_pk_add_f32 v[140:141], v[142:143], v[140:141]
	v_or_b32_e32 v107, v58, v107
	v_or_b32_e32 v106, v62, v106
	v_mov_b32_e32 v58, v63
	v_add_u32_e32 v57, 0x8000, v140
	v_pk_add_f32 v[62:63], v[58:59], v[106:107]
	v_lshrrev_b32_e32 v57, 16, v57
	v_add_u32_e32 v58, 0x8000, v62
	v_and_or_b32 v57, v58, s90, v57
	v_pk_mul_f32 v[58:59], v[62:63], v[62:63]
	v_add_u32_e32 v114, 0x8000, v63
	v_pk_fma_f32 v[106:107], v[140:141], v[140:141], v[58:59]
	v_add_u32_e32 v58, 0x8000, v137
	v_lshrrev_b32_e32 v58, 16, v58
	v_add_u32_e32 v59, 0x8000, v139
	v_and_or_b32 v58, v59, s90, v58
	v_add_u32_e32 v59, 0x8000, v141
	v_lshrrev_b32_e32 v59, 16, v59
	v_add_u32_e32 v56, 0x8000, v138
	v_and_or_b32 v59, v114, s90, v59
	v_lshl_add_u64 v[114:115], s[30:31], 0, v[134:135]
	v_and_or_b32 v56, v56, s90, v60
	v_lshl_add_u64 v[114:115], v[196:197], 1, v[114:115]
	global_store_dwordx4 v[114:115], v[56:59], off nt
	v_lshlrev_b32_sdwa v142, v231, v108 dst_sel:DWORD dst_unused:UNUSED_PAD src0_sel:DWORD src1_sel:BYTE_3
	v_mov_b32_e32 v135, v50
	v_lshrrev_b32_sdwa v56, v229, v109 dst_sel:DWORD dst_unused:UNUSED_PAD src0_sel:DWORD src1_sel:BYTE_0
	v_lshrrev_b32_sdwa v57, v229, v108 dst_sel:DWORD dst_unused:UNUSED_PAD src0_sel:DWORD src1_sel:BYTE_0
	s_waitcnt vmcnt(10)
; #define PG8_GAS __attribute__((address_space(1)))
; __device__ __forceinline__ float e_x24(unsigned h16, unsigned l8) { return __uint_as_float(((h16 - (l8 >> 7)) << 16) | (l8 << 8)); }
;     __device__ __forceinline__ void operator()(const f32x4 (&acc)[2][2][4][2], const Unit& u, int wr, int wc, int fr, int fq) const {
;     ...
;                 for (int bj = 0; bj < 2; ++bj) {
;                     const u32x4 h4 = H4[m][bj];
;                     u32x4 ho;
; #pragma unroll
;                     for (int j = 0; j < 4; ++j) {
;                         const unsigned lw = l4[2 * bj + (j >> 1)], lb0 = (lw >> (16 * (j & 1))) & 0xffu, lb1 = (lw >> (16 * (j & 1) + 8)) & 0xffu;
;                         const float x0 = e_x24(h4[j] & 0xffffu, lb0) + acc[ai][bj][m][j >> 1][2 * (j & 1)] * scale, x1 = e_x24(h4[j] >> 16, lb1) + acc[ai][bj][m][j >> 1][2 * (j & 1) + 1] * scale;
;                         const unsigned b0 = __float_as_uint(x0), b1 = __float_as_uint(x1);
;                         ho[j] = ((b0 + 0x8000u) >> 16) | ((b1 + 0x8000u) & 0xffff0000u);
;                         const unsigned nb = ((b0 >> 8) & 0xffu) | (b1 & 0xff00u);
;                         if ((j & 1) == 0) lo4[2 * bj + (j >> 1)] = nb; else lo4[2 * bj + (j >> 1)] |= nb << 16;
;                         ss += x0 * x0 + x1 * x1;
;                     }
;                     *(PG8_GAS u32x4*)(hout + off + bj * HALF) = ho;
;                 }
;                 *(PG8_GAS u32x4*)(lout + loff) = lo4;
;                 ss += __shfl_xor(ss, 16); ss += __shfl_xor(ss, 32);
;                 if (fq == 0) __hip_atomic_fetch_add((PG8_GAS unsigned long long*)(rowsq_out + row), (unsigned long long)(ss * 16777216.0f + 0.5f), __ATOMIC_RELAXED, __HIP_MEMORY_SCOPE_AGENT);
	v_sub_u32_sdwa v58, v110, v57 dst_sel:WORD_1 dst_unused:UNUSED_PAD src0_sel:DWORD src1_sel:DWORD
	v_sub_u32_sdwa v56, v112, v56 dst_sel:WORD_1 dst_unused:UNUSED_PAD src0_sel:DWORD src1_sel:DWORD
	v_lshlrev_b32_sdwa v57, v230, v109 dst_sel:DWORD dst_unused:UNUSED_PAD src0_sel:DWORD src1_sel:BYTE_0
	v_lshlrev_b32_sdwa v59, v230, v108 dst_sel:DWORD dst_unused:UNUSED_PAD src0_sel:DWORD src1_sel:BYTE_0
	v_or_b32_e32 v57, v56, v57
	v_or_b32_e32 v56, v58, v59
	v_mov_b32_e32 v58, v52
	v_mov_b32_e32 v59, v48
	v_pk_add_f32 v[56:57], v[58:59], v[56:57]
	v_lshlrev_b32_e32 v52, 1, v108
	v_add_u32_e32 v48, 0x8000, v56
	v_lshrrev_b32_e32 v116, 16, v48
	v_lshlrev_b32_e32 v48, 1, v109
	v_and_b32_e32 v48, 0x10000, v48
	v_and_b32_e32 v52, 0x10000, v52
	v_sub_u32_e32 v48, v112, v48
	v_sub_u32_e32 v52, v110, v52
	v_and_b32_e32 v48, 0xffff0000, v48
	v_and_b32_e32 v52, 0xffff0000, v52
	v_and_b32_e32 v58, 0xff00, v109
	v_and_b32_e32 v110, 0xff00, v108
	v_or_b32_e32 v59, v48, v58
	v_or_b32_e32 v58, v52, v110
	v_mov_b32_e32 v48, v53
	v_pk_add_f32 v[52:53], v[48:49], v[58:59]
	v_and_b32_sdwa v49, v109, s93 dst_sel:DWORD dst_unused:UNUSED_PAD src0_sel:WORD_1 src1_sel:DWORD
	v_add_u32_e32 v48, 0x8000, v52
	v_and_b32_sdwa v110, v108, s93 dst_sel:DWORD dst_unused:UNUSED_PAD src0_sel:WORD_1 src1_sel:DWORD
	v_lshlrev_b32_sdwa v50, v231, v109 dst_sel:DWORD dst_unused:UNUSED_PAD src0_sel:DWORD src1_sel:BYTE_3
	v_and_or_b32 v48, v48, s90, v116
	v_lshrrev_b32_e32 v112, 7, v110
	v_lshrrev_b32_e32 v116, 7, v49
	v_mov_b32_e32 v134, v54
	v_and_b32_e32 v50, 0x10000, v50
	v_and_b32_e32 v54, 0x10000, v142
	v_sub_u32_sdwa v112, v111, v112 dst_sel:WORD_1 dst_unused:UNUSED_PAD src0_sel:DWORD src1_sel:DWORD
	v_sub_u32_sdwa v116, v113, v116 dst_sel:WORD_1 dst_unused:UNUSED_PAD src0_sel:DWORD src1_sel:DWORD
	v_lshlrev_b32_e32 v49, 8, v49
	v_lshlrev_b32_e32 v110, 8, v110
	v_sub_u32_e32 v50, v113, v50
	v_sub_u32_e32 v54, v111, v54
	v_or_b32_e32 v117, v116, v49
	v_or_b32_e32 v116, v112, v110
	v_and_b32_e32 v50, 0xffff0000, v50
	v_and_b32_e32 v54, 0xffff0000, v54
	v_lshlrev_b32_sdwa v109, v230, v109 dst_sel:DWORD dst_unused:UNUSED_PAD src0_sel:DWORD src1_sel:BYTE_3
	v_lshlrev_b32_sdwa v108, v230, v108 dst_sel:DWORD dst_unused:UNUSED_PAD src0_sel:DWORD src1_sel:BYTE_3
	v_pk_add_f32 v[116:117], v[134:135], v[116:117]
	v_or_b32_e32 v109, v50, v109
	v_or_b32_e32 v108, v54, v108
	v_mov_b32_e32 v50, v55
	v_add_u32_e32 v49, 0x8000, v116
	v_pk_add_f32 v[54:55], v[50:51], v[108:109]
	v_lshrrev_b32_e32 v49, 16, v49
	v_add_u32_e32 v50, 0x8000, v54
	v_pk_mul_f32 v[60:61], v[138:139], v[138:139]
	v_pk_mul_f32 v[58:59], v[52:53], v[52:53]
	v_and_or_b32 v49, v50, s90, v49
	v_pk_mul_f32 v[50:51], v[54:55], v[54:55]
	v_pk_fma_f32 v[60:61], v[136:137], v[136:137], v[60:61]
	v_pk_fma_f32 v[58:59], v[56:57], v[56:57], v[58:59]
	v_pk_fma_f32 v[108:109], v[116:117], v[116:117], v[50:51]
	v_add_u32_e32 v50, 0x8000, v57
	v_lshrrev_b32_e32 v56, 8, v56
	v_lshrrev_b32_e32 v50, 16, v50
	v_add_u32_e32 v51, 0x8000, v53
	v_perm_b32 v52, v52, v56, s94
	v_add_f32_e32 v56, v60, v106
	v_and_or_b32 v50, v51, s90, v50
	v_add_u32_e32 v51, 0x8000, v117
	v_add_f32_e32 v56, v61, v56
	v_lshrrev_b32_e32 v51, 16, v51
	v_add_u32_e32 v110, 0x8000, v55
	v_add_f32_e32 v56, v107, v56
	v_and_or_b32 v51, v110, s90, v51
	v_lshrrev_b32_e32 v110, 8, v117
	v_lshrrev_b32_e32 v111, 8, v116
	v_add_f32_e32 v56, v58, v56
	v_lshrrev_b32_e32 v112, 8, v141
	v_lshrrev_b32_e32 v113, 8, v140
	v_perm_b32 v54, v54, v111, s94
	v_perm_b32 v55, v55, v110, s94
	v_lshrrev_b32_e32 v57, 8, v57
	v_lshrrev_b32_e32 v110, 8, v137
	v_lshrrev_b32_e32 v111, 8, v136
	v_add_f32_e32 v56, v108, v56
	v_perm_b32 v62, v62, v113, s94
	v_perm_b32 v63, v63, v112, s94
	v_perm_b32 v111, v138, v111, s94
	v_perm_b32 v110, v139, v110, s94
	v_perm_b32 v53, v53, v57, s94
	v_add_f32_e32 v56, v59, v56
	global_store_dwordx4 v[114:115], v[48:51], off offset:256 nt
	v_lshl_or_b32 v55, v55, 16, v53
	v_lshl_or_b32 v54, v54, 16, v52
	v_lshl_add_u64 v[48:49], s[34:35], 0, v[132:133]
	v_lshl_or_b32 v53, v63, 16, v110
	v_lshl_or_b32 v52, v62, 16, v111
	v_add_f32_e32 v56, v109, v56
	v_lshl_add_u64 v[48:49], v[48:49], 0, v[194:195]
	global_store_dwordx4 v[48:49], v[52:55], off nt
	ds_bpermute_b32 v48, v238, v56
	s_waitcnt lgkmcnt(0)
	v_add_f32_e32 v48, v56, v48
	ds_bpermute_b32 v49, v237, v48
	s_and_saveexec_b64 s[54:55], s[40:41]
	s_cbranch_execz .LBB0_1210
	s_waitcnt lgkmcnt(0)
	v_add_f32_e32 v48, v48, v49
	v_fma_f32 v48, v48, s80, 0.5
	v_trunc_f32_e32 v48, v48
	v_mul_f32_e32 v49, 0x2f800000, v48
	v_floor_f32_e32 v49, v49
	v_fmac_f32_e32 v48, 0xcf800000, v49
	v_cvt_u32_f32_e32 v48, v48
	v_cvt_u32_f32_e32 v49, v49
	v_lshl_add_u64 v[50:51], v[130:131], 3, s[44:45]
	global_atomic_add_x2 v[50:51], v[48:49], off
; #define PG8_GAS __attribute__((address_space(1)))
; __device__ __forceinline__ float e_x24(unsigned h16, unsigned l8) { return __uint_as_float(((h16 - (l8 >> 7)) << 16) | (l8 << 8)); }
;     __device__ __forceinline__ void operator()(const f32x4 (&acc)[2][2][4][2], const Unit& u, int wr, int wc, int fr, int fq) const {
;     ...
;             for (int m = 0; m < 4; ++m) {
;                 const int row = row0 + ai * HALF + m * 16; const size_t off = (size_t)row * 2048 + col0, loff = (size_t)row * 2048 + lcol; float ss = 0.f;
;                 const u32x4 l4 = L4[m];
;                 u32x4 lo4;
; #pragma unroll
;                 for (int bj = 0; bj < 2; ++bj) {
;                     const u32x4 h4 = H4[m][bj];
;                     u32x4 ho;
; #pragma unroll
;                     for (int j = 0; j < 4; ++j) {
;                         const unsigned lw = l4[2 * bj + (j >> 1)], lb0 = (lw >> (16 * (j & 1))) & 0xffu, lb1 = (lw >> (16 * (j & 1) + 8)) & 0xffu;
;                         const float x0 = e_x24(h4[j] & 0xffffu, lb0) + acc[ai][bj][m][j >> 1][2 * (j & 1)] * scale, x1 = e_x24(h4[j] >> 16, lb1) + acc[ai][bj][m][j >> 1][2 * (j & 1) + 1] * scale;
;                         const unsigned b0 = __float_as_uint(x0), b1 = __float_as_uint(x1);
;                         ho[j] = ((b0 + 0x8000u) >> 16) | ((b1 + 0x8000u) & 0xffff0000u);
;                         const unsigned nb = ((b0 >> 8) & 0xffu) | (b1 & 0xff00u);
;                         if ((j & 1) == 0) lo4[2 * bj + (j >> 1)] = nb; else lo4[2 * bj + (j >> 1)] |= nb << 16;
;                         ss += x0 * x0 + x1 * x1;
;                     }
;                     *(PG8_GAS u32x4*)(hout + off + bj * HALF) = ho;
;                 }
;                 *(PG8_GAS u32x4*)(lout + loff) = lo4;
;                 ss += __shfl_xor(ss, 16); ss += __shfl_xor(ss, 32);
;                 if (fq == 0) __hip_atomic_fetch_add((PG8_GAS unsigned long long*)(rowsq_out + row), (unsigned long long)(ss * 16777216.0f + 0.5f), __ATOMIC_RELAXED, __HIP_MEMORY_SCOPE_AGENT);
.LBB0_1210:
	s_or_b64 exec, exec, s[54:55]
	s_waitcnt vmcnt(11)
	v_lshrrev_b32_sdwa v48, v229, v89 dst_sel:DWORD dst_unused:UNUSED_PAD src0_sel:DWORD src1_sel:BYTE_0
	s_waitcnt lgkmcnt(0)
	v_lshrrev_b32_sdwa v49, v229, v88 dst_sel:DWORD dst_unused:UNUSED_PAD src0_sel:DWORD src1_sel:BYTE_0
	s_waitcnt vmcnt(10)
	v_sub_u32_sdwa v50, v102, v49 dst_sel:WORD_1 dst_unused:UNUSED_PAD src0_sel:DWORD src1_sel:DWORD
	v_sub_u32_sdwa v48, v104, v48 dst_sel:WORD_1 dst_unused:UNUSED_PAD src0_sel:DWORD src1_sel:DWORD
	v_lshlrev_b32_sdwa v49, v230, v89 dst_sel:DWORD dst_unused:UNUSED_PAD src0_sel:DWORD src1_sel:BYTE_0
	v_lshlrev_b32_sdwa v51, v230, v88 dst_sel:DWORD dst_unused:UNUSED_PAD src0_sel:DWORD src1_sel:BYTE_0
	v_or_b32_e32 v49, v48, v49
	v_or_b32_e32 v48, v50, v51
	v_mov_b32_e32 v50, v44
	v_mov_b32_e32 v51, v40
	v_pk_add_f32 v[48:49], v[50:51], v[48:49]
	v_lshlrev_b32_e32 v52, 1, v89
	v_lshlrev_b32_e32 v53, 1, v88
	v_add_u32_e32 v40, 0x8000, v48
	v_lshrrev_b32_e32 v58, 16, v40
	v_and_b32_e32 v40, 0x10000, v52
	v_and_b32_e32 v44, 0x10000, v53
	v_sub_u32_e32 v40, v104, v40
	v_sub_u32_e32 v44, v102, v44
	v_and_b32_e32 v54, 0xff00, v89
	v_and_b32_e32 v55, 0xff00, v88
	v_and_b32_e32 v40, 0xffff0000, v40
	v_and_b32_e32 v44, 0xffff0000, v44
	v_or_b32_e32 v51, v40, v54
	v_or_b32_e32 v50, v44, v55
	v_mov_b32_e32 v40, v45
	v_and_b32_sdwa v52, v88, s93 dst_sel:DWORD dst_unused:UNUSED_PAD src0_sel:WORD_1 src1_sel:DWORD
	v_pk_add_f32 v[44:45], v[40:41], v[50:51]
	v_and_b32_sdwa v41, v89, s93 dst_sel:DWORD dst_unused:UNUSED_PAD src0_sel:WORD_1 src1_sel:DWORD
	v_lshrrev_b32_e32 v53, 7, v52
	v_lshlrev_b32_sdwa v56, v231, v88 dst_sel:DWORD dst_unused:UNUSED_PAD src0_sel:DWORD src1_sel:BYTE_3
	v_lshlrev_b32_sdwa v57, v231, v89 dst_sel:DWORD dst_unused:UNUSED_PAD src0_sel:DWORD src1_sel:BYTE_3
	v_lshrrev_b32_e32 v54, 7, v41
	v_sub_u32_sdwa v55, v103, v53 dst_sel:WORD_1 dst_unused:UNUSED_PAD src0_sel:DWORD src1_sel:DWORD
	v_lshlrev_b32_e32 v52, 8, v52
	v_sub_u32_sdwa v53, v105, v54 dst_sel:WORD_1 dst_unused:UNUSED_PAD src0_sel:DWORD src1_sel:DWORD
	v_lshlrev_b32_e32 v41, 8, v41
	v_or_b32_e32 v52, v55, v52
	v_mov_b32_e32 v54, v46
	v_mov_b32_e32 v55, v42
	v_and_b32_e32 v42, 0x10000, v57
	v_and_b32_e32 v46, 0x10000, v56
	v_or_b32_e32 v53, v53, v41
	v_sub_u32_e32 v42, v105, v42
	v_sub_u32_e32 v46, v103, v46
	v_pk_add_f32 v[52:53], v[54:55], v[52:53]
	v_and_b32_e32 v42, 0xffff0000, v42
	v_and_b32_e32 v46, 0xffff0000, v46
	v_lshlrev_b32_sdwa v54, v230, v89 dst_sel:DWORD dst_unused:UNUSED_PAD src0_sel:DWORD src1_sel:BYTE_3
	v_lshlrev_b32_sdwa v56, v230, v88 dst_sel:DWORD dst_unused:UNUSED_PAD src0_sel:DWORD src1_sel:BYTE_3
	v_or_b32_e32 v55, v42, v54
	v_or_b32_e32 v54, v46, v56
	v_mov_b32_e32 v42, v47
	v_add_u32_e32 v41, 0x8000, v52
	v_pk_add_f32 v[46:47], v[42:43], v[54:55]
	v_lshrrev_b32_e32 v41, 16, v41
	v_add_u32_e32 v42, 0x8000, v46
	v_and_or_b32 v41, v42, s90, v41
	v_pk_mul_f32 v[42:43], v[46:47], v[46:47]
	v_add_u32_e32 v56, 0x8000, v47
	v_pk_fma_f32 v[54:55], v[52:53], v[52:53], v[42:43]
	v_add_u32_e32 v42, 0x8000, v49
	v_lshrrev_b32_e32 v42, 16, v42
	v_add_u32_e32 v43, 0x8000, v45
	v_and_or_b32 v42, v43, s90, v42
	v_add_u32_e32 v43, 0x8000, v53
	v_lshrrev_b32_e32 v43, 16, v43
	v_add_u32_e32 v40, 0x8000, v44
	v_and_or_b32 v43, v56, s90, v43
	v_lshl_add_u64 v[56:57], v[128:129], 1, s[30:31]
	v_and_or_b32 v40, v40, s90, v58
	v_lshl_add_u64 v[56:57], v[196:197], 1, v[56:57]
	global_store_dwordx4 v[56:57], v[40:43], off nt
	v_lshlrev_b32_e32 v58, 1, v91
	v_lshlrev_b32_e32 v59, 1, v90
	v_lshrrev_b32_sdwa v40, v229, v91 dst_sel:DWORD dst_unused:UNUSED_PAD src0_sel:DWORD src1_sel:BYTE_0
	v_lshrrev_b32_sdwa v41, v229, v90 dst_sel:DWORD dst_unused:UNUSED_PAD src0_sel:DWORD src1_sel:BYTE_0
	s_waitcnt vmcnt(10)
	v_sub_u32_sdwa v42, v92, v41 dst_sel:WORD_1 dst_unused:UNUSED_PAD src0_sel:DWORD src1_sel:DWORD
	v_sub_u32_sdwa v40, v94, v40 dst_sel:WORD_1 dst_unused:UNUSED_PAD src0_sel:DWORD src1_sel:DWORD
	v_lshlrev_b32_sdwa v41, v230, v91 dst_sel:DWORD dst_unused:UNUSED_PAD src0_sel:DWORD src1_sel:BYTE_0
	v_lshlrev_b32_sdwa v43, v230, v90 dst_sel:DWORD dst_unused:UNUSED_PAD src0_sel:DWORD src1_sel:BYTE_0
	v_or_b32_e32 v41, v40, v41
	v_or_b32_e32 v40, v42, v43
	v_mov_b32_e32 v42, v36
	v_mov_b32_e32 v43, v32
	v_pk_add_f32 v[40:41], v[42:43], v[40:41]
	v_and_b32_e32 v42, 0x10000, v59
	v_add_u32_e32 v32, 0x8000, v40
	v_lshrrev_b32_e32 v36, 16, v32
	v_and_b32_e32 v32, 0x10000, v58
	v_sub_u32_e32 v32, v94, v32
	v_sub_u32_e32 v42, v92, v42
	v_and_b32_e32 v60, 0xff00, v91
	v_and_b32_e32 v61, 0xff00, v90
	v_and_b32_e32 v32, 0xffff0000, v32
	v_and_b32_e32 v42, 0xffff0000, v42
	v_or_b32_e32 v43, v32, v60
	v_or_b32_e32 v42, v42, v61
	v_mov_b32_e32 v32, v37
	v_pk_add_f32 v[32:33], v[32:33], v[42:43]
	v_and_b32_sdwa v58, v90, s93 dst_sel:DWORD dst_unused:UNUSED_PAD src0_sel:WORD_1 src1_sel:DWORD
	v_add_u32_e32 v37, 0x8000, v32
	v_and_or_b32 v36, v37, s90, v36
	v_and_b32_sdwa v37, v91, s93 dst_sel:DWORD dst_unused:UNUSED_PAD src0_sel:WORD_1 src1_sel:DWORD
	v_lshrrev_b32_e32 v59, 7, v58
	v_lshrrev_b32_e32 v60, 7, v37
	v_sub_u32_sdwa v61, v93, v59 dst_sel:WORD_1 dst_unused:UNUSED_PAD src0_sel:DWORD src1_sel:DWORD
	v_sub_u32_sdwa v59, v95, v60 dst_sel:WORD_1 dst_unused:UNUSED_PAD src0_sel:DWORD src1_sel:DWORD
	v_lshlrev_b32_e32 v37, 8, v37
	v_lshlrev_b32_e32 v58, 8, v58
	v_or_b32_e32 v59, v59, v37
	v_or_b32_e32 v58, v61, v58
	v_mov_b32_e32 v60, v38
	v_mov_b32_e32 v61, v34
	v_pk_add_f32 v[58:59], v[60:61], v[58:59]
	v_lshlrev_b32_sdwa v62, v231, v90 dst_sel:DWORD dst_unused:UNUSED_PAD src0_sel:DWORD src1_sel:BYTE_3
	v_lshlrev_b32_sdwa v63, v231, v91 dst_sel:DWORD dst_unused:UNUSED_PAD src0_sel:DWORD src1_sel:BYTE_3
; #define PG8_GAS __attribute__((address_space(1)))
; __device__ __forceinline__ float e_x24(unsigned h16, unsigned l8) { return __uint_as_float(((h16 - (l8 >> 7)) << 16) | (l8 << 8)); }
;     __device__ __forceinline__ void operator()(const f32x4 (&acc)[2][2][4][2], const Unit& u, int wr, int wc, int fr, int fq) const {
;     ...
;             for (int m = 0; m < 4; ++m) {
;                 const int row = row0 + ai * HALF + m * 16; const size_t off = (size_t)row * 2048 + col0, loff = (size_t)row * 2048 + lcol; float ss = 0.f;
;                 const u32x4 l4 = L4[m];
;                 u32x4 lo4;
; #pragma unroll
;                 for (int bj = 0; bj < 2; ++bj) {
;                     const u32x4 h4 = H4[m][bj];
;                     u32x4 ho;
; #pragma unroll
;                     for (int j = 0; j < 4; ++j) {
;                         const unsigned lw = l4[2 * bj + (j >> 1)], lb0 = (lw >> (16 * (j & 1))) & 0xffu, lb1 = (lw >> (16 * (j & 1) + 8)) & 0xffu;
;                         const float x0 = e_x24(h4[j] & 0xffffu, lb0) + acc[ai][bj][m][j >> 1][2 * (j & 1)] * scale, x1 = e_x24(h4[j] >> 16, lb1) + acc[ai][bj][m][j >> 1][2 * (j & 1) + 1] * scale;
;                         const unsigned b0 = __float_as_uint(x0), b1 = __float_as_uint(x1);
;                         ho[j] = ((b0 + 0x8000u) >> 16) | ((b1 + 0x8000u) & 0xffff0000u);
;                         const unsigned nb = ((b0 >> 8) & 0xffu) | (b1 & 0xff00u);
;                         if ((j & 1) == 0) lo4[2 * bj + (j >> 1)] = nb; else lo4[2 * bj + (j >> 1)] |= nb << 16;
;                         ss += x0 * x0 + x1 * x1;
;                     }
;                     *(PG8_GAS u32x4*)(hout + off + bj * HALF) = ho;
;                 }
;                 *(PG8_GAS u32x4*)(lout + loff) = lo4;
;                 ss += __shfl_xor(ss, 16); ss += __shfl_xor(ss, 32);
;                 if (fq == 0) __hip_atomic_fetch_add((PG8_GAS unsigned long long*)(rowsq_out + row), (unsigned long long)(ss * 16777216.0f + 0.5f), __ATOMIC_RELAXED, __HIP_MEMORY_SCOPE_AGENT);
	v_add_u32_e32 v34, 0x8000, v58
	v_lshrrev_b32_e32 v37, 16, v34
	v_and_b32_e32 v34, 0x10000, v63
	v_and_b32_e32 v38, 0x10000, v62
	v_sub_u32_e32 v34, v95, v34
	v_sub_u32_e32 v38, v93, v38
	v_pk_mul_f32 v[50:51], v[44:45], v[44:45]
	v_pk_mul_f32 v[42:43], v[32:33], v[32:33]
	v_and_b32_e32 v34, 0xffff0000, v34
	v_and_b32_e32 v38, 0xffff0000, v38
	v_lshlrev_b32_sdwa v60, v230, v91 dst_sel:DWORD dst_unused:UNUSED_PAD src0_sel:DWORD src1_sel:BYTE_3
	v_lshlrev_b32_sdwa v62, v230, v90 dst_sel:DWORD dst_unused:UNUSED_PAD src0_sel:DWORD src1_sel:BYTE_3
	v_pk_fma_f32 v[50:51], v[48:49], v[48:49], v[50:51]
	v_pk_fma_f32 v[42:43], v[40:41], v[40:41], v[42:43]
	v_or_b32_e32 v61, v34, v60
	v_or_b32_e32 v60, v38, v62
	v_mov_b32_e32 v34, v39
	v_lshrrev_b32_e32 v40, 8, v40
	v_pk_add_f32 v[34:35], v[34:35], v[60:61]
	v_perm_b32 v32, v32, v40, s94
	v_add_f32_e32 v40, v50, v54
	v_add_u32_e32 v38, 0x8000, v34
	v_add_f32_e32 v40, v51, v40
	v_and_or_b32 v37, v38, s90, v37
	v_pk_mul_f32 v[38:39], v[34:35], v[34:35]
	v_add_f32_e32 v40, v55, v40
	v_pk_fma_f32 v[60:61], v[58:59], v[58:59], v[38:39]
	v_add_f32_e32 v40, v42, v40
	v_add_f32_e32 v40, v60, v40
	v_lshrrev_b32_e32 v48, 8, v48
	v_add_f32_e32 v40, v43, v40
	v_lshrrev_b32_e32 v49, 8, v49
	v_perm_b32 v44, v44, v48, s94
	v_add_f32_e32 v48, v61, v40
	v_perm_b32 v45, v45, v49, s94
	ds_bpermute_b32 v49, v238, v48
	v_add_u32_e32 v38, 0x8000, v41
	v_lshrrev_b32_e32 v38, 16, v38
	v_add_u32_e32 v39, 0x8000, v33
	v_lshrrev_b32_e32 v58, 8, v58
	v_and_or_b32 v38, v39, s90, v38
	v_add_u32_e32 v39, 0x8000, v59
	v_lshrrev_b32_e32 v59, 8, v59
	v_perm_b32 v34, v34, v58, s94
	v_lshrrev_b32_e32 v41, 8, v41
	v_add_u32_e32 v62, 0x8000, v35
	v_perm_b32 v35, v35, v59, s94
	v_perm_b32 v33, v33, v41, s94
	v_lshl_or_b32 v42, v34, 16, v32
	s_waitcnt lgkmcnt(0)
	v_add_f32_e32 v32, v48, v49
	v_lshl_or_b32 v43, v35, 16, v33
	ds_bpermute_b32 v33, v237, v32
	v_lshrrev_b32_e32 v53, 8, v53
	v_lshrrev_b32_e32 v52, 8, v52
	v_lshrrev_b32_e32 v39, 16, v39
	v_perm_b32 v46, v46, v52, s94
	v_perm_b32 v47, v47, v53, s94
	v_lshl_add_u64 v[34:35], s[34:35], 0, v[128:129]
	v_and_or_b32 v39, v62, s90, v39
	v_lshl_or_b32 v41, v47, 16, v45
	v_lshl_or_b32 v40, v46, 16, v44
	v_lshl_add_u64 v[34:35], v[34:35], 0, v[194:195]
	global_store_dwordx4 v[56:57], v[36:39], off offset:256 nt
	global_store_dwordx4 v[34:35], v[40:43], off nt
	s_and_saveexec_b64 s[54:55], s[40:41]
	s_cbranch_execz .LBB0_1212
	s_waitcnt lgkmcnt(0)
	v_add_f32_e32 v32, v32, v33
	v_fma_f32 v32, v32, s80, 0.5
	v_trunc_f32_e32 v32, v32
	v_mul_f32_e32 v33, 0x2f800000, v32
	v_floor_f32_e32 v33, v33
	v_fmac_f32_e32 v32, 0xcf800000, v33
	v_cvt_u32_f32_e32 v32, v32
	v_cvt_u32_f32_e32 v33, v33
	v_lshl_add_u64 v[34:35], v[126:127], 3, s[44:45]
	global_atomic_add_x2 v[34:35], v[32:33], off
.LBB0_1212:
	s_or_b64 exec, exec, s[54:55]
	s_waitcnt vmcnt(11)
	v_lshrrev_b32_sdwa v32, v229, v77 dst_sel:DWORD dst_unused:UNUSED_PAD src0_sel:DWORD src1_sel:BYTE_0
	s_waitcnt lgkmcnt(0)
	v_lshrrev_b32_sdwa v33, v229, v76 dst_sel:DWORD dst_unused:UNUSED_PAD src0_sel:DWORD src1_sel:BYTE_0
	s_waitcnt vmcnt(10)
	v_sub_u32_sdwa v34, v84, v33 dst_sel:WORD_1 dst_unused:UNUSED_PAD src0_sel:DWORD src1_sel:DWORD
	v_sub_u32_sdwa v32, v86, v32 dst_sel:WORD_1 dst_unused:UNUSED_PAD src0_sel:DWORD src1_sel:DWORD
	v_lshlrev_b32_sdwa v33, v230, v77 dst_sel:DWORD dst_unused:UNUSED_PAD src0_sel:DWORD src1_sel:BYTE_0
	v_lshlrev_b32_sdwa v35, v230, v76 dst_sel:DWORD dst_unused:UNUSED_PAD src0_sel:DWORD src1_sel:BYTE_0
	v_or_b32_e32 v33, v32, v33
	v_or_b32_e32 v32, v34, v35
	v_mov_b32_e32 v34, v28
	v_mov_b32_e32 v35, v24
	v_pk_add_f32 v[32:33], v[34:35], v[32:33]
	v_lshlrev_b32_e32 v36, 1, v77
	v_lshlrev_b32_e32 v37, 1, v76
	v_add_u32_e32 v24, 0x8000, v32
	v_lshrrev_b32_e32 v42, 16, v24
	v_and_b32_e32 v24, 0x10000, v36
	v_and_b32_e32 v28, 0x10000, v37
	v_sub_u32_e32 v24, v86, v24
	v_sub_u32_e32 v28, v84, v28
	v_and_b32_e32 v38, 0xff00, v77
	v_and_b32_e32 v39, 0xff00, v76
	v_and_b32_e32 v24, 0xffff0000, v24
	v_and_b32_e32 v28, 0xffff0000, v28
	v_or_b32_e32 v35, v24, v38
	v_or_b32_e32 v34, v28, v39
	v_mov_b32_e32 v24, v29
	v_and_b32_sdwa v36, v76, s93 dst_sel:DWORD dst_unused:UNUSED_PAD src0_sel:WORD_1 src1_sel:DWORD
	v_pk_add_f32 v[28:29], v[24:25], v[34:35]
	v_and_b32_sdwa v25, v77, s93 dst_sel:DWORD dst_unused:UNUSED_PAD src0_sel:WORD_1 src1_sel:DWORD
	v_lshrrev_b32_e32 v37, 7, v36
	v_lshlrev_b32_sdwa v40, v231, v76 dst_sel:DWORD dst_unused:UNUSED_PAD src0_sel:DWORD src1_sel:BYTE_3
	v_lshlrev_b32_sdwa v41, v231, v77 dst_sel:DWORD dst_unused:UNUSED_PAD src0_sel:DWORD src1_sel:BYTE_3
	v_lshrrev_b32_e32 v38, 7, v25
	v_sub_u32_sdwa v39, v85, v37 dst_sel:WORD_1 dst_unused:UNUSED_PAD src0_sel:DWORD src1_sel:DWORD
	v_lshlrev_b32_e32 v36, 8, v36
	v_sub_u32_sdwa v37, v87, v38 dst_sel:WORD_1 dst_unused:UNUSED_PAD src0_sel:DWORD src1_sel:DWORD
	v_lshlrev_b32_e32 v25, 8, v25
	v_or_b32_e32 v36, v39, v36
	v_mov_b32_e32 v38, v30
	v_mov_b32_e32 v39, v26
	v_and_b32_e32 v26, 0x10000, v41
	v_and_b32_e32 v30, 0x10000, v40
	v_or_b32_e32 v37, v37, v25
	v_sub_u32_e32 v26, v87, v26
	v_sub_u32_e32 v30, v85, v30
	v_pk_add_f32 v[36:37], v[38:39], v[36:37]
	v_and_b32_e32 v26, 0xffff0000, v26
	v_and_b32_e32 v30, 0xffff0000, v30
	v_lshlrev_b32_sdwa v38, v230, v77 dst_sel:DWORD dst_unused:UNUSED_PAD src0_sel:DWORD src1_sel:BYTE_3
	v_lshlrev_b32_sdwa v40, v230, v76 dst_sel:DWORD dst_unused:UNUSED_PAD src0_sel:DWORD src1_sel:BYTE_3
	v_or_b32_e32 v39, v26, v38
	v_or_b32_e32 v38, v30, v40
	v_mov_b32_e32 v26, v31
	v_add_u32_e32 v25, 0x8000, v36
	v_pk_add_f32 v[30:31], v[26:27], v[38:39]
	v_lshrrev_b32_e32 v25, 16, v25
	v_add_u32_e32 v26, 0x8000, v30
	v_and_or_b32 v25, v26, s90, v25
	v_pk_mul_f32 v[26:27], v[30:31], v[30:31]
	v_add_u32_e32 v40, 0x8000, v31
	v_pk_fma_f32 v[38:39], v[36:37], v[36:37], v[26:27]
	v_add_u32_e32 v26, 0x8000, v33
	v_lshrrev_b32_e32 v26, 16, v26
	v_add_u32_e32 v27, 0x8000, v29
	v_and_or_b32 v26, v27, s90, v26
	v_add_u32_e32 v27, 0x8000, v37
	v_lshrrev_b32_e32 v27, 16, v27
	v_add_u32_e32 v24, 0x8000, v28
	v_and_or_b32 v27, v40, s90, v27
	v_lshl_add_u64 v[40:41], v[124:125], 1, s[30:31]
	v_and_or_b32 v24, v24, s90, v42
	v_lshl_add_u64 v[40:41], v[196:197], 1, v[40:41]
	global_store_dwordx4 v[40:41], v[24:27], off nt
	v_lshlrev_b32_e32 v42, 1, v79
	v_lshlrev_b32_e32 v43, 1, v78
	v_lshrrev_b32_sdwa v24, v229, v79 dst_sel:DWORD dst_unused:UNUSED_PAD src0_sel:DWORD src1_sel:BYTE_0
	v_lshrrev_b32_sdwa v25, v229, v78 dst_sel:DWORD dst_unused:UNUSED_PAD src0_sel:DWORD src1_sel:BYTE_0
	s_waitcnt vmcnt(10)
; #define PG8_GAS __attribute__((address_space(1)))
; __device__ __forceinline__ float e_x24(unsigned h16, unsigned l8) { return __uint_as_float(((h16 - (l8 >> 7)) << 16) | (l8 << 8)); }
;     __device__ __forceinline__ void operator()(const f32x4 (&acc)[2][2][4][2], const Unit& u, int wr, int wc, int fr, int fq) const {
;     ...
;             for (int m = 0; m < 4; ++m) {
;                 const int row = row0 + ai * HALF + m * 16; const size_t off = (size_t)row * 2048 + col0, loff = (size_t)row * 2048 + lcol; float ss = 0.f;
;                 const u32x4 l4 = L4[m];
;                 u32x4 lo4;
; #pragma unroll
;                 for (int bj = 0; bj < 2; ++bj) {
;                     const u32x4 h4 = H4[m][bj];
;                     u32x4 ho;
; #pragma unroll
;                     for (int j = 0; j < 4; ++j) {
;                         const unsigned lw = l4[2 * bj + (j >> 1)], lb0 = (lw >> (16 * (j & 1))) & 0xffu, lb1 = (lw >> (16 * (j & 1) + 8)) & 0xffu;
;                         const float x0 = e_x24(h4[j] & 0xffffu, lb0) + acc[ai][bj][m][j >> 1][2 * (j & 1)] * scale, x1 = e_x24(h4[j] >> 16, lb1) + acc[ai][bj][m][j >> 1][2 * (j & 1) + 1] * scale;
;                         const unsigned b0 = __float_as_uint(x0), b1 = __float_as_uint(x1);
;                         ho[j] = ((b0 + 0x8000u) >> 16) | ((b1 + 0x8000u) & 0xffff0000u);
;                         const unsigned nb = ((b0 >> 8) & 0xffu) | (b1 & 0xff00u);
;                         if ((j & 1) == 0) lo4[2 * bj + (j >> 1)] = nb; else lo4[2 * bj + (j >> 1)] |= nb << 16;
;                         ss += x0 * x0 + x1 * x1;
;                     }
;                     *(PG8_GAS u32x4*)(hout + off + bj * HALF) = ho;
;                 }
;                 *(PG8_GAS u32x4*)(lout + loff) = lo4;
;                 ss += __shfl_xor(ss, 16); ss += __shfl_xor(ss, 32);
;                 if (fq == 0) __hip_atomic_fetch_add((PG8_GAS unsigned long long*)(rowsq_out + row), (unsigned long long)(ss * 16777216.0f + 0.5f), __ATOMIC_RELAXED, __HIP_MEMORY_SCOPE_AGENT);
	v_sub_u32_sdwa v26, v80, v25 dst_sel:WORD_1 dst_unused:UNUSED_PAD src0_sel:DWORD src1_sel:DWORD
	v_sub_u32_sdwa v24, v82, v24 dst_sel:WORD_1 dst_unused:UNUSED_PAD src0_sel:DWORD src1_sel:DWORD
	v_lshlrev_b32_sdwa v25, v230, v79 dst_sel:DWORD dst_unused:UNUSED_PAD src0_sel:DWORD src1_sel:BYTE_0
	v_lshlrev_b32_sdwa v27, v230, v78 dst_sel:DWORD dst_unused:UNUSED_PAD src0_sel:DWORD src1_sel:BYTE_0
	v_or_b32_e32 v25, v24, v25
	v_or_b32_e32 v24, v26, v27
	v_mov_b32_e32 v26, v20
	v_mov_b32_e32 v27, v16
	v_pk_add_f32 v[24:25], v[26:27], v[24:25]
	v_and_b32_e32 v26, 0x10000, v43
	v_add_u32_e32 v16, 0x8000, v24
	v_lshrrev_b32_e32 v20, 16, v16
	v_and_b32_e32 v16, 0x10000, v42
	v_sub_u32_e32 v16, v82, v16
	v_sub_u32_e32 v26, v80, v26
	v_and_b32_e32 v44, 0xff00, v79
	v_and_b32_e32 v45, 0xff00, v78
	v_and_b32_e32 v16, 0xffff0000, v16
	v_and_b32_e32 v26, 0xffff0000, v26
	v_or_b32_e32 v27, v16, v44
	v_or_b32_e32 v26, v26, v45
	v_mov_b32_e32 v16, v21
	v_pk_add_f32 v[16:17], v[16:17], v[26:27]
	v_and_b32_sdwa v42, v78, s93 dst_sel:DWORD dst_unused:UNUSED_PAD src0_sel:WORD_1 src1_sel:DWORD
	v_add_u32_e32 v21, 0x8000, v16
	v_and_or_b32 v20, v21, s90, v20
	v_and_b32_sdwa v21, v79, s93 dst_sel:DWORD dst_unused:UNUSED_PAD src0_sel:WORD_1 src1_sel:DWORD
	v_lshrrev_b32_e32 v43, 7, v42
	v_lshrrev_b32_e32 v44, 7, v21
	v_sub_u32_sdwa v45, v81, v43 dst_sel:WORD_1 dst_unused:UNUSED_PAD src0_sel:DWORD src1_sel:DWORD
	v_sub_u32_sdwa v43, v83, v44 dst_sel:WORD_1 dst_unused:UNUSED_PAD src0_sel:DWORD src1_sel:DWORD
	v_lshlrev_b32_e32 v21, 8, v21
	v_lshlrev_b32_e32 v42, 8, v42
	v_or_b32_e32 v43, v43, v21
	v_or_b32_e32 v42, v45, v42
	v_mov_b32_e32 v44, v22
	v_mov_b32_e32 v45, v18
	v_pk_add_f32 v[42:43], v[44:45], v[42:43]
	v_lshlrev_b32_sdwa v46, v231, v78 dst_sel:DWORD dst_unused:UNUSED_PAD src0_sel:DWORD src1_sel:BYTE_3
	v_lshlrev_b32_sdwa v47, v231, v79 dst_sel:DWORD dst_unused:UNUSED_PAD src0_sel:DWORD src1_sel:BYTE_3
	v_add_u32_e32 v18, 0x8000, v42
	v_lshrrev_b32_e32 v21, 16, v18
	v_and_b32_e32 v18, 0x10000, v47
	v_and_b32_e32 v22, 0x10000, v46
	v_sub_u32_e32 v18, v83, v18
	v_sub_u32_e32 v22, v81, v22
	v_pk_mul_f32 v[34:35], v[28:29], v[28:29]
	v_pk_mul_f32 v[26:27], v[16:17], v[16:17]
	v_and_b32_e32 v18, 0xffff0000, v18
	v_and_b32_e32 v22, 0xffff0000, v22
	v_lshlrev_b32_sdwa v44, v230, v79 dst_sel:DWORD dst_unused:UNUSED_PAD src0_sel:DWORD src1_sel:BYTE_3
	v_lshlrev_b32_sdwa v46, v230, v78 dst_sel:DWORD dst_unused:UNUSED_PAD src0_sel:DWORD src1_sel:BYTE_3
	v_pk_fma_f32 v[34:35], v[32:33], v[32:33], v[34:35]
	v_pk_fma_f32 v[26:27], v[24:25], v[24:25], v[26:27]
	v_or_b32_e32 v45, v18, v44
	v_or_b32_e32 v44, v22, v46
	v_mov_b32_e32 v18, v23
	v_lshrrev_b32_e32 v24, 8, v24
	v_pk_add_f32 v[18:19], v[18:19], v[44:45]
	v_perm_b32 v16, v16, v24, s94
	v_add_f32_e32 v24, v34, v38
	v_add_u32_e32 v22, 0x8000, v18
	v_add_f32_e32 v24, v35, v24
	v_and_or_b32 v21, v22, s90, v21
	v_pk_mul_f32 v[22:23], v[18:19], v[18:19]
	v_add_f32_e32 v24, v39, v24
	v_pk_fma_f32 v[44:45], v[42:43], v[42:43], v[22:23]
	v_add_f32_e32 v24, v26, v24
	v_add_f32_e32 v24, v44, v24
	v_lshrrev_b32_e32 v32, 8, v32
	v_add_f32_e32 v24, v27, v24
	v_lshrrev_b32_e32 v33, 8, v33
	v_perm_b32 v28, v28, v32, s94
	v_add_f32_e32 v32, v45, v24
	v_perm_b32 v29, v29, v33, s94
	ds_bpermute_b32 v33, v238, v32
	v_add_u32_e32 v22, 0x8000, v25
	v_lshrrev_b32_e32 v22, 16, v22
	v_add_u32_e32 v23, 0x8000, v17
	v_lshrrev_b32_e32 v42, 8, v42
	v_and_or_b32 v22, v23, s90, v22
	v_add_u32_e32 v23, 0x8000, v43
	v_lshrrev_b32_e32 v43, 8, v43
	v_perm_b32 v18, v18, v42, s94
	v_lshrrev_b32_e32 v25, 8, v25
	v_add_u32_e32 v46, 0x8000, v19
	v_perm_b32 v19, v19, v43, s94
	v_perm_b32 v17, v17, v25, s94
	v_lshl_or_b32 v26, v18, 16, v16
	s_waitcnt lgkmcnt(0)
	v_add_f32_e32 v16, v32, v33
	v_lshl_or_b32 v27, v19, 16, v17
	ds_bpermute_b32 v17, v237, v16
	v_lshrrev_b32_e32 v37, 8, v37
	v_lshrrev_b32_e32 v36, 8, v36
	v_lshrrev_b32_e32 v23, 16, v23
	v_perm_b32 v30, v30, v36, s94
	v_perm_b32 v31, v31, v37, s94
	v_lshl_add_u64 v[18:19], s[34:35], 0, v[124:125]
	v_and_or_b32 v23, v46, s90, v23
	v_lshl_or_b32 v25, v31, 16, v29
	v_lshl_or_b32 v24, v30, 16, v28
	v_lshl_add_u64 v[18:19], v[18:19], 0, v[194:195]
	global_store_dwordx4 v[40:41], v[20:23], off offset:256 nt
	global_store_dwordx4 v[18:19], v[24:27], off nt
	s_and_saveexec_b64 s[54:55], s[40:41]
	s_cbranch_execz .LBB0_1214
	s_waitcnt lgkmcnt(0)
	v_add_f32_e32 v16, v16, v17
	v_fma_f32 v16, v16, s80, 0.5
	v_trunc_f32_e32 v16, v16
	v_mul_f32_e32 v17, 0x2f800000, v16
	v_floor_f32_e32 v17, v17
	v_fmac_f32_e32 v16, 0xcf800000, v17
	v_cvt_u32_f32_e32 v16, v16
	v_cvt_u32_f32_e32 v17, v17
	v_lshl_add_u64 v[18:19], v[122:123], 3, s[44:45]
	global_atomic_add_x2 v[18:19], v[16:17], off
; #define PG8_GAS __attribute__((address_space(1)))
; __device__ __forceinline__ float e_x24(unsigned h16, unsigned l8) { return __uint_as_float(((h16 - (l8 >> 7)) << 16) | (l8 << 8)); }
;     __device__ __forceinline__ void operator()(const f32x4 (&acc)[2][2][4][2], const Unit& u, int wr, int wc, int fr, int fq) const {
;     ...
;             for (int m = 0; m < 4; ++m) {
;                 const int row = row0 + ai * HALF + m * 16; const size_t off = (size_t)row * 2048 + col0, loff = (size_t)row * 2048 + lcol; float ss = 0.f;
;                 const u32x4 l4 = L4[m];
;                 u32x4 lo4;
; #pragma unroll
;                 for (int bj = 0; bj < 2; ++bj) {
;                     const u32x4 h4 = H4[m][bj];
;                     u32x4 ho;
; #pragma unroll
;                     for (int j = 0; j < 4; ++j) {
;                         const unsigned lw = l4[2 * bj + (j >> 1)], lb0 = (lw >> (16 * (j & 1))) & 0xffu, lb1 = (lw >> (16 * (j & 1) + 8)) & 0xffu;
;                         const float x0 = e_x24(h4[j] & 0xffffu, lb0) + acc[ai][bj][m][j >> 1][2 * (j & 1)] * scale, x1 = e_x24(h4[j] >> 16, lb1) + acc[ai][bj][m][j >> 1][2 * (j & 1) + 1] * scale;
;                         const unsigned b0 = __float_as_uint(x0), b1 = __float_as_uint(x1);
;                         ho[j] = ((b0 + 0x8000u) >> 16) | ((b1 + 0x8000u) & 0xffff0000u);
;                         const unsigned nb = ((b0 >> 8) & 0xffu) | (b1 & 0xff00u);
;                         if ((j & 1) == 0) lo4[2 * bj + (j >> 1)] = nb; else lo4[2 * bj + (j >> 1)] |= nb << 16;
;                         ss += x0 * x0 + x1 * x1;
;                     }
;                     *(PG8_GAS u32x4*)(hout + off + bj * HALF) = ho;
;                 }
;                 *(PG8_GAS u32x4*)(lout + loff) = lo4;
.LBB0_1214:
	s_or_b64 exec, exec, s[54:55]
	s_waitcnt vmcnt(11)
	v_lshrrev_b32_sdwa v16, v229, v65 dst_sel:DWORD dst_unused:UNUSED_PAD src0_sel:DWORD src1_sel:BYTE_0
	s_waitcnt lgkmcnt(0)
	v_lshrrev_b32_sdwa v17, v229, v64 dst_sel:DWORD dst_unused:UNUSED_PAD src0_sel:DWORD src1_sel:BYTE_0
	s_waitcnt vmcnt(10)
	v_sub_u32_sdwa v18, v72, v17 dst_sel:WORD_1 dst_unused:UNUSED_PAD src0_sel:DWORD src1_sel:DWORD
	v_sub_u32_sdwa v16, v74, v16 dst_sel:WORD_1 dst_unused:UNUSED_PAD src0_sel:DWORD src1_sel:DWORD
	v_lshlrev_b32_sdwa v17, v230, v65 dst_sel:DWORD dst_unused:UNUSED_PAD src0_sel:DWORD src1_sel:BYTE_0
	v_lshlrev_b32_sdwa v19, v230, v64 dst_sel:DWORD dst_unused:UNUSED_PAD src0_sel:DWORD src1_sel:BYTE_0
	v_or_b32_e32 v17, v16, v17
	v_or_b32_e32 v16, v18, v19
	v_mov_b32_e32 v18, v12
	v_mov_b32_e32 v19, v8
	v_pk_add_f32 v[16:17], v[18:19], v[16:17]
	v_lshlrev_b32_e32 v20, 1, v65
	v_lshlrev_b32_e32 v21, 1, v64
	v_add_u32_e32 v8, 0x8000, v16
	v_lshrrev_b32_e32 v26, 16, v8
	v_and_b32_e32 v8, 0x10000, v20
	v_and_b32_e32 v12, 0x10000, v21
	v_sub_u32_e32 v8, v74, v8
	v_sub_u32_e32 v12, v72, v12
	v_and_b32_e32 v22, 0xff00, v65
	v_and_b32_e32 v23, 0xff00, v64
	v_and_b32_e32 v8, 0xffff0000, v8
	v_and_b32_e32 v12, 0xffff0000, v12
	v_or_b32_e32 v19, v8, v22
	v_or_b32_e32 v18, v12, v23
	v_mov_b32_e32 v8, v13
	v_and_b32_sdwa v20, v64, s93 dst_sel:DWORD dst_unused:UNUSED_PAD src0_sel:WORD_1 src1_sel:DWORD
	v_pk_add_f32 v[12:13], v[8:9], v[18:19]
	v_and_b32_sdwa v9, v65, s93 dst_sel:DWORD dst_unused:UNUSED_PAD src0_sel:WORD_1 src1_sel:DWORD
	v_lshrrev_b32_e32 v21, 7, v20
	v_lshlrev_b32_sdwa v24, v231, v64 dst_sel:DWORD dst_unused:UNUSED_PAD src0_sel:DWORD src1_sel:BYTE_3
	v_lshlrev_b32_sdwa v25, v231, v65 dst_sel:DWORD dst_unused:UNUSED_PAD src0_sel:DWORD src1_sel:BYTE_3
	v_lshrrev_b32_e32 v22, 7, v9
	v_sub_u32_sdwa v23, v73, v21 dst_sel:WORD_1 dst_unused:UNUSED_PAD src0_sel:DWORD src1_sel:DWORD
	v_lshlrev_b32_e32 v20, 8, v20
	v_sub_u32_sdwa v21, v75, v22 dst_sel:WORD_1 dst_unused:UNUSED_PAD src0_sel:DWORD src1_sel:DWORD
	v_lshlrev_b32_e32 v9, 8, v9
	v_or_b32_e32 v20, v23, v20
	v_mov_b32_e32 v22, v14
	v_mov_b32_e32 v23, v10
	v_and_b32_e32 v10, 0x10000, v25
	v_and_b32_e32 v14, 0x10000, v24
	v_or_b32_e32 v21, v21, v9
	v_sub_u32_e32 v10, v75, v10
	v_sub_u32_e32 v14, v73, v14
	v_pk_add_f32 v[20:21], v[22:23], v[20:21]
	v_and_b32_e32 v10, 0xffff0000, v10
	v_and_b32_e32 v14, 0xffff0000, v14
	v_lshlrev_b32_sdwa v22, v230, v65 dst_sel:DWORD dst_unused:UNUSED_PAD src0_sel:DWORD src1_sel:BYTE_3
	v_lshlrev_b32_sdwa v24, v230, v64 dst_sel:DWORD dst_unused:UNUSED_PAD src0_sel:DWORD src1_sel:BYTE_3
	v_or_b32_e32 v23, v10, v22
	v_or_b32_e32 v22, v14, v24
	v_mov_b32_e32 v10, v15
	v_add_u32_e32 v9, 0x8000, v20
	v_pk_add_f32 v[14:15], v[10:11], v[22:23]
	v_lshrrev_b32_e32 v9, 16, v9
	v_add_u32_e32 v10, 0x8000, v14
	v_and_or_b32 v9, v10, s90, v9
	v_pk_mul_f32 v[10:11], v[14:15], v[14:15]
	v_add_u32_e32 v24, 0x8000, v15
	v_pk_fma_f32 v[22:23], v[20:21], v[20:21], v[10:11]
	v_add_u32_e32 v10, 0x8000, v17
	v_lshrrev_b32_e32 v10, 16, v10
	v_add_u32_e32 v11, 0x8000, v13
	v_and_or_b32 v10, v11, s90, v10
	v_add_u32_e32 v11, 0x8000, v21
	v_lshrrev_b32_e32 v11, 16, v11
	v_add_u32_e32 v8, 0x8000, v12
	v_and_or_b32 v11, v24, s90, v11
	v_lshl_add_u64 v[24:25], v[120:121], 1, s[30:31]
	v_and_or_b32 v8, v8, s90, v26
	v_lshl_add_u64 v[24:25], v[196:197], 1, v[24:25]
	global_store_dwordx4 v[24:25], v[8:11], off nt
	v_lshlrev_b32_e32 v26, 1, v67
	v_lshlrev_b32_e32 v27, 1, v66
	v_lshrrev_b32_sdwa v8, v229, v67 dst_sel:DWORD dst_unused:UNUSED_PAD src0_sel:DWORD src1_sel:BYTE_0
	v_lshrrev_b32_sdwa v9, v229, v66 dst_sel:DWORD dst_unused:UNUSED_PAD src0_sel:DWORD src1_sel:BYTE_0
	s_waitcnt vmcnt(10)
; #define PG8_GAS __attribute__((address_space(1)))
; __device__ __forceinline__ float e_x24(unsigned h16, unsigned l8) { return __uint_as_float(((h16 - (l8 >> 7)) << 16) | (l8 << 8)); }
;     __device__ __forceinline__ void operator()(const f32x4 (&acc)[2][2][4][2], const Unit& u, int wr, int wc, int fr, int fq) const {
;     ...
;                 for (int bj = 0; bj < 2; ++bj) {
;                     const u32x4 h4 = H4[m][bj];
;                     u32x4 ho;
; #pragma unroll
;                     for (int j = 0; j < 4; ++j) {
;                         const unsigned lw = l4[2 * bj + (j >> 1)], lb0 = (lw >> (16 * (j & 1))) & 0xffu, lb1 = (lw >> (16 * (j & 1) + 8)) & 0xffu;
;                         const float x0 = e_x24(h4[j] & 0xffffu, lb0) + acc[ai][bj][m][j >> 1][2 * (j & 1)] * scale, x1 = e_x24(h4[j] >> 16, lb1) + acc[ai][bj][m][j >> 1][2 * (j & 1) + 1] * scale;
;                         const unsigned b0 = __float_as_uint(x0), b1 = __float_as_uint(x1);
;                         ho[j] = ((b0 + 0x8000u) >> 16) | ((b1 + 0x8000u) & 0xffff0000u);
;                         const unsigned nb = ((b0 >> 8) & 0xffu) | (b1 & 0xff00u);
;                         if ((j & 1) == 0) lo4[2 * bj + (j >> 1)] = nb; else lo4[2 * bj + (j >> 1)] |= nb << 16;
;                         ss += x0 * x0 + x1 * x1;
;                     }
;                     *(PG8_GAS u32x4*)(hout + off + bj * HALF) = ho;
;                 }
;                 *(PG8_GAS u32x4*)(lout + loff) = lo4;
;                 ss += __shfl_xor(ss, 16); ss += __shfl_xor(ss, 32);
;                 if (fq == 0) __hip_atomic_fetch_add((PG8_GAS unsigned long long*)(rowsq_out + row), (unsigned long long)(ss * 16777216.0f + 0.5f), __ATOMIC_RELAXED, __HIP_MEMORY_SCOPE_AGENT);
	v_sub_u32_sdwa v10, v68, v9 dst_sel:WORD_1 dst_unused:UNUSED_PAD src0_sel:DWORD src1_sel:DWORD
	v_sub_u32_sdwa v8, v70, v8 dst_sel:WORD_1 dst_unused:UNUSED_PAD src0_sel:DWORD src1_sel:DWORD
	v_lshlrev_b32_sdwa v9, v230, v67 dst_sel:DWORD dst_unused:UNUSED_PAD src0_sel:DWORD src1_sel:BYTE_0
	v_lshlrev_b32_sdwa v11, v230, v66 dst_sel:DWORD dst_unused:UNUSED_PAD src0_sel:DWORD src1_sel:BYTE_0
	v_or_b32_e32 v9, v8, v9
	v_or_b32_e32 v8, v10, v11
	v_mov_b32_e32 v10, v4
	v_mov_b32_e32 v11, v0
	v_pk_add_f32 v[8:9], v[10:11], v[8:9]
	v_and_b32_e32 v10, 0x10000, v27
	v_add_u32_e32 v0, 0x8000, v8
	v_lshrrev_b32_e32 v4, 16, v0
	v_and_b32_e32 v0, 0x10000, v26
	v_sub_u32_e32 v0, v70, v0
	v_sub_u32_e32 v10, v68, v10
	v_and_b32_e32 v28, 0xff00, v67
	v_and_b32_e32 v29, 0xff00, v66
	v_and_b32_e32 v0, 0xffff0000, v0
	v_and_b32_e32 v10, 0xffff0000, v10
	v_or_b32_e32 v11, v0, v28
	v_or_b32_e32 v10, v10, v29
	v_mov_b32_e32 v0, v5
	v_pk_add_f32 v[0:1], v[0:1], v[10:11]
	v_and_b32_sdwa v26, v66, s93 dst_sel:DWORD dst_unused:UNUSED_PAD src0_sel:WORD_1 src1_sel:DWORD
	v_add_u32_e32 v5, 0x8000, v0
	v_and_or_b32 v4, v5, s90, v4
	v_and_b32_sdwa v5, v67, s93 dst_sel:DWORD dst_unused:UNUSED_PAD src0_sel:WORD_1 src1_sel:DWORD
	v_lshrrev_b32_e32 v27, 7, v26
	v_lshrrev_b32_e32 v28, 7, v5
	v_sub_u32_sdwa v29, v69, v27 dst_sel:WORD_1 dst_unused:UNUSED_PAD src0_sel:DWORD src1_sel:DWORD
	v_sub_u32_sdwa v27, v71, v28 dst_sel:WORD_1 dst_unused:UNUSED_PAD src0_sel:DWORD src1_sel:DWORD
	v_lshlrev_b32_e32 v5, 8, v5
	v_lshlrev_b32_e32 v26, 8, v26
	v_or_b32_e32 v27, v27, v5
	v_or_b32_e32 v26, v29, v26
	v_mov_b32_e32 v28, v6
	v_mov_b32_e32 v29, v2
	v_pk_add_f32 v[26:27], v[28:29], v[26:27]
	v_lshlrev_b32_sdwa v30, v231, v66 dst_sel:DWORD dst_unused:UNUSED_PAD src0_sel:DWORD src1_sel:BYTE_3
	v_lshlrev_b32_sdwa v31, v231, v67 dst_sel:DWORD dst_unused:UNUSED_PAD src0_sel:DWORD src1_sel:BYTE_3
	v_add_u32_e32 v2, 0x8000, v26
	v_lshrrev_b32_e32 v5, 16, v2
	v_and_b32_e32 v2, 0x10000, v31
	v_and_b32_e32 v6, 0x10000, v30
	v_sub_u32_e32 v2, v71, v2
	v_sub_u32_e32 v6, v69, v6
	v_pk_mul_f32 v[18:19], v[12:13], v[12:13]
	v_pk_mul_f32 v[10:11], v[0:1], v[0:1]
	v_and_b32_e32 v2, 0xffff0000, v2
	v_and_b32_e32 v6, 0xffff0000, v6
	v_lshlrev_b32_sdwa v28, v230, v67 dst_sel:DWORD dst_unused:UNUSED_PAD src0_sel:DWORD src1_sel:BYTE_3
	v_lshlrev_b32_sdwa v30, v230, v66 dst_sel:DWORD dst_unused:UNUSED_PAD src0_sel:DWORD src1_sel:BYTE_3
	v_pk_fma_f32 v[18:19], v[16:17], v[16:17], v[18:19]
	v_pk_fma_f32 v[10:11], v[8:9], v[8:9], v[10:11]
	v_or_b32_e32 v29, v2, v28
	v_or_b32_e32 v28, v6, v30
	v_mov_b32_e32 v2, v7
	v_lshrrev_b32_e32 v8, 8, v8
	v_pk_add_f32 v[2:3], v[2:3], v[28:29]
	v_perm_b32 v0, v0, v8, s94
	v_add_f32_e32 v8, v18, v22
	v_add_u32_e32 v6, 0x8000, v2
	v_add_f32_e32 v8, v19, v8
	v_and_or_b32 v5, v6, s90, v5
	v_pk_mul_f32 v[6:7], v[2:3], v[2:3]
	v_add_f32_e32 v8, v23, v8
	v_pk_fma_f32 v[28:29], v[26:27], v[26:27], v[6:7]
	v_add_f32_e32 v8, v10, v8
	v_add_f32_e32 v8, v28, v8
	v_lshrrev_b32_e32 v16, 8, v16
	v_add_f32_e32 v8, v11, v8
	v_lshrrev_b32_e32 v17, 8, v17
	v_perm_b32 v12, v12, v16, s94
	v_add_f32_e32 v16, v29, v8
	v_perm_b32 v13, v13, v17, s94
	ds_bpermute_b32 v17, v238, v16
	v_add_u32_e32 v6, 0x8000, v9
	v_lshrrev_b32_e32 v6, 16, v6
	v_add_u32_e32 v7, 0x8000, v1
	v_lshrrev_b32_e32 v26, 8, v26
	v_and_or_b32 v6, v7, s90, v6
	v_add_u32_e32 v7, 0x8000, v27
	v_lshrrev_b32_e32 v27, 8, v27
	v_perm_b32 v2, v2, v26, s94
	v_lshrrev_b32_e32 v9, 8, v9
	v_add_u32_e32 v30, 0x8000, v3
	v_perm_b32 v3, v3, v27, s94
	v_perm_b32 v1, v1, v9, s94
	v_lshl_or_b32 v10, v2, 16, v0
	s_waitcnt lgkmcnt(0)
	v_add_f32_e32 v0, v16, v17
	v_lshl_or_b32 v11, v3, 16, v1
	ds_bpermute_b32 v1, v237, v0
	v_lshrrev_b32_e32 v21, 8, v21
	v_lshrrev_b32_e32 v20, 8, v20
	v_lshrrev_b32_e32 v7, 16, v7
	v_perm_b32 v14, v14, v20, s94
	v_perm_b32 v15, v15, v21, s94
	v_lshl_add_u64 v[2:3], s[34:35], 0, v[120:121]
	v_and_or_b32 v7, v30, s90, v7
	v_lshl_or_b32 v9, v15, 16, v13
	v_lshl_or_b32 v8, v14, 16, v12
	v_lshl_add_u64 v[2:3], v[2:3], 0, v[194:195]
	global_store_dwordx4 v[24:25], v[4:7], off offset:256 nt
	global_store_dwordx4 v[2:3], v[8:11], off nt
	s_and_saveexec_b64 s[54:55], s[40:41]
	s_cbranch_execz .LBB0_1191
	s_waitcnt lgkmcnt(0)
	v_add_f32_e32 v0, v0, v1
	v_fma_f32 v0, v0, s80, 0.5
	v_trunc_f32_e32 v0, v0
	v_mul_f32_e32 v1, 0x2f800000, v0
	v_floor_f32_e32 v1, v1
	v_fmac_f32_e32 v0, 0xcf800000, v1
	v_cvt_u32_f32_e32 v0, v0
	v_cvt_u32_f32_e32 v1, v1
	v_lshl_add_u64 v[2:3], v[118:119], 3, s[44:45]
	global_atomic_add_x2 v[2:3], v[0:1], off
	s_branch .LBB0_1191
